# RG-LRU scan passes 1 and 2: token loops with batched loads and counted waits (were one load per wait)
# speedup vs baseline: 1.0236x; 1.0053x over previous
; DI unsigned cvt_pk_bf16(float lo, float hi) { unsigned r; asm volatile("v_cvt_pk_bf16_f32 %0, %1, %2" : "=v"(r) : "v"(lo), "v"(hi)); return r; }
; DI void unpack8(const u32x4 v, float* f) { f[0] = bf_lo(v.x); f[1] = bf_hi(v.x); f[2] = bf_lo(v.y); f[3] = bf_hi(v.y); f[4] = bf_lo(v.z); f[5] = bf_hi(v.z); f[6] = bf_lo(v.w); f[7] = bf_hi(v.w); }
; DI void phase_scan2(const bf16_t* la, const bf16_t* bb, const bf16_t* y, const float* hin, bf16_t* yh) {
;     ...
;     const size_t base = ((size_t)b * SEQ + c * 32) * DM + chg * 8;
;     const size_t so = ((size_t)b * 128 + c) * DM + chg * 8;
;     float h[8];
;     { const f32x4 a = *(const f32x4*)(hin + so), bq = *(const f32x4*)(hin + so + 4);
; #pragma unroll
;       for (int e = 0; e < 4; ++e) { h[e] = a[e]; h[4 + e] = bq[e]; } }
; #pragma unroll 8
;     for (int t = 0; t < 32; ++t) {
;       float l[8], bv[8], yv[8]; unpack8(*(const u32x4*)(la + base + (size_t)t * DM), l); unpack8(*(const u32x4*)(bb + base + (size_t)t * DM), bv); unpack8(*(const u32x4*)(y + base + (size_t)t * DM), yv);
;       float o[8];
; #pragma unroll
;       for (int e = 0; e < 8; ++e) { h[e] = __expf(l[e]) * h[e] + bv[e]; o[e] = h[e] * yv[e]; }
;       u32x4 wv; wv.x = cvt_pk_bf16(o[0], o[1]); wv.y = cvt_pk_bf16(o[2], o[3]); wv.z = cvt_pk_bf16(o[4], o[5]); wv.w = cvt_pk_bf16(o[6], o[7]);
;       *(u32x4*)(yh + base + (size_t)t * DM) = wv;
.LBB0_35:
	v_mov_b32_e32 v18, 0x8000000
	v_mov_b32_e32 v19, 0
	v_lshl_add_u64 v[16:17], v[12:13], 0, v[18:19]
	v_mov_b32_e32 v18, 0x1000
	global_load_dwordx4 v[40:43], v[16:17], off
	global_load_dwordx4 v[44:47], v[14:15], off
	global_load_dwordx4 v[48:51], v[12:13], off
	v_lshl_add_u64 v[16:17], v[16:17], 0, v[18:19]
	v_lshl_add_u64 v[14:15], v[14:15], 0, v[18:19]
	v_lshl_add_u64 v[12:13], v[12:13], 0, v[18:19]
	global_load_dwordx4 v[52:55], v[16:17], off
	global_load_dwordx4 v[56:59], v[14:15], off
	global_load_dwordx4 v[60:63], v[12:13], off
	v_lshl_add_u64 v[16:17], v[16:17], 0, v[18:19]
	v_lshl_add_u64 v[14:15], v[14:15], 0, v[18:19]
	v_lshl_add_u64 v[12:13], v[12:13], 0, v[18:19]
	global_load_dwordx4 v[64:67], v[16:17], off
	global_load_dwordx4 v[68:71], v[14:15], off
	global_load_dwordx4 v[72:75], v[12:13], off
	v_lshl_add_u64 v[16:17], v[16:17], 0, v[18:19]
	v_lshl_add_u64 v[14:15], v[14:15], 0, v[18:19]
	v_lshl_add_u64 v[12:13], v[12:13], 0, v[18:19]
	global_load_dwordx4 v[76:79], v[16:17], off
	global_load_dwordx4 v[80:83], v[14:15], off
	global_load_dwordx4 v[84:87], v[12:13], off
	v_lshl_add_u64 v[16:17], v[16:17], 0, v[18:19]
	v_lshl_add_u64 v[14:15], v[14:15], 0, v[18:19]
	v_lshl_add_u64 v[12:13], v[12:13], 0, v[18:19]
	global_load_dwordx4 v[88:91], v[16:17], off
	global_load_dwordx4 v[92:95], v[14:15], off
	global_load_dwordx4 v[96:99], v[12:13], off
	v_lshl_add_u64 v[16:17], v[16:17], 0, v[18:19]
	v_lshl_add_u64 v[14:15], v[14:15], 0, v[18:19]
	v_lshl_add_u64 v[12:13], v[12:13], 0, v[18:19]
	global_load_dwordx4 v[100:103], v[16:17], off
	global_load_dwordx4 v[104:107], v[14:15], off
	global_load_dwordx4 v[108:111], v[12:13], off
	v_lshl_add_u64 v[16:17], v[16:17], 0, v[18:19]
	v_lshl_add_u64 v[14:15], v[14:15], 0, v[18:19]
	v_lshl_add_u64 v[12:13], v[12:13], 0, v[18:19]
	global_load_dwordx4 v[112:115], v[16:17], off
	global_load_dwordx4 v[116:119], v[14:15], off
	global_load_dwordx4 v[120:123], v[12:13], off
	v_lshl_add_u64 v[16:17], v[16:17], 0, v[18:19]
	v_lshl_add_u64 v[14:15], v[14:15], 0, v[18:19]
	v_lshl_add_u64 v[12:13], v[12:13], 0, v[18:19]
	global_load_dwordx4 v[124:127], v[16:17], off
	global_load_dwordx4 v[128:131], v[14:15], off
	global_load_dwordx4 v[132:135], v[12:13], off
	v_lshl_add_u64 v[16:17], v[16:17], 0, v[18:19]
	v_lshl_add_u64 v[14:15], v[14:15], 0, v[18:19]
	v_lshl_add_u64 v[12:13], v[12:13], 0, v[18:19]
	s_waitcnt vmcnt(21)
	v_lshlrev_b32_e32 v20, 16, v40
	v_and_b32_e32 v21, 0xffff0000, v40
	v_mul_f32_e32 v22, 0x3fb8aa3b, v20
	v_mul_f32_e32 v23, 0x3fb8aa3b, v21
	v_exp_f32_e32 v22, v22
	v_exp_f32_e32 v23, v23
	v_lshlrev_b32_e32 v20, 16, v44
	v_and_b32_e32 v21, 0xffff0000, v44
	v_fma_f32 v6, v6, v22, v20
	v_fma_f32 v7, v7, v23, v21
	v_lshlrev_b32_e32 v20, 16, v48
	v_and_b32_e32 v21, 0xffff0000, v48
	v_mul_f32_e32 v20, v6, v20
	v_mul_f32_e32 v21, v7, v21
	v_cvt_pk_bf16_f32 v136, v20, v21
	v_lshlrev_b32_e32 v24, 16, v41
	v_and_b32_e32 v25, 0xffff0000, v41
	v_mul_f32_e32 v26, 0x3fb8aa3b, v24
	v_mul_f32_e32 v27, 0x3fb8aa3b, v25
	v_exp_f32_e32 v26, v26
	v_exp_f32_e32 v27, v27
	v_lshlrev_b32_e32 v24, 16, v45
	v_and_b32_e32 v25, 0xffff0000, v45
	v_fma_f32 v8, v8, v26, v24
	v_fma_f32 v9, v9, v27, v25
	v_lshlrev_b32_e32 v24, 16, v49
	v_and_b32_e32 v25, 0xffff0000, v49
	v_mul_f32_e32 v24, v8, v24
	v_mul_f32_e32 v25, v9, v25
	v_cvt_pk_bf16_f32 v137, v24, v25
	v_lshlrev_b32_e32 v20, 16, v42
	v_and_b32_e32 v21, 0xffff0000, v42
	v_mul_f32_e32 v22, 0x3fb8aa3b, v20
	v_mul_f32_e32 v23, 0x3fb8aa3b, v21
	v_exp_f32_e32 v22, v22
	v_exp_f32_e32 v23, v23
	v_lshlrev_b32_e32 v20, 16, v46
	v_and_b32_e32 v21, 0xffff0000, v46
	v_fma_f32 v2, v2, v22, v20
	v_fma_f32 v3, v3, v23, v21
	v_lshlrev_b32_e32 v20, 16, v50
	v_and_b32_e32 v21, 0xffff0000, v50
	v_mul_f32_e32 v20, v2, v20
	v_mul_f32_e32 v21, v3, v21
	v_cvt_pk_bf16_f32 v138, v20, v21
	v_lshlrev_b32_e32 v24, 16, v43
	v_and_b32_e32 v25, 0xffff0000, v43
	v_mul_f32_e32 v26, 0x3fb8aa3b, v24
	v_mul_f32_e32 v27, 0x3fb8aa3b, v25
	v_exp_f32_e32 v26, v26
	v_exp_f32_e32 v27, v27
	v_lshlrev_b32_e32 v24, 16, v47
	v_and_b32_e32 v25, 0xffff0000, v47
	v_fma_f32 v4, v4, v26, v24
	v_fma_f32 v5, v5, v27, v25
	v_lshlrev_b32_e32 v24, 16, v51
	v_and_b32_e32 v25, 0xffff0000, v51
	v_mul_f32_e32 v24, v4, v24
	v_mul_f32_e32 v25, v5, v25
	v_cvt_pk_bf16_f32 v139, v24, v25
	s_nop 0
	global_store_dwordx4 v[10:11], v[136:139], off
	v_lshl_add_u64 v[10:11], v[10:11], 0, v[18:19]
	s_waitcnt vmcnt(19)
	v_lshlrev_b32_e32 v20, 16, v52
	v_and_b32_e32 v21, 0xffff0000, v52
	v_mul_f32_e32 v22, 0x3fb8aa3b, v20
	v_mul_f32_e32 v23, 0x3fb8aa3b, v21
	v_exp_f32_e32 v22, v22
	v_exp_f32_e32 v23, v23
	v_lshlrev_b32_e32 v20, 16, v56
	v_and_b32_e32 v21, 0xffff0000, v56
	v_fma_f32 v6, v6, v22, v20
	v_fma_f32 v7, v7, v23, v21
	v_lshlrev_b32_e32 v20, 16, v60
	v_and_b32_e32 v21, 0xffff0000, v60
	v_mul_f32_e32 v20, v6, v20
	v_mul_f32_e32 v21, v7, v21
	v_cvt_pk_bf16_f32 v136, v20, v21
	v_lshlrev_b32_e32 v24, 16, v53
	v_and_b32_e32 v25, 0xffff0000, v53
	v_mul_f32_e32 v26, 0x3fb8aa3b, v24
	v_mul_f32_e32 v27, 0x3fb8aa3b, v25
	v_exp_f32_e32 v26, v26
	v_exp_f32_e32 v27, v27
	v_lshlrev_b32_e32 v24, 16, v57
	v_and_b32_e32 v25, 0xffff0000, v57
	v_fma_f32 v8, v8, v26, v24
	v_fma_f32 v9, v9, v27, v25
	v_lshlrev_b32_e32 v24, 16, v61
	v_and_b32_e32 v25, 0xffff0000, v61
	v_mul_f32_e32 v24, v8, v24
	v_mul_f32_e32 v25, v9, v25
	v_cvt_pk_bf16_f32 v137, v24, v25
	v_lshlrev_b32_e32 v20, 16, v54
	v_and_b32_e32 v21, 0xffff0000, v54
	v_mul_f32_e32 v22, 0x3fb8aa3b, v20
	v_mul_f32_e32 v23, 0x3fb8aa3b, v21
	v_exp_f32_e32 v22, v22
	v_exp_f32_e32 v23, v23
	v_lshlrev_b32_e32 v20, 16, v58
	v_and_b32_e32 v21, 0xffff0000, v58
	v_fma_f32 v2, v2, v22, v20
	v_fma_f32 v3, v3, v23, v21
	v_lshlrev_b32_e32 v20, 16, v62
	v_and_b32_e32 v21, 0xffff0000, v62
	v_mul_f32_e32 v20, v2, v20
	v_mul_f32_e32 v21, v3, v21
	v_cvt_pk_bf16_f32 v138, v20, v21
	v_lshlrev_b32_e32 v24, 16, v55
	v_and_b32_e32 v25, 0xffff0000, v55
	v_mul_f32_e32 v26, 0x3fb8aa3b, v24
	v_mul_f32_e32 v27, 0x3fb8aa3b, v25
	v_exp_f32_e32 v26, v26
	v_exp_f32_e32 v27, v27
	v_lshlrev_b32_e32 v24, 16, v59
	v_and_b32_e32 v25, 0xffff0000, v59
	v_fma_f32 v4, v4, v26, v24
	v_fma_f32 v5, v5, v27, v25
	v_lshlrev_b32_e32 v24, 16, v63
	v_and_b32_e32 v25, 0xffff0000, v63
	v_mul_f32_e32 v24, v4, v24
	v_mul_f32_e32 v25, v5, v25
	v_cvt_pk_bf16_f32 v139, v24, v25
	s_nop 0
	global_store_dwordx4 v[10:11], v[136:139], off
	v_lshl_add_u64 v[10:11], v[10:11], 0, v[18:19]
	s_waitcnt vmcnt(17)
; DI unsigned cvt_pk_bf16(float lo, float hi) { unsigned r; asm volatile("v_cvt_pk_bf16_f32 %0, %1, %2" : "=v"(r) : "v"(lo), "v"(hi)); return r; }
; DI void unpack8(const u32x4 v, float* f) { f[0] = bf_lo(v.x); f[1] = bf_hi(v.x); f[2] = bf_lo(v.y); f[3] = bf_hi(v.y); f[4] = bf_lo(v.z); f[5] = bf_hi(v.z); f[6] = bf_lo(v.w); f[7] = bf_hi(v.w); }
; DI void phase_scan2(const bf16_t* la, const bf16_t* bb, const bf16_t* y, const float* hin, bf16_t* yh) {
;     ...
;     for (int t = 0; t < 32; ++t) {
;       float l[8], bv[8], yv[8]; unpack8(*(const u32x4*)(la + base + (size_t)t * DM), l); unpack8(*(const u32x4*)(bb + base + (size_t)t * DM), bv); unpack8(*(const u32x4*)(y + base + (size_t)t * DM), yv);
;       float o[8];
; #pragma unroll
;       for (int e = 0; e < 8; ++e) { h[e] = __expf(l[e]) * h[e] + bv[e]; o[e] = h[e] * yv[e]; }
;       u32x4 wv; wv.x = cvt_pk_bf16(o[0], o[1]); wv.y = cvt_pk_bf16(o[2], o[3]); wv.z = cvt_pk_bf16(o[4], o[5]); wv.w = cvt_pk_bf16(o[6], o[7]);
;       *(u32x4*)(yh + base + (size_t)t * DM) = wv;
	v_lshlrev_b32_e32 v20, 16, v64
	v_and_b32_e32 v21, 0xffff0000, v64
	v_mul_f32_e32 v22, 0x3fb8aa3b, v20
	v_mul_f32_e32 v23, 0x3fb8aa3b, v21
	v_exp_f32_e32 v22, v22
	v_exp_f32_e32 v23, v23
	v_lshlrev_b32_e32 v20, 16, v68
	v_and_b32_e32 v21, 0xffff0000, v68
	v_fma_f32 v6, v6, v22, v20
	v_fma_f32 v7, v7, v23, v21
	v_lshlrev_b32_e32 v20, 16, v72
	v_and_b32_e32 v21, 0xffff0000, v72
	v_mul_f32_e32 v20, v6, v20
	v_mul_f32_e32 v21, v7, v21
	v_cvt_pk_bf16_f32 v136, v20, v21
	v_lshlrev_b32_e32 v24, 16, v65
	v_and_b32_e32 v25, 0xffff0000, v65
	v_mul_f32_e32 v26, 0x3fb8aa3b, v24
	v_mul_f32_e32 v27, 0x3fb8aa3b, v25
	v_exp_f32_e32 v26, v26
	v_exp_f32_e32 v27, v27
	v_lshlrev_b32_e32 v24, 16, v69
	v_and_b32_e32 v25, 0xffff0000, v69
	v_fma_f32 v8, v8, v26, v24
	v_fma_f32 v9, v9, v27, v25
	v_lshlrev_b32_e32 v24, 16, v73
	v_and_b32_e32 v25, 0xffff0000, v73
	v_mul_f32_e32 v24, v8, v24
	v_mul_f32_e32 v25, v9, v25
	v_cvt_pk_bf16_f32 v137, v24, v25
	v_lshlrev_b32_e32 v20, 16, v66
	v_and_b32_e32 v21, 0xffff0000, v66
	v_mul_f32_e32 v22, 0x3fb8aa3b, v20
	v_mul_f32_e32 v23, 0x3fb8aa3b, v21
	v_exp_f32_e32 v22, v22
	v_exp_f32_e32 v23, v23
	v_lshlrev_b32_e32 v20, 16, v70
	v_and_b32_e32 v21, 0xffff0000, v70
	v_fma_f32 v2, v2, v22, v20
	v_fma_f32 v3, v3, v23, v21
	v_lshlrev_b32_e32 v20, 16, v74
	v_and_b32_e32 v21, 0xffff0000, v74
	v_mul_f32_e32 v20, v2, v20
	v_mul_f32_e32 v21, v3, v21
	v_cvt_pk_bf16_f32 v138, v20, v21
	v_lshlrev_b32_e32 v24, 16, v67
	v_and_b32_e32 v25, 0xffff0000, v67
	v_mul_f32_e32 v26, 0x3fb8aa3b, v24
	v_mul_f32_e32 v27, 0x3fb8aa3b, v25
	v_exp_f32_e32 v26, v26
	v_exp_f32_e32 v27, v27
	v_lshlrev_b32_e32 v24, 16, v71
	v_and_b32_e32 v25, 0xffff0000, v71
	v_fma_f32 v4, v4, v26, v24
	v_fma_f32 v5, v5, v27, v25
	v_lshlrev_b32_e32 v24, 16, v75
	v_and_b32_e32 v25, 0xffff0000, v75
	v_mul_f32_e32 v24, v4, v24
	v_mul_f32_e32 v25, v5, v25
	v_cvt_pk_bf16_f32 v139, v24, v25
	s_nop 0
	global_store_dwordx4 v[10:11], v[136:139], off
	v_lshl_add_u64 v[10:11], v[10:11], 0, v[18:19]
	s_waitcnt vmcnt(15)
	v_lshlrev_b32_e32 v20, 16, v76
	v_and_b32_e32 v21, 0xffff0000, v76
	v_mul_f32_e32 v22, 0x3fb8aa3b, v20
	v_mul_f32_e32 v23, 0x3fb8aa3b, v21
	v_exp_f32_e32 v22, v22
	v_exp_f32_e32 v23, v23
	v_lshlrev_b32_e32 v20, 16, v80
	v_and_b32_e32 v21, 0xffff0000, v80
	v_fma_f32 v6, v6, v22, v20
	v_fma_f32 v7, v7, v23, v21
	v_lshlrev_b32_e32 v20, 16, v84
	v_and_b32_e32 v21, 0xffff0000, v84
	v_mul_f32_e32 v20, v6, v20
	v_mul_f32_e32 v21, v7, v21
	v_cvt_pk_bf16_f32 v136, v20, v21
	v_lshlrev_b32_e32 v24, 16, v77
	v_and_b32_e32 v25, 0xffff0000, v77
	v_mul_f32_e32 v26, 0x3fb8aa3b, v24
	v_mul_f32_e32 v27, 0x3fb8aa3b, v25
	v_exp_f32_e32 v26, v26
	v_exp_f32_e32 v27, v27
	v_lshlrev_b32_e32 v24, 16, v81
	v_and_b32_e32 v25, 0xffff0000, v81
	v_fma_f32 v8, v8, v26, v24
	v_fma_f32 v9, v9, v27, v25
	v_lshlrev_b32_e32 v24, 16, v85
	v_and_b32_e32 v25, 0xffff0000, v85
	v_mul_f32_e32 v24, v8, v24
	v_mul_f32_e32 v25, v9, v25
	v_cvt_pk_bf16_f32 v137, v24, v25
	v_lshlrev_b32_e32 v20, 16, v78
	v_and_b32_e32 v21, 0xffff0000, v78
	v_mul_f32_e32 v22, 0x3fb8aa3b, v20
	v_mul_f32_e32 v23, 0x3fb8aa3b, v21
	v_exp_f32_e32 v22, v22
	v_exp_f32_e32 v23, v23
	v_lshlrev_b32_e32 v20, 16, v82
	v_and_b32_e32 v21, 0xffff0000, v82
	v_fma_f32 v2, v2, v22, v20
	v_fma_f32 v3, v3, v23, v21
	v_lshlrev_b32_e32 v20, 16, v86
	v_and_b32_e32 v21, 0xffff0000, v86
	v_mul_f32_e32 v20, v2, v20
	v_mul_f32_e32 v21, v3, v21
	v_cvt_pk_bf16_f32 v138, v20, v21
	v_lshlrev_b32_e32 v24, 16, v79
	v_and_b32_e32 v25, 0xffff0000, v79
	v_mul_f32_e32 v26, 0x3fb8aa3b, v24
	v_mul_f32_e32 v27, 0x3fb8aa3b, v25
	v_exp_f32_e32 v26, v26
	v_exp_f32_e32 v27, v27
	v_lshlrev_b32_e32 v24, 16, v83
	v_and_b32_e32 v25, 0xffff0000, v83
	v_fma_f32 v4, v4, v26, v24
	v_fma_f32 v5, v5, v27, v25
	v_lshlrev_b32_e32 v24, 16, v87
	v_and_b32_e32 v25, 0xffff0000, v87
	v_mul_f32_e32 v24, v4, v24
	v_mul_f32_e32 v25, v5, v25
	v_cvt_pk_bf16_f32 v139, v24, v25
	s_nop 0
	global_store_dwordx4 v[10:11], v[136:139], off
	v_lshl_add_u64 v[10:11], v[10:11], 0, v[18:19]
	global_load_dwordx4 v[40:43], v[16:17], off
	global_load_dwordx4 v[44:47], v[14:15], off
	global_load_dwordx4 v[48:51], v[12:13], off
	v_lshl_add_u64 v[16:17], v[16:17], 0, v[18:19]
	v_lshl_add_u64 v[14:15], v[14:15], 0, v[18:19]
	v_lshl_add_u64 v[12:13], v[12:13], 0, v[18:19]
	global_load_dwordx4 v[52:55], v[16:17], off
	global_load_dwordx4 v[56:59], v[14:15], off
	global_load_dwordx4 v[60:63], v[12:13], off
	v_lshl_add_u64 v[16:17], v[16:17], 0, v[18:19]
	v_lshl_add_u64 v[14:15], v[14:15], 0, v[18:19]
	v_lshl_add_u64 v[12:13], v[12:13], 0, v[18:19]
	global_load_dwordx4 v[64:67], v[16:17], off
	global_load_dwordx4 v[68:71], v[14:15], off
	global_load_dwordx4 v[72:75], v[12:13], off
	v_lshl_add_u64 v[16:17], v[16:17], 0, v[18:19]
	v_lshl_add_u64 v[14:15], v[14:15], 0, v[18:19]
	v_lshl_add_u64 v[12:13], v[12:13], 0, v[18:19]
	global_load_dwordx4 v[76:79], v[16:17], off
	global_load_dwordx4 v[80:83], v[14:15], off
	global_load_dwordx4 v[84:87], v[12:13], off
	v_lshl_add_u64 v[16:17], v[16:17], 0, v[18:19]
	v_lshl_add_u64 v[14:15], v[14:15], 0, v[18:19]
	v_lshl_add_u64 v[12:13], v[12:13], 0, v[18:19]
	s_waitcnt vmcnt(25)
; DI unsigned cvt_pk_bf16(float lo, float hi) { unsigned r; asm volatile("v_cvt_pk_bf16_f32 %0, %1, %2" : "=v"(r) : "v"(lo), "v"(hi)); return r; }
; DI void unpack8(const u32x4 v, float* f) { f[0] = bf_lo(v.x); f[1] = bf_hi(v.x); f[2] = bf_lo(v.y); f[3] = bf_hi(v.y); f[4] = bf_lo(v.z); f[5] = bf_hi(v.z); f[6] = bf_lo(v.w); f[7] = bf_hi(v.w); }
; DI void phase_scan2(const bf16_t* la, const bf16_t* bb, const bf16_t* y, const float* hin, bf16_t* yh) {
;     ...
;     for (int t = 0; t < 32; ++t) {
;       float l[8], bv[8], yv[8]; unpack8(*(const u32x4*)(la + base + (size_t)t * DM), l); unpack8(*(const u32x4*)(bb + base + (size_t)t * DM), bv); unpack8(*(const u32x4*)(y + base + (size_t)t * DM), yv);
;       float o[8];
; #pragma unroll
;       for (int e = 0; e < 8; ++e) { h[e] = __expf(l[e]) * h[e] + bv[e]; o[e] = h[e] * yv[e]; }
;       u32x4 wv; wv.x = cvt_pk_bf16(o[0], o[1]); wv.y = cvt_pk_bf16(o[2], o[3]); wv.z = cvt_pk_bf16(o[4], o[5]); wv.w = cvt_pk_bf16(o[6], o[7]);
;       *(u32x4*)(yh + base + (size_t)t * DM) = wv;
	v_lshlrev_b32_e32 v20, 16, v88
	v_and_b32_e32 v21, 0xffff0000, v88
	v_mul_f32_e32 v22, 0x3fb8aa3b, v20
	v_mul_f32_e32 v23, 0x3fb8aa3b, v21
	v_exp_f32_e32 v22, v22
	v_exp_f32_e32 v23, v23
	v_lshlrev_b32_e32 v20, 16, v92
	v_and_b32_e32 v21, 0xffff0000, v92
	v_fma_f32 v6, v6, v22, v20
	v_fma_f32 v7, v7, v23, v21
	v_lshlrev_b32_e32 v20, 16, v96
	v_and_b32_e32 v21, 0xffff0000, v96
	v_mul_f32_e32 v20, v6, v20
	v_mul_f32_e32 v21, v7, v21
	v_cvt_pk_bf16_f32 v136, v20, v21
	v_lshlrev_b32_e32 v24, 16, v89
	v_and_b32_e32 v25, 0xffff0000, v89
	v_mul_f32_e32 v26, 0x3fb8aa3b, v24
	v_mul_f32_e32 v27, 0x3fb8aa3b, v25
	v_exp_f32_e32 v26, v26
	v_exp_f32_e32 v27, v27
	v_lshlrev_b32_e32 v24, 16, v93
	v_and_b32_e32 v25, 0xffff0000, v93
	v_fma_f32 v8, v8, v26, v24
	v_fma_f32 v9, v9, v27, v25
	v_lshlrev_b32_e32 v24, 16, v97
	v_and_b32_e32 v25, 0xffff0000, v97
	v_mul_f32_e32 v24, v8, v24
	v_mul_f32_e32 v25, v9, v25
	v_cvt_pk_bf16_f32 v137, v24, v25
	v_lshlrev_b32_e32 v20, 16, v90
	v_and_b32_e32 v21, 0xffff0000, v90
	v_mul_f32_e32 v22, 0x3fb8aa3b, v20
	v_mul_f32_e32 v23, 0x3fb8aa3b, v21
	v_exp_f32_e32 v22, v22
	v_exp_f32_e32 v23, v23
	v_lshlrev_b32_e32 v20, 16, v94
	v_and_b32_e32 v21, 0xffff0000, v94
	v_fma_f32 v2, v2, v22, v20
	v_fma_f32 v3, v3, v23, v21
	v_lshlrev_b32_e32 v20, 16, v98
	v_and_b32_e32 v21, 0xffff0000, v98
	v_mul_f32_e32 v20, v2, v20
	v_mul_f32_e32 v21, v3, v21
	v_cvt_pk_bf16_f32 v138, v20, v21
	v_lshlrev_b32_e32 v24, 16, v91
	v_and_b32_e32 v25, 0xffff0000, v91
	v_mul_f32_e32 v26, 0x3fb8aa3b, v24
	v_mul_f32_e32 v27, 0x3fb8aa3b, v25
	v_exp_f32_e32 v26, v26
	v_exp_f32_e32 v27, v27
	v_lshlrev_b32_e32 v24, 16, v95
	v_and_b32_e32 v25, 0xffff0000, v95
	v_fma_f32 v4, v4, v26, v24
	v_fma_f32 v5, v5, v27, v25
	v_lshlrev_b32_e32 v24, 16, v99
	v_and_b32_e32 v25, 0xffff0000, v99
	v_mul_f32_e32 v24, v4, v24
	v_mul_f32_e32 v25, v5, v25
	v_cvt_pk_bf16_f32 v139, v24, v25
	s_nop 0
	global_store_dwordx4 v[10:11], v[136:139], off
	v_lshl_add_u64 v[10:11], v[10:11], 0, v[18:19]
	s_waitcnt vmcnt(23)
	v_lshlrev_b32_e32 v20, 16, v100
	v_and_b32_e32 v21, 0xffff0000, v100
	v_mul_f32_e32 v22, 0x3fb8aa3b, v20
	v_mul_f32_e32 v23, 0x3fb8aa3b, v21
	v_exp_f32_e32 v22, v22
	v_exp_f32_e32 v23, v23
	v_lshlrev_b32_e32 v20, 16, v104
	v_and_b32_e32 v21, 0xffff0000, v104
	v_fma_f32 v6, v6, v22, v20
	v_fma_f32 v7, v7, v23, v21
	v_lshlrev_b32_e32 v20, 16, v108
	v_and_b32_e32 v21, 0xffff0000, v108
	v_mul_f32_e32 v20, v6, v20
	v_mul_f32_e32 v21, v7, v21
	v_cvt_pk_bf16_f32 v136, v20, v21
	v_lshlrev_b32_e32 v24, 16, v101
	v_and_b32_e32 v25, 0xffff0000, v101
	v_mul_f32_e32 v26, 0x3fb8aa3b, v24
	v_mul_f32_e32 v27, 0x3fb8aa3b, v25
	v_exp_f32_e32 v26, v26
	v_exp_f32_e32 v27, v27
	v_lshlrev_b32_e32 v24, 16, v105
	v_and_b32_e32 v25, 0xffff0000, v105
	v_fma_f32 v8, v8, v26, v24
	v_fma_f32 v9, v9, v27, v25
	v_lshlrev_b32_e32 v24, 16, v109
	v_and_b32_e32 v25, 0xffff0000, v109
	v_mul_f32_e32 v24, v8, v24
	v_mul_f32_e32 v25, v9, v25
	v_cvt_pk_bf16_f32 v137, v24, v25
	v_lshlrev_b32_e32 v20, 16, v102
	v_and_b32_e32 v21, 0xffff0000, v102
	v_mul_f32_e32 v22, 0x3fb8aa3b, v20
	v_mul_f32_e32 v23, 0x3fb8aa3b, v21
	v_exp_f32_e32 v22, v22
	v_exp_f32_e32 v23, v23
	v_lshlrev_b32_e32 v20, 16, v106
	v_and_b32_e32 v21, 0xffff0000, v106
	v_fma_f32 v2, v2, v22, v20
	v_fma_f32 v3, v3, v23, v21
	v_lshlrev_b32_e32 v20, 16, v110
	v_and_b32_e32 v21, 0xffff0000, v110
	v_mul_f32_e32 v20, v2, v20
	v_mul_f32_e32 v21, v3, v21
	v_cvt_pk_bf16_f32 v138, v20, v21
	v_lshlrev_b32_e32 v24, 16, v103
	v_and_b32_e32 v25, 0xffff0000, v103
	v_mul_f32_e32 v26, 0x3fb8aa3b, v24
	v_mul_f32_e32 v27, 0x3fb8aa3b, v25
	v_exp_f32_e32 v26, v26
	v_exp_f32_e32 v27, v27
	v_lshlrev_b32_e32 v24, 16, v107
	v_and_b32_e32 v25, 0xffff0000, v107
	v_fma_f32 v4, v4, v26, v24
	v_fma_f32 v5, v5, v27, v25
	v_lshlrev_b32_e32 v24, 16, v111
	v_and_b32_e32 v25, 0xffff0000, v111
	v_mul_f32_e32 v24, v4, v24
	v_mul_f32_e32 v25, v5, v25
	v_cvt_pk_bf16_f32 v139, v24, v25
	s_nop 0
	global_store_dwordx4 v[10:11], v[136:139], off
	v_lshl_add_u64 v[10:11], v[10:11], 0, v[18:19]
	s_waitcnt vmcnt(21)
	v_lshlrev_b32_e32 v20, 16, v112
	v_and_b32_e32 v21, 0xffff0000, v112
	v_mul_f32_e32 v22, 0x3fb8aa3b, v20
	v_mul_f32_e32 v23, 0x3fb8aa3b, v21
	v_exp_f32_e32 v22, v22
	v_exp_f32_e32 v23, v23
	v_lshlrev_b32_e32 v20, 16, v116
	v_and_b32_e32 v21, 0xffff0000, v116
	v_fma_f32 v6, v6, v22, v20
	v_fma_f32 v7, v7, v23, v21
	v_lshlrev_b32_e32 v20, 16, v120
	v_and_b32_e32 v21, 0xffff0000, v120
	v_mul_f32_e32 v20, v6, v20
	v_mul_f32_e32 v21, v7, v21
	v_cvt_pk_bf16_f32 v136, v20, v21
	v_lshlrev_b32_e32 v24, 16, v113
	v_and_b32_e32 v25, 0xffff0000, v113
	v_mul_f32_e32 v26, 0x3fb8aa3b, v24
	v_mul_f32_e32 v27, 0x3fb8aa3b, v25
	v_exp_f32_e32 v26, v26
	v_exp_f32_e32 v27, v27
	v_lshlrev_b32_e32 v24, 16, v117
	v_and_b32_e32 v25, 0xffff0000, v117
	v_fma_f32 v8, v8, v26, v24
	v_fma_f32 v9, v9, v27, v25
	v_lshlrev_b32_e32 v24, 16, v121
	v_and_b32_e32 v25, 0xffff0000, v121
	v_mul_f32_e32 v24, v8, v24
	v_mul_f32_e32 v25, v9, v25
	v_cvt_pk_bf16_f32 v137, v24, v25
	v_lshlrev_b32_e32 v20, 16, v114
	v_and_b32_e32 v21, 0xffff0000, v114
	v_mul_f32_e32 v22, 0x3fb8aa3b, v20
	v_mul_f32_e32 v23, 0x3fb8aa3b, v21
	v_exp_f32_e32 v22, v22
	v_exp_f32_e32 v23, v23
	v_lshlrev_b32_e32 v20, 16, v118
	v_and_b32_e32 v21, 0xffff0000, v118
	v_fma_f32 v2, v2, v22, v20
	v_fma_f32 v3, v3, v23, v21
	v_lshlrev_b32_e32 v20, 16, v122
	v_and_b32_e32 v21, 0xffff0000, v122
	v_mul_f32_e32 v20, v2, v20
	v_mul_f32_e32 v21, v3, v21
	v_cvt_pk_bf16_f32 v138, v20, v21
	v_lshlrev_b32_e32 v24, 16, v115
	v_and_b32_e32 v25, 0xffff0000, v115
	v_mul_f32_e32 v26, 0x3fb8aa3b, v24
	v_mul_f32_e32 v27, 0x3fb8aa3b, v25
	v_exp_f32_e32 v26, v26
	v_exp_f32_e32 v27, v27
	v_lshlrev_b32_e32 v24, 16, v119
	v_and_b32_e32 v25, 0xffff0000, v119
	v_fma_f32 v4, v4, v26, v24
	v_fma_f32 v5, v5, v27, v25
	v_lshlrev_b32_e32 v24, 16, v123
	v_and_b32_e32 v25, 0xffff0000, v123
	v_mul_f32_e32 v24, v4, v24
	v_mul_f32_e32 v25, v5, v25
	v_cvt_pk_bf16_f32 v139, v24, v25
	s_nop 0
	global_store_dwordx4 v[10:11], v[136:139], off
	v_lshl_add_u64 v[10:11], v[10:11], 0, v[18:19]
	s_waitcnt vmcnt(19)
; DI unsigned cvt_pk_bf16(float lo, float hi) { unsigned r; asm volatile("v_cvt_pk_bf16_f32 %0, %1, %2" : "=v"(r) : "v"(lo), "v"(hi)); return r; }
; DI void unpack8(const u32x4 v, float* f) { f[0] = bf_lo(v.x); f[1] = bf_hi(v.x); f[2] = bf_lo(v.y); f[3] = bf_hi(v.y); f[4] = bf_lo(v.z); f[5] = bf_hi(v.z); f[6] = bf_lo(v.w); f[7] = bf_hi(v.w); }
; DI void phase_scan2(const bf16_t* la, const bf16_t* bb, const bf16_t* y, const float* hin, bf16_t* yh) {
;     ...
;     for (int t = 0; t < 32; ++t) {
;       float l[8], bv[8], yv[8]; unpack8(*(const u32x4*)(la + base + (size_t)t * DM), l); unpack8(*(const u32x4*)(bb + base + (size_t)t * DM), bv); unpack8(*(const u32x4*)(y + base + (size_t)t * DM), yv);
;       float o[8];
; #pragma unroll
;       for (int e = 0; e < 8; ++e) { h[e] = __expf(l[e]) * h[e] + bv[e]; o[e] = h[e] * yv[e]; }
;       u32x4 wv; wv.x = cvt_pk_bf16(o[0], o[1]); wv.y = cvt_pk_bf16(o[2], o[3]); wv.z = cvt_pk_bf16(o[4], o[5]); wv.w = cvt_pk_bf16(o[6], o[7]);
;       *(u32x4*)(yh + base + (size_t)t * DM) = wv;
	v_lshlrev_b32_e32 v20, 16, v124
	v_and_b32_e32 v21, 0xffff0000, v124
	v_mul_f32_e32 v22, 0x3fb8aa3b, v20
	v_mul_f32_e32 v23, 0x3fb8aa3b, v21
	v_exp_f32_e32 v22, v22
	v_exp_f32_e32 v23, v23
	v_lshlrev_b32_e32 v20, 16, v128
	v_and_b32_e32 v21, 0xffff0000, v128
	v_fma_f32 v6, v6, v22, v20
	v_fma_f32 v7, v7, v23, v21
	v_lshlrev_b32_e32 v20, 16, v132
	v_and_b32_e32 v21, 0xffff0000, v132
	v_mul_f32_e32 v20, v6, v20
	v_mul_f32_e32 v21, v7, v21
	v_cvt_pk_bf16_f32 v136, v20, v21
	v_lshlrev_b32_e32 v24, 16, v125
	v_and_b32_e32 v25, 0xffff0000, v125
	v_mul_f32_e32 v26, 0x3fb8aa3b, v24
	v_mul_f32_e32 v27, 0x3fb8aa3b, v25
	v_exp_f32_e32 v26, v26
	v_exp_f32_e32 v27, v27
	v_lshlrev_b32_e32 v24, 16, v129
	v_and_b32_e32 v25, 0xffff0000, v129
	v_fma_f32 v8, v8, v26, v24
	v_fma_f32 v9, v9, v27, v25
	v_lshlrev_b32_e32 v24, 16, v133
	v_and_b32_e32 v25, 0xffff0000, v133
	v_mul_f32_e32 v24, v8, v24
	v_mul_f32_e32 v25, v9, v25
	v_cvt_pk_bf16_f32 v137, v24, v25
	v_lshlrev_b32_e32 v20, 16, v126
	v_and_b32_e32 v21, 0xffff0000, v126
	v_mul_f32_e32 v22, 0x3fb8aa3b, v20
	v_mul_f32_e32 v23, 0x3fb8aa3b, v21
	v_exp_f32_e32 v22, v22
	v_exp_f32_e32 v23, v23
	v_lshlrev_b32_e32 v20, 16, v130
	v_and_b32_e32 v21, 0xffff0000, v130
	v_fma_f32 v2, v2, v22, v20
	v_fma_f32 v3, v3, v23, v21
	v_lshlrev_b32_e32 v20, 16, v134
	v_and_b32_e32 v21, 0xffff0000, v134
	v_mul_f32_e32 v20, v2, v20
	v_mul_f32_e32 v21, v3, v21
	v_cvt_pk_bf16_f32 v138, v20, v21
	v_lshlrev_b32_e32 v24, 16, v127
	v_and_b32_e32 v25, 0xffff0000, v127
	v_mul_f32_e32 v26, 0x3fb8aa3b, v24
	v_mul_f32_e32 v27, 0x3fb8aa3b, v25
	v_exp_f32_e32 v26, v26
	v_exp_f32_e32 v27, v27
	v_lshlrev_b32_e32 v24, 16, v131
	v_and_b32_e32 v25, 0xffff0000, v131
	v_fma_f32 v4, v4, v26, v24
	v_fma_f32 v5, v5, v27, v25
	v_lshlrev_b32_e32 v24, 16, v135
	v_and_b32_e32 v25, 0xffff0000, v135
	v_mul_f32_e32 v24, v4, v24
	v_mul_f32_e32 v25, v5, v25
	v_cvt_pk_bf16_f32 v139, v24, v25
	s_nop 0
	global_store_dwordx4 v[10:11], v[136:139], off
	v_lshl_add_u64 v[10:11], v[10:11], 0, v[18:19]
	global_load_dwordx4 v[88:91], v[16:17], off
	global_load_dwordx4 v[92:95], v[14:15], off
	global_load_dwordx4 v[96:99], v[12:13], off
	v_lshl_add_u64 v[16:17], v[16:17], 0, v[18:19]
	v_lshl_add_u64 v[14:15], v[14:15], 0, v[18:19]
	v_lshl_add_u64 v[12:13], v[12:13], 0, v[18:19]
	global_load_dwordx4 v[100:103], v[16:17], off
	global_load_dwordx4 v[104:107], v[14:15], off
	global_load_dwordx4 v[108:111], v[12:13], off
	v_lshl_add_u64 v[16:17], v[16:17], 0, v[18:19]
	v_lshl_add_u64 v[14:15], v[14:15], 0, v[18:19]
	v_lshl_add_u64 v[12:13], v[12:13], 0, v[18:19]
	global_load_dwordx4 v[112:115], v[16:17], off
	global_load_dwordx4 v[116:119], v[14:15], off
	global_load_dwordx4 v[120:123], v[12:13], off
	v_lshl_add_u64 v[16:17], v[16:17], 0, v[18:19]
	v_lshl_add_u64 v[14:15], v[14:15], 0, v[18:19]
	v_lshl_add_u64 v[12:13], v[12:13], 0, v[18:19]
	global_load_dwordx4 v[124:127], v[16:17], off
	global_load_dwordx4 v[128:131], v[14:15], off
	global_load_dwordx4 v[132:135], v[12:13], off
	v_lshl_add_u64 v[16:17], v[16:17], 0, v[18:19]
	v_lshl_add_u64 v[14:15], v[14:15], 0, v[18:19]
	v_lshl_add_u64 v[12:13], v[12:13], 0, v[18:19]
	s_waitcnt vmcnt(25)
	v_lshlrev_b32_e32 v20, 16, v40
	v_and_b32_e32 v21, 0xffff0000, v40
	v_mul_f32_e32 v22, 0x3fb8aa3b, v20
	v_mul_f32_e32 v23, 0x3fb8aa3b, v21
	v_exp_f32_e32 v22, v22
	v_exp_f32_e32 v23, v23
	v_lshlrev_b32_e32 v20, 16, v44
	v_and_b32_e32 v21, 0xffff0000, v44
	v_fma_f32 v6, v6, v22, v20
	v_fma_f32 v7, v7, v23, v21
	v_lshlrev_b32_e32 v20, 16, v48
	v_and_b32_e32 v21, 0xffff0000, v48
	v_mul_f32_e32 v20, v6, v20
	v_mul_f32_e32 v21, v7, v21
	v_cvt_pk_bf16_f32 v136, v20, v21
	v_lshlrev_b32_e32 v24, 16, v41
	v_and_b32_e32 v25, 0xffff0000, v41
	v_mul_f32_e32 v26, 0x3fb8aa3b, v24
	v_mul_f32_e32 v27, 0x3fb8aa3b, v25
	v_exp_f32_e32 v26, v26
	v_exp_f32_e32 v27, v27
	v_lshlrev_b32_e32 v24, 16, v45
	v_and_b32_e32 v25, 0xffff0000, v45
	v_fma_f32 v8, v8, v26, v24
	v_fma_f32 v9, v9, v27, v25
	v_lshlrev_b32_e32 v24, 16, v49
	v_and_b32_e32 v25, 0xffff0000, v49
	v_mul_f32_e32 v24, v8, v24
	v_mul_f32_e32 v25, v9, v25
	v_cvt_pk_bf16_f32 v137, v24, v25
	v_lshlrev_b32_e32 v20, 16, v42
	v_and_b32_e32 v21, 0xffff0000, v42
	v_mul_f32_e32 v22, 0x3fb8aa3b, v20
	v_mul_f32_e32 v23, 0x3fb8aa3b, v21
	v_exp_f32_e32 v22, v22
	v_exp_f32_e32 v23, v23
	v_lshlrev_b32_e32 v20, 16, v46
	v_and_b32_e32 v21, 0xffff0000, v46
	v_fma_f32 v2, v2, v22, v20
	v_fma_f32 v3, v3, v23, v21
	v_lshlrev_b32_e32 v20, 16, v50
	v_and_b32_e32 v21, 0xffff0000, v50
	v_mul_f32_e32 v20, v2, v20
	v_mul_f32_e32 v21, v3, v21
	v_cvt_pk_bf16_f32 v138, v20, v21
	v_lshlrev_b32_e32 v24, 16, v43
	v_and_b32_e32 v25, 0xffff0000, v43
	v_mul_f32_e32 v26, 0x3fb8aa3b, v24
	v_mul_f32_e32 v27, 0x3fb8aa3b, v25
	v_exp_f32_e32 v26, v26
	v_exp_f32_e32 v27, v27
	v_lshlrev_b32_e32 v24, 16, v47
	v_and_b32_e32 v25, 0xffff0000, v47
	v_fma_f32 v4, v4, v26, v24
	v_fma_f32 v5, v5, v27, v25
	v_lshlrev_b32_e32 v24, 16, v51
	v_and_b32_e32 v25, 0xffff0000, v51
	v_mul_f32_e32 v24, v4, v24
	v_mul_f32_e32 v25, v5, v25
	v_cvt_pk_bf16_f32 v139, v24, v25
	s_nop 0
	global_store_dwordx4 v[10:11], v[136:139], off
	v_lshl_add_u64 v[10:11], v[10:11], 0, v[18:19]
	s_waitcnt vmcnt(23)
; DI unsigned cvt_pk_bf16(float lo, float hi) { unsigned r; asm volatile("v_cvt_pk_bf16_f32 %0, %1, %2" : "=v"(r) : "v"(lo), "v"(hi)); return r; }
; DI void unpack8(const u32x4 v, float* f) { f[0] = bf_lo(v.x); f[1] = bf_hi(v.x); f[2] = bf_lo(v.y); f[3] = bf_hi(v.y); f[4] = bf_lo(v.z); f[5] = bf_hi(v.z); f[6] = bf_lo(v.w); f[7] = bf_hi(v.w); }
; DI void phase_scan2(const bf16_t* la, const bf16_t* bb, const bf16_t* y, const float* hin, bf16_t* yh) {
;     ...
;     for (int t = 0; t < 32; ++t) {
;       float l[8], bv[8], yv[8]; unpack8(*(const u32x4*)(la + base + (size_t)t * DM), l); unpack8(*(const u32x4*)(bb + base + (size_t)t * DM), bv); unpack8(*(const u32x4*)(y + base + (size_t)t * DM), yv);
;       float o[8];
; #pragma unroll
;       for (int e = 0; e < 8; ++e) { h[e] = __expf(l[e]) * h[e] + bv[e]; o[e] = h[e] * yv[e]; }
;       u32x4 wv; wv.x = cvt_pk_bf16(o[0], o[1]); wv.y = cvt_pk_bf16(o[2], o[3]); wv.z = cvt_pk_bf16(o[4], o[5]); wv.w = cvt_pk_bf16(o[6], o[7]);
;       *(u32x4*)(yh + base + (size_t)t * DM) = wv;
	v_lshlrev_b32_e32 v20, 16, v52
	v_and_b32_e32 v21, 0xffff0000, v52
	v_mul_f32_e32 v22, 0x3fb8aa3b, v20
	v_mul_f32_e32 v23, 0x3fb8aa3b, v21
	v_exp_f32_e32 v22, v22
	v_exp_f32_e32 v23, v23
	v_lshlrev_b32_e32 v20, 16, v56
	v_and_b32_e32 v21, 0xffff0000, v56
	v_fma_f32 v6, v6, v22, v20
	v_fma_f32 v7, v7, v23, v21
	v_lshlrev_b32_e32 v20, 16, v60
	v_and_b32_e32 v21, 0xffff0000, v60
	v_mul_f32_e32 v20, v6, v20
	v_mul_f32_e32 v21, v7, v21
	v_cvt_pk_bf16_f32 v136, v20, v21
	v_lshlrev_b32_e32 v24, 16, v53
	v_and_b32_e32 v25, 0xffff0000, v53
	v_mul_f32_e32 v26, 0x3fb8aa3b, v24
	v_mul_f32_e32 v27, 0x3fb8aa3b, v25
	v_exp_f32_e32 v26, v26
	v_exp_f32_e32 v27, v27
	v_lshlrev_b32_e32 v24, 16, v57
	v_and_b32_e32 v25, 0xffff0000, v57
	v_fma_f32 v8, v8, v26, v24
	v_fma_f32 v9, v9, v27, v25
	v_lshlrev_b32_e32 v24, 16, v61
	v_and_b32_e32 v25, 0xffff0000, v61
	v_mul_f32_e32 v24, v8, v24
	v_mul_f32_e32 v25, v9, v25
	v_cvt_pk_bf16_f32 v137, v24, v25
	v_lshlrev_b32_e32 v20, 16, v54
	v_and_b32_e32 v21, 0xffff0000, v54
	v_mul_f32_e32 v22, 0x3fb8aa3b, v20
	v_mul_f32_e32 v23, 0x3fb8aa3b, v21
	v_exp_f32_e32 v22, v22
	v_exp_f32_e32 v23, v23
	v_lshlrev_b32_e32 v20, 16, v58
	v_and_b32_e32 v21, 0xffff0000, v58
	v_fma_f32 v2, v2, v22, v20
	v_fma_f32 v3, v3, v23, v21
	v_lshlrev_b32_e32 v20, 16, v62
	v_and_b32_e32 v21, 0xffff0000, v62
	v_mul_f32_e32 v20, v2, v20
	v_mul_f32_e32 v21, v3, v21
	v_cvt_pk_bf16_f32 v138, v20, v21
	v_lshlrev_b32_e32 v24, 16, v55
	v_and_b32_e32 v25, 0xffff0000, v55
	v_mul_f32_e32 v26, 0x3fb8aa3b, v24
	v_mul_f32_e32 v27, 0x3fb8aa3b, v25
	v_exp_f32_e32 v26, v26
	v_exp_f32_e32 v27, v27
	v_lshlrev_b32_e32 v24, 16, v59
	v_and_b32_e32 v25, 0xffff0000, v59
	v_fma_f32 v4, v4, v26, v24
	v_fma_f32 v5, v5, v27, v25
	v_lshlrev_b32_e32 v24, 16, v63
	v_and_b32_e32 v25, 0xffff0000, v63
	v_mul_f32_e32 v24, v4, v24
	v_mul_f32_e32 v25, v5, v25
	v_cvt_pk_bf16_f32 v139, v24, v25
	s_nop 0
	global_store_dwordx4 v[10:11], v[136:139], off
	v_lshl_add_u64 v[10:11], v[10:11], 0, v[18:19]
	s_waitcnt vmcnt(21)
	v_lshlrev_b32_e32 v20, 16, v64
	v_and_b32_e32 v21, 0xffff0000, v64
	v_mul_f32_e32 v22, 0x3fb8aa3b, v20
	v_mul_f32_e32 v23, 0x3fb8aa3b, v21
	v_exp_f32_e32 v22, v22
	v_exp_f32_e32 v23, v23
	v_lshlrev_b32_e32 v20, 16, v68
	v_and_b32_e32 v21, 0xffff0000, v68
	v_fma_f32 v6, v6, v22, v20
	v_fma_f32 v7, v7, v23, v21
	v_lshlrev_b32_e32 v20, 16, v72
	v_and_b32_e32 v21, 0xffff0000, v72
	v_mul_f32_e32 v20, v6, v20
	v_mul_f32_e32 v21, v7, v21
	v_cvt_pk_bf16_f32 v136, v20, v21
	v_lshlrev_b32_e32 v24, 16, v65
	v_and_b32_e32 v25, 0xffff0000, v65
	v_mul_f32_e32 v26, 0x3fb8aa3b, v24
	v_mul_f32_e32 v27, 0x3fb8aa3b, v25
	v_exp_f32_e32 v26, v26
	v_exp_f32_e32 v27, v27
	v_lshlrev_b32_e32 v24, 16, v69
	v_and_b32_e32 v25, 0xffff0000, v69
	v_fma_f32 v8, v8, v26, v24
	v_fma_f32 v9, v9, v27, v25
	v_lshlrev_b32_e32 v24, 16, v73
	v_and_b32_e32 v25, 0xffff0000, v73
	v_mul_f32_e32 v24, v8, v24
	v_mul_f32_e32 v25, v9, v25
	v_cvt_pk_bf16_f32 v137, v24, v25
	v_lshlrev_b32_e32 v20, 16, v66
	v_and_b32_e32 v21, 0xffff0000, v66
	v_mul_f32_e32 v22, 0x3fb8aa3b, v20
	v_mul_f32_e32 v23, 0x3fb8aa3b, v21
	v_exp_f32_e32 v22, v22
	v_exp_f32_e32 v23, v23
	v_lshlrev_b32_e32 v20, 16, v70
	v_and_b32_e32 v21, 0xffff0000, v70
	v_fma_f32 v2, v2, v22, v20
	v_fma_f32 v3, v3, v23, v21
	v_lshlrev_b32_e32 v20, 16, v74
	v_and_b32_e32 v21, 0xffff0000, v74
	v_mul_f32_e32 v20, v2, v20
	v_mul_f32_e32 v21, v3, v21
	v_cvt_pk_bf16_f32 v138, v20, v21
	v_lshlrev_b32_e32 v24, 16, v67
	v_and_b32_e32 v25, 0xffff0000, v67
	v_mul_f32_e32 v26, 0x3fb8aa3b, v24
	v_mul_f32_e32 v27, 0x3fb8aa3b, v25
	v_exp_f32_e32 v26, v26
	v_exp_f32_e32 v27, v27
	v_lshlrev_b32_e32 v24, 16, v71
	v_and_b32_e32 v25, 0xffff0000, v71
	v_fma_f32 v4, v4, v26, v24
	v_fma_f32 v5, v5, v27, v25
	v_lshlrev_b32_e32 v24, 16, v75
	v_and_b32_e32 v25, 0xffff0000, v75
	v_mul_f32_e32 v24, v4, v24
	v_mul_f32_e32 v25, v5, v25
	v_cvt_pk_bf16_f32 v139, v24, v25
	s_nop 0
	global_store_dwordx4 v[10:11], v[136:139], off
	v_lshl_add_u64 v[10:11], v[10:11], 0, v[18:19]
	s_waitcnt vmcnt(19)
	v_lshlrev_b32_e32 v20, 16, v76
	v_and_b32_e32 v21, 0xffff0000, v76
	v_mul_f32_e32 v22, 0x3fb8aa3b, v20
	v_mul_f32_e32 v23, 0x3fb8aa3b, v21
	v_exp_f32_e32 v22, v22
	v_exp_f32_e32 v23, v23
	v_lshlrev_b32_e32 v20, 16, v80
	v_and_b32_e32 v21, 0xffff0000, v80
	v_fma_f32 v6, v6, v22, v20
	v_fma_f32 v7, v7, v23, v21
	v_lshlrev_b32_e32 v20, 16, v84
	v_and_b32_e32 v21, 0xffff0000, v84
	v_mul_f32_e32 v20, v6, v20
	v_mul_f32_e32 v21, v7, v21
	v_cvt_pk_bf16_f32 v136, v20, v21
	v_lshlrev_b32_e32 v24, 16, v77
	v_and_b32_e32 v25, 0xffff0000, v77
	v_mul_f32_e32 v26, 0x3fb8aa3b, v24
	v_mul_f32_e32 v27, 0x3fb8aa3b, v25
	v_exp_f32_e32 v26, v26
	v_exp_f32_e32 v27, v27
	v_lshlrev_b32_e32 v24, 16, v81
	v_and_b32_e32 v25, 0xffff0000, v81
	v_fma_f32 v8, v8, v26, v24
	v_fma_f32 v9, v9, v27, v25
	v_lshlrev_b32_e32 v24, 16, v85
	v_and_b32_e32 v25, 0xffff0000, v85
	v_mul_f32_e32 v24, v8, v24
	v_mul_f32_e32 v25, v9, v25
	v_cvt_pk_bf16_f32 v137, v24, v25
	v_lshlrev_b32_e32 v20, 16, v78
	v_and_b32_e32 v21, 0xffff0000, v78
	v_mul_f32_e32 v22, 0x3fb8aa3b, v20
	v_mul_f32_e32 v23, 0x3fb8aa3b, v21
	v_exp_f32_e32 v22, v22
	v_exp_f32_e32 v23, v23
	v_lshlrev_b32_e32 v20, 16, v82
	v_and_b32_e32 v21, 0xffff0000, v82
	v_fma_f32 v2, v2, v22, v20
	v_fma_f32 v3, v3, v23, v21
	v_lshlrev_b32_e32 v20, 16, v86
	v_and_b32_e32 v21, 0xffff0000, v86
	v_mul_f32_e32 v20, v2, v20
	v_mul_f32_e32 v21, v3, v21
	v_cvt_pk_bf16_f32 v138, v20, v21
	v_lshlrev_b32_e32 v24, 16, v79
	v_and_b32_e32 v25, 0xffff0000, v79
	v_mul_f32_e32 v26, 0x3fb8aa3b, v24
	v_mul_f32_e32 v27, 0x3fb8aa3b, v25
	v_exp_f32_e32 v26, v26
	v_exp_f32_e32 v27, v27
	v_lshlrev_b32_e32 v24, 16, v83
; DI unsigned cvt_pk_bf16(float lo, float hi) { unsigned r; asm volatile("v_cvt_pk_bf16_f32 %0, %1, %2" : "=v"(r) : "v"(lo), "v"(hi)); return r; }
; DI void unpack8(const u32x4 v, float* f) { f[0] = bf_lo(v.x); f[1] = bf_hi(v.x); f[2] = bf_lo(v.y); f[3] = bf_hi(v.y); f[4] = bf_lo(v.z); f[5] = bf_hi(v.z); f[6] = bf_lo(v.w); f[7] = bf_hi(v.w); }
; DI void phase_scan2(const bf16_t* la, const bf16_t* bb, const bf16_t* y, const float* hin, bf16_t* yh) {
;     ...
;     for (int t = 0; t < 32; ++t) {
;       float l[8], bv[8], yv[8]; unpack8(*(const u32x4*)(la + base + (size_t)t * DM), l); unpack8(*(const u32x4*)(bb + base + (size_t)t * DM), bv); unpack8(*(const u32x4*)(y + base + (size_t)t * DM), yv);
;       float o[8];
; #pragma unroll
;       for (int e = 0; e < 8; ++e) { h[e] = __expf(l[e]) * h[e] + bv[e]; o[e] = h[e] * yv[e]; }
;       u32x4 wv; wv.x = cvt_pk_bf16(o[0], o[1]); wv.y = cvt_pk_bf16(o[2], o[3]); wv.z = cvt_pk_bf16(o[4], o[5]); wv.w = cvt_pk_bf16(o[6], o[7]);
;       *(u32x4*)(yh + base + (size_t)t * DM) = wv;
	v_and_b32_e32 v25, 0xffff0000, v83
	v_fma_f32 v4, v4, v26, v24
	v_fma_f32 v5, v5, v27, v25
	v_lshlrev_b32_e32 v24, 16, v87
	v_and_b32_e32 v25, 0xffff0000, v87
	v_mul_f32_e32 v24, v4, v24
	v_mul_f32_e32 v25, v5, v25
	v_cvt_pk_bf16_f32 v139, v24, v25
	s_nop 0
	global_store_dwordx4 v[10:11], v[136:139], off
	v_lshl_add_u64 v[10:11], v[10:11], 0, v[18:19]
	global_load_dwordx4 v[40:43], v[16:17], off
	global_load_dwordx4 v[44:47], v[14:15], off
	global_load_dwordx4 v[48:51], v[12:13], off
	v_lshl_add_u64 v[16:17], v[16:17], 0, v[18:19]
	v_lshl_add_u64 v[14:15], v[14:15], 0, v[18:19]
	v_lshl_add_u64 v[12:13], v[12:13], 0, v[18:19]
	global_load_dwordx4 v[52:55], v[16:17], off
	global_load_dwordx4 v[56:59], v[14:15], off
	global_load_dwordx4 v[60:63], v[12:13], off
	v_lshl_add_u64 v[16:17], v[16:17], 0, v[18:19]
	v_lshl_add_u64 v[14:15], v[14:15], 0, v[18:19]
	v_lshl_add_u64 v[12:13], v[12:13], 0, v[18:19]
	global_load_dwordx4 v[64:67], v[16:17], off
	global_load_dwordx4 v[68:71], v[14:15], off
	global_load_dwordx4 v[72:75], v[12:13], off
	v_lshl_add_u64 v[16:17], v[16:17], 0, v[18:19]
	v_lshl_add_u64 v[14:15], v[14:15], 0, v[18:19]
	v_lshl_add_u64 v[12:13], v[12:13], 0, v[18:19]
	global_load_dwordx4 v[76:79], v[16:17], off
	global_load_dwordx4 v[80:83], v[14:15], off
	global_load_dwordx4 v[84:87], v[12:13], off
	v_lshl_add_u64 v[16:17], v[16:17], 0, v[18:19]
	v_lshl_add_u64 v[14:15], v[14:15], 0, v[18:19]
	v_lshl_add_u64 v[12:13], v[12:13], 0, v[18:19]
	s_waitcnt vmcnt(25)
	v_lshlrev_b32_e32 v20, 16, v88
	v_and_b32_e32 v21, 0xffff0000, v88
	v_mul_f32_e32 v22, 0x3fb8aa3b, v20
	v_mul_f32_e32 v23, 0x3fb8aa3b, v21
	v_exp_f32_e32 v22, v22
	v_exp_f32_e32 v23, v23
	v_lshlrev_b32_e32 v20, 16, v92
	v_and_b32_e32 v21, 0xffff0000, v92
	v_fma_f32 v6, v6, v22, v20
	v_fma_f32 v7, v7, v23, v21
	v_lshlrev_b32_e32 v20, 16, v96
	v_and_b32_e32 v21, 0xffff0000, v96
	v_mul_f32_e32 v20, v6, v20
	v_mul_f32_e32 v21, v7, v21
	v_cvt_pk_bf16_f32 v136, v20, v21
	v_lshlrev_b32_e32 v24, 16, v89
	v_and_b32_e32 v25, 0xffff0000, v89
	v_mul_f32_e32 v26, 0x3fb8aa3b, v24
	v_mul_f32_e32 v27, 0x3fb8aa3b, v25
	v_exp_f32_e32 v26, v26
	v_exp_f32_e32 v27, v27
	v_lshlrev_b32_e32 v24, 16, v93
	v_and_b32_e32 v25, 0xffff0000, v93
	v_fma_f32 v8, v8, v26, v24
	v_fma_f32 v9, v9, v27, v25
	v_lshlrev_b32_e32 v24, 16, v97
	v_and_b32_e32 v25, 0xffff0000, v97
	v_mul_f32_e32 v24, v8, v24
	v_mul_f32_e32 v25, v9, v25
	v_cvt_pk_bf16_f32 v137, v24, v25
	v_lshlrev_b32_e32 v20, 16, v90
	v_and_b32_e32 v21, 0xffff0000, v90
	v_mul_f32_e32 v22, 0x3fb8aa3b, v20
	v_mul_f32_e32 v23, 0x3fb8aa3b, v21
	v_exp_f32_e32 v22, v22
	v_exp_f32_e32 v23, v23
	v_lshlrev_b32_e32 v20, 16, v94
	v_and_b32_e32 v21, 0xffff0000, v94
	v_fma_f32 v2, v2, v22, v20
	v_fma_f32 v3, v3, v23, v21
	v_lshlrev_b32_e32 v20, 16, v98
	v_and_b32_e32 v21, 0xffff0000, v98
	v_mul_f32_e32 v20, v2, v20
	v_mul_f32_e32 v21, v3, v21
	v_cvt_pk_bf16_f32 v138, v20, v21
	v_lshlrev_b32_e32 v24, 16, v91
	v_and_b32_e32 v25, 0xffff0000, v91
	v_mul_f32_e32 v26, 0x3fb8aa3b, v24
	v_mul_f32_e32 v27, 0x3fb8aa3b, v25
	v_exp_f32_e32 v26, v26
	v_exp_f32_e32 v27, v27
	v_lshlrev_b32_e32 v24, 16, v95
	v_and_b32_e32 v25, 0xffff0000, v95
	v_fma_f32 v4, v4, v26, v24
	v_fma_f32 v5, v5, v27, v25
	v_lshlrev_b32_e32 v24, 16, v99
	v_and_b32_e32 v25, 0xffff0000, v99
	v_mul_f32_e32 v24, v4, v24
	v_mul_f32_e32 v25, v5, v25
	v_cvt_pk_bf16_f32 v139, v24, v25
	s_nop 0
	global_store_dwordx4 v[10:11], v[136:139], off
	v_lshl_add_u64 v[10:11], v[10:11], 0, v[18:19]
	s_waitcnt vmcnt(23)
	v_lshlrev_b32_e32 v20, 16, v100
	v_and_b32_e32 v21, 0xffff0000, v100
	v_mul_f32_e32 v22, 0x3fb8aa3b, v20
	v_mul_f32_e32 v23, 0x3fb8aa3b, v21
	v_exp_f32_e32 v22, v22
	v_exp_f32_e32 v23, v23
	v_lshlrev_b32_e32 v20, 16, v104
	v_and_b32_e32 v21, 0xffff0000, v104
	v_fma_f32 v6, v6, v22, v20
	v_fma_f32 v7, v7, v23, v21
	v_lshlrev_b32_e32 v20, 16, v108
	v_and_b32_e32 v21, 0xffff0000, v108
	v_mul_f32_e32 v20, v6, v20
	v_mul_f32_e32 v21, v7, v21
	v_cvt_pk_bf16_f32 v136, v20, v21
	v_lshlrev_b32_e32 v24, 16, v101
	v_and_b32_e32 v25, 0xffff0000, v101
	v_mul_f32_e32 v26, 0x3fb8aa3b, v24
	v_mul_f32_e32 v27, 0x3fb8aa3b, v25
	v_exp_f32_e32 v26, v26
	v_exp_f32_e32 v27, v27
	v_lshlrev_b32_e32 v24, 16, v105
	v_and_b32_e32 v25, 0xffff0000, v105
	v_fma_f32 v8, v8, v26, v24
	v_fma_f32 v9, v9, v27, v25
	v_lshlrev_b32_e32 v24, 16, v109
	v_and_b32_e32 v25, 0xffff0000, v109
	v_mul_f32_e32 v24, v8, v24
	v_mul_f32_e32 v25, v9, v25
	v_cvt_pk_bf16_f32 v137, v24, v25
	v_lshlrev_b32_e32 v20, 16, v102
	v_and_b32_e32 v21, 0xffff0000, v102
	v_mul_f32_e32 v22, 0x3fb8aa3b, v20
	v_mul_f32_e32 v23, 0x3fb8aa3b, v21
	v_exp_f32_e32 v22, v22
	v_exp_f32_e32 v23, v23
	v_lshlrev_b32_e32 v20, 16, v106
	v_and_b32_e32 v21, 0xffff0000, v106
	v_fma_f32 v2, v2, v22, v20
	v_fma_f32 v3, v3, v23, v21
	v_lshlrev_b32_e32 v20, 16, v110
	v_and_b32_e32 v21, 0xffff0000, v110
	v_mul_f32_e32 v20, v2, v20
	v_mul_f32_e32 v21, v3, v21
	v_cvt_pk_bf16_f32 v138, v20, v21
	v_lshlrev_b32_e32 v24, 16, v103
	v_and_b32_e32 v25, 0xffff0000, v103
	v_mul_f32_e32 v26, 0x3fb8aa3b, v24
	v_mul_f32_e32 v27, 0x3fb8aa3b, v25
	v_exp_f32_e32 v26, v26
	v_exp_f32_e32 v27, v27
	v_lshlrev_b32_e32 v24, 16, v107
	v_and_b32_e32 v25, 0xffff0000, v107
	v_fma_f32 v4, v4, v26, v24
	v_fma_f32 v5, v5, v27, v25
	v_lshlrev_b32_e32 v24, 16, v111
	v_and_b32_e32 v25, 0xffff0000, v111
	v_mul_f32_e32 v24, v4, v24
	v_mul_f32_e32 v25, v5, v25
	v_cvt_pk_bf16_f32 v139, v24, v25
	s_nop 0
	global_store_dwordx4 v[10:11], v[136:139], off
	v_lshl_add_u64 v[10:11], v[10:11], 0, v[18:19]
	s_waitcnt vmcnt(21)
; DI unsigned cvt_pk_bf16(float lo, float hi) { unsigned r; asm volatile("v_cvt_pk_bf16_f32 %0, %1, %2" : "=v"(r) : "v"(lo), "v"(hi)); return r; }
; DI void unpack8(const u32x4 v, float* f) { f[0] = bf_lo(v.x); f[1] = bf_hi(v.x); f[2] = bf_lo(v.y); f[3] = bf_hi(v.y); f[4] = bf_lo(v.z); f[5] = bf_hi(v.z); f[6] = bf_lo(v.w); f[7] = bf_hi(v.w); }
; DI void phase_scan2(const bf16_t* la, const bf16_t* bb, const bf16_t* y, const float* hin, bf16_t* yh) {
;     ...
;     for (int t = 0; t < 32; ++t) {
;       float l[8], bv[8], yv[8]; unpack8(*(const u32x4*)(la + base + (size_t)t * DM), l); unpack8(*(const u32x4*)(bb + base + (size_t)t * DM), bv); unpack8(*(const u32x4*)(y + base + (size_t)t * DM), yv);
;       float o[8];
; #pragma unroll
;       for (int e = 0; e < 8; ++e) { h[e] = __expf(l[e]) * h[e] + bv[e]; o[e] = h[e] * yv[e]; }
;       u32x4 wv; wv.x = cvt_pk_bf16(o[0], o[1]); wv.y = cvt_pk_bf16(o[2], o[3]); wv.z = cvt_pk_bf16(o[4], o[5]); wv.w = cvt_pk_bf16(o[6], o[7]);
;       *(u32x4*)(yh + base + (size_t)t * DM) = wv;
	v_lshlrev_b32_e32 v20, 16, v112
	v_and_b32_e32 v21, 0xffff0000, v112
	v_mul_f32_e32 v22, 0x3fb8aa3b, v20
	v_mul_f32_e32 v23, 0x3fb8aa3b, v21
	v_exp_f32_e32 v22, v22
	v_exp_f32_e32 v23, v23
	v_lshlrev_b32_e32 v20, 16, v116
	v_and_b32_e32 v21, 0xffff0000, v116
	v_fma_f32 v6, v6, v22, v20
	v_fma_f32 v7, v7, v23, v21
	v_lshlrev_b32_e32 v20, 16, v120
	v_and_b32_e32 v21, 0xffff0000, v120
	v_mul_f32_e32 v20, v6, v20
	v_mul_f32_e32 v21, v7, v21
	v_cvt_pk_bf16_f32 v136, v20, v21
	v_lshlrev_b32_e32 v24, 16, v113
	v_and_b32_e32 v25, 0xffff0000, v113
	v_mul_f32_e32 v26, 0x3fb8aa3b, v24
	v_mul_f32_e32 v27, 0x3fb8aa3b, v25
	v_exp_f32_e32 v26, v26
	v_exp_f32_e32 v27, v27
	v_lshlrev_b32_e32 v24, 16, v117
	v_and_b32_e32 v25, 0xffff0000, v117
	v_fma_f32 v8, v8, v26, v24
	v_fma_f32 v9, v9, v27, v25
	v_lshlrev_b32_e32 v24, 16, v121
	v_and_b32_e32 v25, 0xffff0000, v121
	v_mul_f32_e32 v24, v8, v24
	v_mul_f32_e32 v25, v9, v25
	v_cvt_pk_bf16_f32 v137, v24, v25
	v_lshlrev_b32_e32 v20, 16, v114
	v_and_b32_e32 v21, 0xffff0000, v114
	v_mul_f32_e32 v22, 0x3fb8aa3b, v20
	v_mul_f32_e32 v23, 0x3fb8aa3b, v21
	v_exp_f32_e32 v22, v22
	v_exp_f32_e32 v23, v23
	v_lshlrev_b32_e32 v20, 16, v118
	v_and_b32_e32 v21, 0xffff0000, v118
	v_fma_f32 v2, v2, v22, v20
	v_fma_f32 v3, v3, v23, v21
	v_lshlrev_b32_e32 v20, 16, v122
	v_and_b32_e32 v21, 0xffff0000, v122
	v_mul_f32_e32 v20, v2, v20
	v_mul_f32_e32 v21, v3, v21
	v_cvt_pk_bf16_f32 v138, v20, v21
	v_lshlrev_b32_e32 v24, 16, v115
	v_and_b32_e32 v25, 0xffff0000, v115
	v_mul_f32_e32 v26, 0x3fb8aa3b, v24
	v_mul_f32_e32 v27, 0x3fb8aa3b, v25
	v_exp_f32_e32 v26, v26
	v_exp_f32_e32 v27, v27
	v_lshlrev_b32_e32 v24, 16, v119
	v_and_b32_e32 v25, 0xffff0000, v119
	v_fma_f32 v4, v4, v26, v24
	v_fma_f32 v5, v5, v27, v25
	v_lshlrev_b32_e32 v24, 16, v123
	v_and_b32_e32 v25, 0xffff0000, v123
	v_mul_f32_e32 v24, v4, v24
	v_mul_f32_e32 v25, v5, v25
	v_cvt_pk_bf16_f32 v139, v24, v25
	s_nop 0
	global_store_dwordx4 v[10:11], v[136:139], off
	v_lshl_add_u64 v[10:11], v[10:11], 0, v[18:19]
	s_waitcnt vmcnt(19)
	v_lshlrev_b32_e32 v20, 16, v124
	v_and_b32_e32 v21, 0xffff0000, v124
	v_mul_f32_e32 v22, 0x3fb8aa3b, v20
	v_mul_f32_e32 v23, 0x3fb8aa3b, v21
	v_exp_f32_e32 v22, v22
	v_exp_f32_e32 v23, v23
	v_lshlrev_b32_e32 v20, 16, v128
	v_and_b32_e32 v21, 0xffff0000, v128
	v_fma_f32 v6, v6, v22, v20
	v_fma_f32 v7, v7, v23, v21
	v_lshlrev_b32_e32 v20, 16, v132
	v_and_b32_e32 v21, 0xffff0000, v132
	v_mul_f32_e32 v20, v6, v20
	v_mul_f32_e32 v21, v7, v21
	v_cvt_pk_bf16_f32 v136, v20, v21
	v_lshlrev_b32_e32 v24, 16, v125
	v_and_b32_e32 v25, 0xffff0000, v125
	v_mul_f32_e32 v26, 0x3fb8aa3b, v24
	v_mul_f32_e32 v27, 0x3fb8aa3b, v25
	v_exp_f32_e32 v26, v26
	v_exp_f32_e32 v27, v27
	v_lshlrev_b32_e32 v24, 16, v129
	v_and_b32_e32 v25, 0xffff0000, v129
	v_fma_f32 v8, v8, v26, v24
	v_fma_f32 v9, v9, v27, v25
	v_lshlrev_b32_e32 v24, 16, v133
	v_and_b32_e32 v25, 0xffff0000, v133
	v_mul_f32_e32 v24, v8, v24
	v_mul_f32_e32 v25, v9, v25
	v_cvt_pk_bf16_f32 v137, v24, v25
	v_lshlrev_b32_e32 v20, 16, v126
	v_and_b32_e32 v21, 0xffff0000, v126
	v_mul_f32_e32 v22, 0x3fb8aa3b, v20
	v_mul_f32_e32 v23, 0x3fb8aa3b, v21
	v_exp_f32_e32 v22, v22
	v_exp_f32_e32 v23, v23
	v_lshlrev_b32_e32 v20, 16, v130
	v_and_b32_e32 v21, 0xffff0000, v130
	v_fma_f32 v2, v2, v22, v20
	v_fma_f32 v3, v3, v23, v21
	v_lshlrev_b32_e32 v20, 16, v134
	v_and_b32_e32 v21, 0xffff0000, v134
	v_mul_f32_e32 v20, v2, v20
	v_mul_f32_e32 v21, v3, v21
	v_cvt_pk_bf16_f32 v138, v20, v21
	v_lshlrev_b32_e32 v24, 16, v127
	v_and_b32_e32 v25, 0xffff0000, v127
	v_mul_f32_e32 v26, 0x3fb8aa3b, v24
	v_mul_f32_e32 v27, 0x3fb8aa3b, v25
	v_exp_f32_e32 v26, v26
	v_exp_f32_e32 v27, v27
	v_lshlrev_b32_e32 v24, 16, v131
	v_and_b32_e32 v25, 0xffff0000, v131
	v_fma_f32 v4, v4, v26, v24
	v_fma_f32 v5, v5, v27, v25
	v_lshlrev_b32_e32 v24, 16, v135
	v_and_b32_e32 v25, 0xffff0000, v135
	v_mul_f32_e32 v24, v4, v24
	v_mul_f32_e32 v25, v5, v25
	v_cvt_pk_bf16_f32 v139, v24, v25
	s_nop 0
	global_store_dwordx4 v[10:11], v[136:139], off
	v_lshl_add_u64 v[10:11], v[10:11], 0, v[18:19]
	global_load_dwordx4 v[88:91], v[16:17], off
	global_load_dwordx4 v[92:95], v[14:15], off
	global_load_dwordx4 v[96:99], v[12:13], off
	v_lshl_add_u64 v[16:17], v[16:17], 0, v[18:19]
	v_lshl_add_u64 v[14:15], v[14:15], 0, v[18:19]
	v_lshl_add_u64 v[12:13], v[12:13], 0, v[18:19]
	global_load_dwordx4 v[100:103], v[16:17], off
	global_load_dwordx4 v[104:107], v[14:15], off
	global_load_dwordx4 v[108:111], v[12:13], off
	v_lshl_add_u64 v[16:17], v[16:17], 0, v[18:19]
	v_lshl_add_u64 v[14:15], v[14:15], 0, v[18:19]
	v_lshl_add_u64 v[12:13], v[12:13], 0, v[18:19]
	global_load_dwordx4 v[112:115], v[16:17], off
	global_load_dwordx4 v[116:119], v[14:15], off
	global_load_dwordx4 v[120:123], v[12:13], off
	v_lshl_add_u64 v[16:17], v[16:17], 0, v[18:19]
	v_lshl_add_u64 v[14:15], v[14:15], 0, v[18:19]
	v_lshl_add_u64 v[12:13], v[12:13], 0, v[18:19]
	global_load_dwordx4 v[124:127], v[16:17], off
	global_load_dwordx4 v[128:131], v[14:15], off
	global_load_dwordx4 v[132:135], v[12:13], off
	v_lshl_add_u64 v[16:17], v[16:17], 0, v[18:19]
	v_lshl_add_u64 v[14:15], v[14:15], 0, v[18:19]
	v_lshl_add_u64 v[12:13], v[12:13], 0, v[18:19]
	s_waitcnt vmcnt(25)
; DI unsigned cvt_pk_bf16(float lo, float hi) { unsigned r; asm volatile("v_cvt_pk_bf16_f32 %0, %1, %2" : "=v"(r) : "v"(lo), "v"(hi)); return r; }
; DI void unpack8(const u32x4 v, float* f) { f[0] = bf_lo(v.x); f[1] = bf_hi(v.x); f[2] = bf_lo(v.y); f[3] = bf_hi(v.y); f[4] = bf_lo(v.z); f[5] = bf_hi(v.z); f[6] = bf_lo(v.w); f[7] = bf_hi(v.w); }
; DI void phase_scan2(const bf16_t* la, const bf16_t* bb, const bf16_t* y, const float* hin, bf16_t* yh) {
;     ...
;     for (int t = 0; t < 32; ++t) {
;       float l[8], bv[8], yv[8]; unpack8(*(const u32x4*)(la + base + (size_t)t * DM), l); unpack8(*(const u32x4*)(bb + base + (size_t)t * DM), bv); unpack8(*(const u32x4*)(y + base + (size_t)t * DM), yv);
;       float o[8];
; #pragma unroll
;       for (int e = 0; e < 8; ++e) { h[e] = __expf(l[e]) * h[e] + bv[e]; o[e] = h[e] * yv[e]; }
;       u32x4 wv; wv.x = cvt_pk_bf16(o[0], o[1]); wv.y = cvt_pk_bf16(o[2], o[3]); wv.z = cvt_pk_bf16(o[4], o[5]); wv.w = cvt_pk_bf16(o[6], o[7]);
;       *(u32x4*)(yh + base + (size_t)t * DM) = wv;
	v_lshlrev_b32_e32 v20, 16, v40
	v_and_b32_e32 v21, 0xffff0000, v40
	v_mul_f32_e32 v22, 0x3fb8aa3b, v20
	v_mul_f32_e32 v23, 0x3fb8aa3b, v21
	v_exp_f32_e32 v22, v22
	v_exp_f32_e32 v23, v23
	v_lshlrev_b32_e32 v20, 16, v44
	v_and_b32_e32 v21, 0xffff0000, v44
	v_fma_f32 v6, v6, v22, v20
	v_fma_f32 v7, v7, v23, v21
	v_lshlrev_b32_e32 v20, 16, v48
	v_and_b32_e32 v21, 0xffff0000, v48
	v_mul_f32_e32 v20, v6, v20
	v_mul_f32_e32 v21, v7, v21
	v_cvt_pk_bf16_f32 v136, v20, v21
	v_lshlrev_b32_e32 v24, 16, v41
	v_and_b32_e32 v25, 0xffff0000, v41
	v_mul_f32_e32 v26, 0x3fb8aa3b, v24
	v_mul_f32_e32 v27, 0x3fb8aa3b, v25
	v_exp_f32_e32 v26, v26
	v_exp_f32_e32 v27, v27
	v_lshlrev_b32_e32 v24, 16, v45
	v_and_b32_e32 v25, 0xffff0000, v45
	v_fma_f32 v8, v8, v26, v24
	v_fma_f32 v9, v9, v27, v25
	v_lshlrev_b32_e32 v24, 16, v49
	v_and_b32_e32 v25, 0xffff0000, v49
	v_mul_f32_e32 v24, v8, v24
	v_mul_f32_e32 v25, v9, v25
	v_cvt_pk_bf16_f32 v137, v24, v25
	v_lshlrev_b32_e32 v20, 16, v42
	v_and_b32_e32 v21, 0xffff0000, v42
	v_mul_f32_e32 v22, 0x3fb8aa3b, v20
	v_mul_f32_e32 v23, 0x3fb8aa3b, v21
	v_exp_f32_e32 v22, v22
	v_exp_f32_e32 v23, v23
	v_lshlrev_b32_e32 v20, 16, v46
	v_and_b32_e32 v21, 0xffff0000, v46
	v_fma_f32 v2, v2, v22, v20
	v_fma_f32 v3, v3, v23, v21
	v_lshlrev_b32_e32 v20, 16, v50
	v_and_b32_e32 v21, 0xffff0000, v50
	v_mul_f32_e32 v20, v2, v20
	v_mul_f32_e32 v21, v3, v21
	v_cvt_pk_bf16_f32 v138, v20, v21
	v_lshlrev_b32_e32 v24, 16, v43
	v_and_b32_e32 v25, 0xffff0000, v43
	v_mul_f32_e32 v26, 0x3fb8aa3b, v24
	v_mul_f32_e32 v27, 0x3fb8aa3b, v25
	v_exp_f32_e32 v26, v26
	v_exp_f32_e32 v27, v27
	v_lshlrev_b32_e32 v24, 16, v47
	v_and_b32_e32 v25, 0xffff0000, v47
	v_fma_f32 v4, v4, v26, v24
	v_fma_f32 v5, v5, v27, v25
	v_lshlrev_b32_e32 v24, 16, v51
	v_and_b32_e32 v25, 0xffff0000, v51
	v_mul_f32_e32 v24, v4, v24
	v_mul_f32_e32 v25, v5, v25
	v_cvt_pk_bf16_f32 v139, v24, v25
	s_nop 0
	global_store_dwordx4 v[10:11], v[136:139], off
	v_lshl_add_u64 v[10:11], v[10:11], 0, v[18:19]
	s_waitcnt vmcnt(23)
	v_lshlrev_b32_e32 v20, 16, v52
	v_and_b32_e32 v21, 0xffff0000, v52
	v_mul_f32_e32 v22, 0x3fb8aa3b, v20
	v_mul_f32_e32 v23, 0x3fb8aa3b, v21
	v_exp_f32_e32 v22, v22
	v_exp_f32_e32 v23, v23
	v_lshlrev_b32_e32 v20, 16, v56
	v_and_b32_e32 v21, 0xffff0000, v56
	v_fma_f32 v6, v6, v22, v20
	v_fma_f32 v7, v7, v23, v21
	v_lshlrev_b32_e32 v20, 16, v60
	v_and_b32_e32 v21, 0xffff0000, v60
	v_mul_f32_e32 v20, v6, v20
	v_mul_f32_e32 v21, v7, v21
	v_cvt_pk_bf16_f32 v136, v20, v21
	v_lshlrev_b32_e32 v24, 16, v53
	v_and_b32_e32 v25, 0xffff0000, v53
	v_mul_f32_e32 v26, 0x3fb8aa3b, v24
	v_mul_f32_e32 v27, 0x3fb8aa3b, v25
	v_exp_f32_e32 v26, v26
	v_exp_f32_e32 v27, v27
	v_lshlrev_b32_e32 v24, 16, v57
	v_and_b32_e32 v25, 0xffff0000, v57
	v_fma_f32 v8, v8, v26, v24
	v_fma_f32 v9, v9, v27, v25
	v_lshlrev_b32_e32 v24, 16, v61
	v_and_b32_e32 v25, 0xffff0000, v61
	v_mul_f32_e32 v24, v8, v24
	v_mul_f32_e32 v25, v9, v25
	v_cvt_pk_bf16_f32 v137, v24, v25
	v_lshlrev_b32_e32 v20, 16, v54
	v_and_b32_e32 v21, 0xffff0000, v54
	v_mul_f32_e32 v22, 0x3fb8aa3b, v20
	v_mul_f32_e32 v23, 0x3fb8aa3b, v21
	v_exp_f32_e32 v22, v22
	v_exp_f32_e32 v23, v23
	v_lshlrev_b32_e32 v20, 16, v58
	v_and_b32_e32 v21, 0xffff0000, v58
	v_fma_f32 v2, v2, v22, v20
	v_fma_f32 v3, v3, v23, v21
	v_lshlrev_b32_e32 v20, 16, v62
	v_and_b32_e32 v21, 0xffff0000, v62
	v_mul_f32_e32 v20, v2, v20
	v_mul_f32_e32 v21, v3, v21
	v_cvt_pk_bf16_f32 v138, v20, v21
	v_lshlrev_b32_e32 v24, 16, v55
	v_and_b32_e32 v25, 0xffff0000, v55
	v_mul_f32_e32 v26, 0x3fb8aa3b, v24
	v_mul_f32_e32 v27, 0x3fb8aa3b, v25
	v_exp_f32_e32 v26, v26
	v_exp_f32_e32 v27, v27
	v_lshlrev_b32_e32 v24, 16, v59
	v_and_b32_e32 v25, 0xffff0000, v59
	v_fma_f32 v4, v4, v26, v24
	v_fma_f32 v5, v5, v27, v25
	v_lshlrev_b32_e32 v24, 16, v63
	v_and_b32_e32 v25, 0xffff0000, v63
	v_mul_f32_e32 v24, v4, v24
	v_mul_f32_e32 v25, v5, v25
	v_cvt_pk_bf16_f32 v139, v24, v25
	s_nop 0
	global_store_dwordx4 v[10:11], v[136:139], off
	v_lshl_add_u64 v[10:11], v[10:11], 0, v[18:19]
	s_waitcnt vmcnt(21)
	v_lshlrev_b32_e32 v20, 16, v64
	v_and_b32_e32 v21, 0xffff0000, v64
	v_mul_f32_e32 v22, 0x3fb8aa3b, v20
	v_mul_f32_e32 v23, 0x3fb8aa3b, v21
	v_exp_f32_e32 v22, v22
	v_exp_f32_e32 v23, v23
	v_lshlrev_b32_e32 v20, 16, v68
	v_and_b32_e32 v21, 0xffff0000, v68
	v_fma_f32 v6, v6, v22, v20
	v_fma_f32 v7, v7, v23, v21
	v_lshlrev_b32_e32 v20, 16, v72
	v_and_b32_e32 v21, 0xffff0000, v72
	v_mul_f32_e32 v20, v6, v20
	v_mul_f32_e32 v21, v7, v21
	v_cvt_pk_bf16_f32 v136, v20, v21
	v_lshlrev_b32_e32 v24, 16, v65
	v_and_b32_e32 v25, 0xffff0000, v65
	v_mul_f32_e32 v26, 0x3fb8aa3b, v24
	v_mul_f32_e32 v27, 0x3fb8aa3b, v25
	v_exp_f32_e32 v26, v26
	v_exp_f32_e32 v27, v27
	v_lshlrev_b32_e32 v24, 16, v69
	v_and_b32_e32 v25, 0xffff0000, v69
	v_fma_f32 v8, v8, v26, v24
	v_fma_f32 v9, v9, v27, v25
	v_lshlrev_b32_e32 v24, 16, v73
	v_and_b32_e32 v25, 0xffff0000, v73
	v_mul_f32_e32 v24, v8, v24
	v_mul_f32_e32 v25, v9, v25
	v_cvt_pk_bf16_f32 v137, v24, v25
	v_lshlrev_b32_e32 v20, 16, v66
	v_and_b32_e32 v21, 0xffff0000, v66
	v_mul_f32_e32 v22, 0x3fb8aa3b, v20
	v_mul_f32_e32 v23, 0x3fb8aa3b, v21
	v_exp_f32_e32 v22, v22
	v_exp_f32_e32 v23, v23
	v_lshlrev_b32_e32 v20, 16, v70
	v_and_b32_e32 v21, 0xffff0000, v70
	v_fma_f32 v2, v2, v22, v20
	v_fma_f32 v3, v3, v23, v21
	v_lshlrev_b32_e32 v20, 16, v74
	v_and_b32_e32 v21, 0xffff0000, v74
	v_mul_f32_e32 v20, v2, v20
	v_mul_f32_e32 v21, v3, v21
	v_cvt_pk_bf16_f32 v138, v20, v21
	v_lshlrev_b32_e32 v24, 16, v67
	v_and_b32_e32 v25, 0xffff0000, v67
	v_mul_f32_e32 v26, 0x3fb8aa3b, v24
	v_mul_f32_e32 v27, 0x3fb8aa3b, v25
	v_exp_f32_e32 v26, v26
	v_exp_f32_e32 v27, v27
	v_lshlrev_b32_e32 v24, 16, v71
	v_and_b32_e32 v25, 0xffff0000, v71
	v_fma_f32 v4, v4, v26, v24
	v_fma_f32 v5, v5, v27, v25
	v_lshlrev_b32_e32 v24, 16, v75
	v_and_b32_e32 v25, 0xffff0000, v75
	v_mul_f32_e32 v24, v4, v24
	v_mul_f32_e32 v25, v5, v25
	v_cvt_pk_bf16_f32 v139, v24, v25
	s_nop 0
	global_store_dwordx4 v[10:11], v[136:139], off
	v_lshl_add_u64 v[10:11], v[10:11], 0, v[18:19]
	s_waitcnt vmcnt(19)
; DI unsigned cvt_pk_bf16(float lo, float hi) { unsigned r; asm volatile("v_cvt_pk_bf16_f32 %0, %1, %2" : "=v"(r) : "v"(lo), "v"(hi)); return r; }
; DI void unpack8(const u32x4 v, float* f) { f[0] = bf_lo(v.x); f[1] = bf_hi(v.x); f[2] = bf_lo(v.y); f[3] = bf_hi(v.y); f[4] = bf_lo(v.z); f[5] = bf_hi(v.z); f[6] = bf_lo(v.w); f[7] = bf_hi(v.w); }
; DI void phase_scan2(const bf16_t* la, const bf16_t* bb, const bf16_t* y, const float* hin, bf16_t* yh) {
;     ...
;     for (int t = 0; t < 32; ++t) {
;       float l[8], bv[8], yv[8]; unpack8(*(const u32x4*)(la + base + (size_t)t * DM), l); unpack8(*(const u32x4*)(bb + base + (size_t)t * DM), bv); unpack8(*(const u32x4*)(y + base + (size_t)t * DM), yv);
;       float o[8];
; #pragma unroll
;       for (int e = 0; e < 8; ++e) { h[e] = __expf(l[e]) * h[e] + bv[e]; o[e] = h[e] * yv[e]; }
;       u32x4 wv; wv.x = cvt_pk_bf16(o[0], o[1]); wv.y = cvt_pk_bf16(o[2], o[3]); wv.z = cvt_pk_bf16(o[4], o[5]); wv.w = cvt_pk_bf16(o[6], o[7]);
;       *(u32x4*)(yh + base + (size_t)t * DM) = wv;
	v_lshlrev_b32_e32 v20, 16, v76
	v_and_b32_e32 v21, 0xffff0000, v76
	v_mul_f32_e32 v22, 0x3fb8aa3b, v20
	v_mul_f32_e32 v23, 0x3fb8aa3b, v21
	v_exp_f32_e32 v22, v22
	v_exp_f32_e32 v23, v23
	v_lshlrev_b32_e32 v20, 16, v80
	v_and_b32_e32 v21, 0xffff0000, v80
	v_fma_f32 v6, v6, v22, v20
	v_fma_f32 v7, v7, v23, v21
	v_lshlrev_b32_e32 v20, 16, v84
	v_and_b32_e32 v21, 0xffff0000, v84
	v_mul_f32_e32 v20, v6, v20
	v_mul_f32_e32 v21, v7, v21
	v_cvt_pk_bf16_f32 v136, v20, v21
	v_lshlrev_b32_e32 v24, 16, v77
	v_and_b32_e32 v25, 0xffff0000, v77
	v_mul_f32_e32 v26, 0x3fb8aa3b, v24
	v_mul_f32_e32 v27, 0x3fb8aa3b, v25
	v_exp_f32_e32 v26, v26
	v_exp_f32_e32 v27, v27
	v_lshlrev_b32_e32 v24, 16, v81
	v_and_b32_e32 v25, 0xffff0000, v81
	v_fma_f32 v8, v8, v26, v24
	v_fma_f32 v9, v9, v27, v25
	v_lshlrev_b32_e32 v24, 16, v85
	v_and_b32_e32 v25, 0xffff0000, v85
	v_mul_f32_e32 v24, v8, v24
	v_mul_f32_e32 v25, v9, v25
	v_cvt_pk_bf16_f32 v137, v24, v25
	v_lshlrev_b32_e32 v20, 16, v78
	v_and_b32_e32 v21, 0xffff0000, v78
	v_mul_f32_e32 v22, 0x3fb8aa3b, v20
	v_mul_f32_e32 v23, 0x3fb8aa3b, v21
	v_exp_f32_e32 v22, v22
	v_exp_f32_e32 v23, v23
	v_lshlrev_b32_e32 v20, 16, v82
	v_and_b32_e32 v21, 0xffff0000, v82
	v_fma_f32 v2, v2, v22, v20
	v_fma_f32 v3, v3, v23, v21
	v_lshlrev_b32_e32 v20, 16, v86
	v_and_b32_e32 v21, 0xffff0000, v86
	v_mul_f32_e32 v20, v2, v20
	v_mul_f32_e32 v21, v3, v21
	v_cvt_pk_bf16_f32 v138, v20, v21
	v_lshlrev_b32_e32 v24, 16, v79
	v_and_b32_e32 v25, 0xffff0000, v79
	v_mul_f32_e32 v26, 0x3fb8aa3b, v24
	v_mul_f32_e32 v27, 0x3fb8aa3b, v25
	v_exp_f32_e32 v26, v26
	v_exp_f32_e32 v27, v27
	v_lshlrev_b32_e32 v24, 16, v83
	v_and_b32_e32 v25, 0xffff0000, v83
	v_fma_f32 v4, v4, v26, v24
	v_fma_f32 v5, v5, v27, v25
	v_lshlrev_b32_e32 v24, 16, v87
	v_and_b32_e32 v25, 0xffff0000, v87
	v_mul_f32_e32 v24, v4, v24
	v_mul_f32_e32 v25, v5, v25
	v_cvt_pk_bf16_f32 v139, v24, v25
	s_nop 0
	global_store_dwordx4 v[10:11], v[136:139], off
	v_lshl_add_u64 v[10:11], v[10:11], 0, v[18:19]
	global_load_dwordx4 v[40:43], v[16:17], off
	global_load_dwordx4 v[44:47], v[14:15], off
	global_load_dwordx4 v[48:51], v[12:13], off
	v_lshl_add_u64 v[16:17], v[16:17], 0, v[18:19]
	v_lshl_add_u64 v[14:15], v[14:15], 0, v[18:19]
	v_lshl_add_u64 v[12:13], v[12:13], 0, v[18:19]
	global_load_dwordx4 v[52:55], v[16:17], off
	global_load_dwordx4 v[56:59], v[14:15], off
	global_load_dwordx4 v[60:63], v[12:13], off
	v_lshl_add_u64 v[16:17], v[16:17], 0, v[18:19]
	v_lshl_add_u64 v[14:15], v[14:15], 0, v[18:19]
	v_lshl_add_u64 v[12:13], v[12:13], 0, v[18:19]
	global_load_dwordx4 v[64:67], v[16:17], off
	global_load_dwordx4 v[68:71], v[14:15], off
	global_load_dwordx4 v[72:75], v[12:13], off
	v_lshl_add_u64 v[16:17], v[16:17], 0, v[18:19]
	v_lshl_add_u64 v[14:15], v[14:15], 0, v[18:19]
	v_lshl_add_u64 v[12:13], v[12:13], 0, v[18:19]
	global_load_dwordx4 v[76:79], v[16:17], off
	global_load_dwordx4 v[80:83], v[14:15], off
	global_load_dwordx4 v[84:87], v[12:13], off
	v_lshl_add_u64 v[16:17], v[16:17], 0, v[18:19]
	v_lshl_add_u64 v[14:15], v[14:15], 0, v[18:19]
	v_lshl_add_u64 v[12:13], v[12:13], 0, v[18:19]
	s_waitcnt vmcnt(25)
	v_lshlrev_b32_e32 v20, 16, v88
	v_and_b32_e32 v21, 0xffff0000, v88
	v_mul_f32_e32 v22, 0x3fb8aa3b, v20
	v_mul_f32_e32 v23, 0x3fb8aa3b, v21
	v_exp_f32_e32 v22, v22
	v_exp_f32_e32 v23, v23
	v_lshlrev_b32_e32 v20, 16, v92
	v_and_b32_e32 v21, 0xffff0000, v92
	v_fma_f32 v6, v6, v22, v20
	v_fma_f32 v7, v7, v23, v21
	v_lshlrev_b32_e32 v20, 16, v96
	v_and_b32_e32 v21, 0xffff0000, v96
	v_mul_f32_e32 v20, v6, v20
	v_mul_f32_e32 v21, v7, v21
	v_cvt_pk_bf16_f32 v136, v20, v21
	v_lshlrev_b32_e32 v24, 16, v89
	v_and_b32_e32 v25, 0xffff0000, v89
	v_mul_f32_e32 v26, 0x3fb8aa3b, v24
	v_mul_f32_e32 v27, 0x3fb8aa3b, v25
	v_exp_f32_e32 v26, v26
	v_exp_f32_e32 v27, v27
	v_lshlrev_b32_e32 v24, 16, v93
	v_and_b32_e32 v25, 0xffff0000, v93
	v_fma_f32 v8, v8, v26, v24
	v_fma_f32 v9, v9, v27, v25
	v_lshlrev_b32_e32 v24, 16, v97
	v_and_b32_e32 v25, 0xffff0000, v97
	v_mul_f32_e32 v24, v8, v24
	v_mul_f32_e32 v25, v9, v25
	v_cvt_pk_bf16_f32 v137, v24, v25
	v_lshlrev_b32_e32 v20, 16, v90
	v_and_b32_e32 v21, 0xffff0000, v90
	v_mul_f32_e32 v22, 0x3fb8aa3b, v20
	v_mul_f32_e32 v23, 0x3fb8aa3b, v21
	v_exp_f32_e32 v22, v22
	v_exp_f32_e32 v23, v23
	v_lshlrev_b32_e32 v20, 16, v94
	v_and_b32_e32 v21, 0xffff0000, v94
	v_fma_f32 v2, v2, v22, v20
	v_fma_f32 v3, v3, v23, v21
	v_lshlrev_b32_e32 v20, 16, v98
	v_and_b32_e32 v21, 0xffff0000, v98
	v_mul_f32_e32 v20, v2, v20
	v_mul_f32_e32 v21, v3, v21
	v_cvt_pk_bf16_f32 v138, v20, v21
	v_lshlrev_b32_e32 v24, 16, v91
	v_and_b32_e32 v25, 0xffff0000, v91
	v_mul_f32_e32 v26, 0x3fb8aa3b, v24
	v_mul_f32_e32 v27, 0x3fb8aa3b, v25
	v_exp_f32_e32 v26, v26
	v_exp_f32_e32 v27, v27
	v_lshlrev_b32_e32 v24, 16, v95
	v_and_b32_e32 v25, 0xffff0000, v95
	v_fma_f32 v4, v4, v26, v24
	v_fma_f32 v5, v5, v27, v25
	v_lshlrev_b32_e32 v24, 16, v99
	v_and_b32_e32 v25, 0xffff0000, v99
	v_mul_f32_e32 v24, v4, v24
	v_mul_f32_e32 v25, v5, v25
	v_cvt_pk_bf16_f32 v139, v24, v25
	s_nop 0
	global_store_dwordx4 v[10:11], v[136:139], off
	v_lshl_add_u64 v[10:11], v[10:11], 0, v[18:19]
	s_waitcnt vmcnt(23)
; DI unsigned cvt_pk_bf16(float lo, float hi) { unsigned r; asm volatile("v_cvt_pk_bf16_f32 %0, %1, %2" : "=v"(r) : "v"(lo), "v"(hi)); return r; }
; DI void unpack8(const u32x4 v, float* f) { f[0] = bf_lo(v.x); f[1] = bf_hi(v.x); f[2] = bf_lo(v.y); f[3] = bf_hi(v.y); f[4] = bf_lo(v.z); f[5] = bf_hi(v.z); f[6] = bf_lo(v.w); f[7] = bf_hi(v.w); }
; DI void phase_scan2(const bf16_t* la, const bf16_t* bb, const bf16_t* y, const float* hin, bf16_t* yh) {
;     ...
;     for (int t = 0; t < 32; ++t) {
;       float l[8], bv[8], yv[8]; unpack8(*(const u32x4*)(la + base + (size_t)t * DM), l); unpack8(*(const u32x4*)(bb + base + (size_t)t * DM), bv); unpack8(*(const u32x4*)(y + base + (size_t)t * DM), yv);
;       float o[8];
; #pragma unroll
;       for (int e = 0; e < 8; ++e) { h[e] = __expf(l[e]) * h[e] + bv[e]; o[e] = h[e] * yv[e]; }
;       u32x4 wv; wv.x = cvt_pk_bf16(o[0], o[1]); wv.y = cvt_pk_bf16(o[2], o[3]); wv.z = cvt_pk_bf16(o[4], o[5]); wv.w = cvt_pk_bf16(o[6], o[7]);
;       *(u32x4*)(yh + base + (size_t)t * DM) = wv;
	v_lshlrev_b32_e32 v20, 16, v100
	v_and_b32_e32 v21, 0xffff0000, v100
	v_mul_f32_e32 v22, 0x3fb8aa3b, v20
	v_mul_f32_e32 v23, 0x3fb8aa3b, v21
	v_exp_f32_e32 v22, v22
	v_exp_f32_e32 v23, v23
	v_lshlrev_b32_e32 v20, 16, v104
	v_and_b32_e32 v21, 0xffff0000, v104
	v_fma_f32 v6, v6, v22, v20
	v_fma_f32 v7, v7, v23, v21
	v_lshlrev_b32_e32 v20, 16, v108
	v_and_b32_e32 v21, 0xffff0000, v108
	v_mul_f32_e32 v20, v6, v20
	v_mul_f32_e32 v21, v7, v21
	v_cvt_pk_bf16_f32 v136, v20, v21
	v_lshlrev_b32_e32 v24, 16, v101
	v_and_b32_e32 v25, 0xffff0000, v101
	v_mul_f32_e32 v26, 0x3fb8aa3b, v24
	v_mul_f32_e32 v27, 0x3fb8aa3b, v25
	v_exp_f32_e32 v26, v26
	v_exp_f32_e32 v27, v27
	v_lshlrev_b32_e32 v24, 16, v105
	v_and_b32_e32 v25, 0xffff0000, v105
	v_fma_f32 v8, v8, v26, v24
	v_fma_f32 v9, v9, v27, v25
	v_lshlrev_b32_e32 v24, 16, v109
	v_and_b32_e32 v25, 0xffff0000, v109
	v_mul_f32_e32 v24, v8, v24
	v_mul_f32_e32 v25, v9, v25
	v_cvt_pk_bf16_f32 v137, v24, v25
	v_lshlrev_b32_e32 v20, 16, v102
	v_and_b32_e32 v21, 0xffff0000, v102
	v_mul_f32_e32 v22, 0x3fb8aa3b, v20
	v_mul_f32_e32 v23, 0x3fb8aa3b, v21
	v_exp_f32_e32 v22, v22
	v_exp_f32_e32 v23, v23
	v_lshlrev_b32_e32 v20, 16, v106
	v_and_b32_e32 v21, 0xffff0000, v106
	v_fma_f32 v2, v2, v22, v20
	v_fma_f32 v3, v3, v23, v21
	v_lshlrev_b32_e32 v20, 16, v110
	v_and_b32_e32 v21, 0xffff0000, v110
	v_mul_f32_e32 v20, v2, v20
	v_mul_f32_e32 v21, v3, v21
	v_cvt_pk_bf16_f32 v138, v20, v21
	v_lshlrev_b32_e32 v24, 16, v103
	v_and_b32_e32 v25, 0xffff0000, v103
	v_mul_f32_e32 v26, 0x3fb8aa3b, v24
	v_mul_f32_e32 v27, 0x3fb8aa3b, v25
	v_exp_f32_e32 v26, v26
	v_exp_f32_e32 v27, v27
	v_lshlrev_b32_e32 v24, 16, v107
	v_and_b32_e32 v25, 0xffff0000, v107
	v_fma_f32 v4, v4, v26, v24
	v_fma_f32 v5, v5, v27, v25
	v_lshlrev_b32_e32 v24, 16, v111
	v_and_b32_e32 v25, 0xffff0000, v111
	v_mul_f32_e32 v24, v4, v24
	v_mul_f32_e32 v25, v5, v25
	v_cvt_pk_bf16_f32 v139, v24, v25
	s_nop 0
	global_store_dwordx4 v[10:11], v[136:139], off
	v_lshl_add_u64 v[10:11], v[10:11], 0, v[18:19]
	s_waitcnt vmcnt(21)
	v_lshlrev_b32_e32 v20, 16, v112
	v_and_b32_e32 v21, 0xffff0000, v112
	v_mul_f32_e32 v22, 0x3fb8aa3b, v20
	v_mul_f32_e32 v23, 0x3fb8aa3b, v21
	v_exp_f32_e32 v22, v22
	v_exp_f32_e32 v23, v23
	v_lshlrev_b32_e32 v20, 16, v116
	v_and_b32_e32 v21, 0xffff0000, v116
	v_fma_f32 v6, v6, v22, v20
	v_fma_f32 v7, v7, v23, v21
	v_lshlrev_b32_e32 v20, 16, v120
	v_and_b32_e32 v21, 0xffff0000, v120
	v_mul_f32_e32 v20, v6, v20
	v_mul_f32_e32 v21, v7, v21
	v_cvt_pk_bf16_f32 v136, v20, v21
	v_lshlrev_b32_e32 v24, 16, v113
	v_and_b32_e32 v25, 0xffff0000, v113
	v_mul_f32_e32 v26, 0x3fb8aa3b, v24
	v_mul_f32_e32 v27, 0x3fb8aa3b, v25
	v_exp_f32_e32 v26, v26
	v_exp_f32_e32 v27, v27
	v_lshlrev_b32_e32 v24, 16, v117
	v_and_b32_e32 v25, 0xffff0000, v117
	v_fma_f32 v8, v8, v26, v24
	v_fma_f32 v9, v9, v27, v25
	v_lshlrev_b32_e32 v24, 16, v121
	v_and_b32_e32 v25, 0xffff0000, v121
	v_mul_f32_e32 v24, v8, v24
	v_mul_f32_e32 v25, v9, v25
	v_cvt_pk_bf16_f32 v137, v24, v25
	v_lshlrev_b32_e32 v20, 16, v114
	v_and_b32_e32 v21, 0xffff0000, v114
	v_mul_f32_e32 v22, 0x3fb8aa3b, v20
	v_mul_f32_e32 v23, 0x3fb8aa3b, v21
	v_exp_f32_e32 v22, v22
	v_exp_f32_e32 v23, v23
	v_lshlrev_b32_e32 v20, 16, v118
	v_and_b32_e32 v21, 0xffff0000, v118
	v_fma_f32 v2, v2, v22, v20
	v_fma_f32 v3, v3, v23, v21
	v_lshlrev_b32_e32 v20, 16, v122
	v_and_b32_e32 v21, 0xffff0000, v122
	v_mul_f32_e32 v20, v2, v20
	v_mul_f32_e32 v21, v3, v21
	v_cvt_pk_bf16_f32 v138, v20, v21
	v_lshlrev_b32_e32 v24, 16, v115
	v_and_b32_e32 v25, 0xffff0000, v115
	v_mul_f32_e32 v26, 0x3fb8aa3b, v24
	v_mul_f32_e32 v27, 0x3fb8aa3b, v25
	v_exp_f32_e32 v26, v26
	v_exp_f32_e32 v27, v27
	v_lshlrev_b32_e32 v24, 16, v119
	v_and_b32_e32 v25, 0xffff0000, v119
	v_fma_f32 v4, v4, v26, v24
	v_fma_f32 v5, v5, v27, v25
	v_lshlrev_b32_e32 v24, 16, v123
	v_and_b32_e32 v25, 0xffff0000, v123
	v_mul_f32_e32 v24, v4, v24
	v_mul_f32_e32 v25, v5, v25
	v_cvt_pk_bf16_f32 v139, v24, v25
	s_nop 0
	global_store_dwordx4 v[10:11], v[136:139], off
	v_lshl_add_u64 v[10:11], v[10:11], 0, v[18:19]
	s_waitcnt vmcnt(19)
	v_lshlrev_b32_e32 v20, 16, v124
	v_and_b32_e32 v21, 0xffff0000, v124
	v_mul_f32_e32 v22, 0x3fb8aa3b, v20
	v_mul_f32_e32 v23, 0x3fb8aa3b, v21
	v_exp_f32_e32 v22, v22
	v_exp_f32_e32 v23, v23
	v_lshlrev_b32_e32 v20, 16, v128
	v_and_b32_e32 v21, 0xffff0000, v128
	v_fma_f32 v6, v6, v22, v20
	v_fma_f32 v7, v7, v23, v21
	v_lshlrev_b32_e32 v20, 16, v132
	v_and_b32_e32 v21, 0xffff0000, v132
	v_mul_f32_e32 v20, v6, v20
	v_mul_f32_e32 v21, v7, v21
	v_cvt_pk_bf16_f32 v136, v20, v21
	v_lshlrev_b32_e32 v24, 16, v125
	v_and_b32_e32 v25, 0xffff0000, v125
	v_mul_f32_e32 v26, 0x3fb8aa3b, v24
	v_mul_f32_e32 v27, 0x3fb8aa3b, v25
	v_exp_f32_e32 v26, v26
	v_exp_f32_e32 v27, v27
	v_lshlrev_b32_e32 v24, 16, v129
	v_and_b32_e32 v25, 0xffff0000, v129
	v_fma_f32 v8, v8, v26, v24
	v_fma_f32 v9, v9, v27, v25
	v_lshlrev_b32_e32 v24, 16, v133
	v_and_b32_e32 v25, 0xffff0000, v133
	v_mul_f32_e32 v24, v8, v24
	v_mul_f32_e32 v25, v9, v25
	v_cvt_pk_bf16_f32 v137, v24, v25
	v_lshlrev_b32_e32 v20, 16, v126
	v_and_b32_e32 v21, 0xffff0000, v126
	v_mul_f32_e32 v22, 0x3fb8aa3b, v20
	v_mul_f32_e32 v23, 0x3fb8aa3b, v21
	v_exp_f32_e32 v22, v22
	v_exp_f32_e32 v23, v23
	v_lshlrev_b32_e32 v20, 16, v130
	v_and_b32_e32 v21, 0xffff0000, v130
	v_fma_f32 v2, v2, v22, v20
	v_fma_f32 v3, v3, v23, v21
	v_lshlrev_b32_e32 v20, 16, v134
	v_and_b32_e32 v21, 0xffff0000, v134
	v_mul_f32_e32 v20, v2, v20
	v_mul_f32_e32 v21, v3, v21
	v_cvt_pk_bf16_f32 v138, v20, v21
	v_lshlrev_b32_e32 v24, 16, v127
	v_and_b32_e32 v25, 0xffff0000, v127
	v_mul_f32_e32 v26, 0x3fb8aa3b, v24
	v_mul_f32_e32 v27, 0x3fb8aa3b, v25
; DI unsigned cvt_pk_bf16(float lo, float hi) { unsigned r; asm volatile("v_cvt_pk_bf16_f32 %0, %1, %2" : "=v"(r) : "v"(lo), "v"(hi)); return r; }
; DI void unpack8(const u32x4 v, float* f) { f[0] = bf_lo(v.x); f[1] = bf_hi(v.x); f[2] = bf_lo(v.y); f[3] = bf_hi(v.y); f[4] = bf_lo(v.z); f[5] = bf_hi(v.z); f[6] = bf_lo(v.w); f[7] = bf_hi(v.w); }
; DI void phase_scan2(const bf16_t* la, const bf16_t* bb, const bf16_t* y, const float* hin, bf16_t* yh) {
;     ...
;     for (int t = 0; t < 32; ++t) {
;       float l[8], bv[8], yv[8]; unpack8(*(const u32x4*)(la + base + (size_t)t * DM), l); unpack8(*(const u32x4*)(bb + base + (size_t)t * DM), bv); unpack8(*(const u32x4*)(y + base + (size_t)t * DM), yv);
;       float o[8];
; #pragma unroll
;       for (int e = 0; e < 8; ++e) { h[e] = __expf(l[e]) * h[e] + bv[e]; o[e] = h[e] * yv[e]; }
;       u32x4 wv; wv.x = cvt_pk_bf16(o[0], o[1]); wv.y = cvt_pk_bf16(o[2], o[3]); wv.z = cvt_pk_bf16(o[4], o[5]); wv.w = cvt_pk_bf16(o[6], o[7]);
;       *(u32x4*)(yh + base + (size_t)t * DM) = wv;
	v_exp_f32_e32 v26, v26
	v_exp_f32_e32 v27, v27
	v_lshlrev_b32_e32 v24, 16, v131
	v_and_b32_e32 v25, 0xffff0000, v131
	v_fma_f32 v4, v4, v26, v24
	v_fma_f32 v5, v5, v27, v25
	v_lshlrev_b32_e32 v24, 16, v135
	v_and_b32_e32 v25, 0xffff0000, v135
	v_mul_f32_e32 v24, v4, v24
	v_mul_f32_e32 v25, v5, v25
	v_cvt_pk_bf16_f32 v139, v24, v25
	s_nop 0
	global_store_dwordx4 v[10:11], v[136:139], off
	v_lshl_add_u64 v[10:11], v[10:11], 0, v[18:19]
	global_load_dwordx4 v[88:91], v[16:17], off
	global_load_dwordx4 v[92:95], v[14:15], off
	global_load_dwordx4 v[96:99], v[12:13], off
	v_lshl_add_u64 v[16:17], v[16:17], 0, v[18:19]
	v_lshl_add_u64 v[14:15], v[14:15], 0, v[18:19]
	v_lshl_add_u64 v[12:13], v[12:13], 0, v[18:19]
	global_load_dwordx4 v[100:103], v[16:17], off
	global_load_dwordx4 v[104:107], v[14:15], off
	global_load_dwordx4 v[108:111], v[12:13], off
	v_lshl_add_u64 v[16:17], v[16:17], 0, v[18:19]
	v_lshl_add_u64 v[14:15], v[14:15], 0, v[18:19]
	v_lshl_add_u64 v[12:13], v[12:13], 0, v[18:19]
	global_load_dwordx4 v[112:115], v[16:17], off
	global_load_dwordx4 v[116:119], v[14:15], off
	global_load_dwordx4 v[120:123], v[12:13], off
	v_lshl_add_u64 v[16:17], v[16:17], 0, v[18:19]
	v_lshl_add_u64 v[14:15], v[14:15], 0, v[18:19]
	v_lshl_add_u64 v[12:13], v[12:13], 0, v[18:19]
	global_load_dwordx4 v[124:127], v[16:17], off
	global_load_dwordx4 v[128:131], v[14:15], off
	global_load_dwordx4 v[132:135], v[12:13], off
	v_lshl_add_u64 v[16:17], v[16:17], 0, v[18:19]
	v_lshl_add_u64 v[14:15], v[14:15], 0, v[18:19]
	v_lshl_add_u64 v[12:13], v[12:13], 0, v[18:19]
	s_waitcnt vmcnt(25)
	v_lshlrev_b32_e32 v20, 16, v40
	v_and_b32_e32 v21, 0xffff0000, v40
	v_mul_f32_e32 v22, 0x3fb8aa3b, v20
	v_mul_f32_e32 v23, 0x3fb8aa3b, v21
	v_exp_f32_e32 v22, v22
	v_exp_f32_e32 v23, v23
	v_lshlrev_b32_e32 v20, 16, v44
	v_and_b32_e32 v21, 0xffff0000, v44
	v_fma_f32 v6, v6, v22, v20
	v_fma_f32 v7, v7, v23, v21
	v_lshlrev_b32_e32 v20, 16, v48
	v_and_b32_e32 v21, 0xffff0000, v48
	v_mul_f32_e32 v20, v6, v20
	v_mul_f32_e32 v21, v7, v21
	v_cvt_pk_bf16_f32 v136, v20, v21
	v_lshlrev_b32_e32 v24, 16, v41
	v_and_b32_e32 v25, 0xffff0000, v41
	v_mul_f32_e32 v26, 0x3fb8aa3b, v24
	v_mul_f32_e32 v27, 0x3fb8aa3b, v25
	v_exp_f32_e32 v26, v26
	v_exp_f32_e32 v27, v27
	v_lshlrev_b32_e32 v24, 16, v45
	v_and_b32_e32 v25, 0xffff0000, v45
	v_fma_f32 v8, v8, v26, v24
	v_fma_f32 v9, v9, v27, v25
	v_lshlrev_b32_e32 v24, 16, v49
	v_and_b32_e32 v25, 0xffff0000, v49
	v_mul_f32_e32 v24, v8, v24
	v_mul_f32_e32 v25, v9, v25
	v_cvt_pk_bf16_f32 v137, v24, v25
	v_lshlrev_b32_e32 v20, 16, v42
	v_and_b32_e32 v21, 0xffff0000, v42
	v_mul_f32_e32 v22, 0x3fb8aa3b, v20
	v_mul_f32_e32 v23, 0x3fb8aa3b, v21
	v_exp_f32_e32 v22, v22
	v_exp_f32_e32 v23, v23
	v_lshlrev_b32_e32 v20, 16, v46
	v_and_b32_e32 v21, 0xffff0000, v46
	v_fma_f32 v2, v2, v22, v20
	v_fma_f32 v3, v3, v23, v21
	v_lshlrev_b32_e32 v20, 16, v50
	v_and_b32_e32 v21, 0xffff0000, v50
	v_mul_f32_e32 v20, v2, v20
	v_mul_f32_e32 v21, v3, v21
	v_cvt_pk_bf16_f32 v138, v20, v21
	v_lshlrev_b32_e32 v24, 16, v43
	v_and_b32_e32 v25, 0xffff0000, v43
	v_mul_f32_e32 v26, 0x3fb8aa3b, v24
	v_mul_f32_e32 v27, 0x3fb8aa3b, v25
	v_exp_f32_e32 v26, v26
	v_exp_f32_e32 v27, v27
	v_lshlrev_b32_e32 v24, 16, v47
	v_and_b32_e32 v25, 0xffff0000, v47
	v_fma_f32 v4, v4, v26, v24
	v_fma_f32 v5, v5, v27, v25
	v_lshlrev_b32_e32 v24, 16, v51
	v_and_b32_e32 v25, 0xffff0000, v51
	v_mul_f32_e32 v24, v4, v24
	v_mul_f32_e32 v25, v5, v25
	v_cvt_pk_bf16_f32 v139, v24, v25
	s_nop 0
	global_store_dwordx4 v[10:11], v[136:139], off
	v_lshl_add_u64 v[10:11], v[10:11], 0, v[18:19]
	s_waitcnt vmcnt(23)
	v_lshlrev_b32_e32 v20, 16, v52
	v_and_b32_e32 v21, 0xffff0000, v52
	v_mul_f32_e32 v22, 0x3fb8aa3b, v20
	v_mul_f32_e32 v23, 0x3fb8aa3b, v21
	v_exp_f32_e32 v22, v22
	v_exp_f32_e32 v23, v23
	v_lshlrev_b32_e32 v20, 16, v56
	v_and_b32_e32 v21, 0xffff0000, v56
	v_fma_f32 v6, v6, v22, v20
	v_fma_f32 v7, v7, v23, v21
	v_lshlrev_b32_e32 v20, 16, v60
	v_and_b32_e32 v21, 0xffff0000, v60
	v_mul_f32_e32 v20, v6, v20
	v_mul_f32_e32 v21, v7, v21
	v_cvt_pk_bf16_f32 v136, v20, v21
	v_lshlrev_b32_e32 v24, 16, v53
	v_and_b32_e32 v25, 0xffff0000, v53
	v_mul_f32_e32 v26, 0x3fb8aa3b, v24
	v_mul_f32_e32 v27, 0x3fb8aa3b, v25
	v_exp_f32_e32 v26, v26
	v_exp_f32_e32 v27, v27
	v_lshlrev_b32_e32 v24, 16, v57
	v_and_b32_e32 v25, 0xffff0000, v57
	v_fma_f32 v8, v8, v26, v24
	v_fma_f32 v9, v9, v27, v25
	v_lshlrev_b32_e32 v24, 16, v61
	v_and_b32_e32 v25, 0xffff0000, v61
	v_mul_f32_e32 v24, v8, v24
	v_mul_f32_e32 v25, v9, v25
	v_cvt_pk_bf16_f32 v137, v24, v25
	v_lshlrev_b32_e32 v20, 16, v54
	v_and_b32_e32 v21, 0xffff0000, v54
	v_mul_f32_e32 v22, 0x3fb8aa3b, v20
	v_mul_f32_e32 v23, 0x3fb8aa3b, v21
	v_exp_f32_e32 v22, v22
	v_exp_f32_e32 v23, v23
	v_lshlrev_b32_e32 v20, 16, v58
	v_and_b32_e32 v21, 0xffff0000, v58
	v_fma_f32 v2, v2, v22, v20
	v_fma_f32 v3, v3, v23, v21
	v_lshlrev_b32_e32 v20, 16, v62
	v_and_b32_e32 v21, 0xffff0000, v62
	v_mul_f32_e32 v20, v2, v20
	v_mul_f32_e32 v21, v3, v21
	v_cvt_pk_bf16_f32 v138, v20, v21
	v_lshlrev_b32_e32 v24, 16, v55
	v_and_b32_e32 v25, 0xffff0000, v55
	v_mul_f32_e32 v26, 0x3fb8aa3b, v24
	v_mul_f32_e32 v27, 0x3fb8aa3b, v25
	v_exp_f32_e32 v26, v26
	v_exp_f32_e32 v27, v27
	v_lshlrev_b32_e32 v24, 16, v59
	v_and_b32_e32 v25, 0xffff0000, v59
	v_fma_f32 v4, v4, v26, v24
	v_fma_f32 v5, v5, v27, v25
	v_lshlrev_b32_e32 v24, 16, v63
	v_and_b32_e32 v25, 0xffff0000, v63
	v_mul_f32_e32 v24, v4, v24
	v_mul_f32_e32 v25, v5, v25
	v_cvt_pk_bf16_f32 v139, v24, v25
	s_nop 0
	global_store_dwordx4 v[10:11], v[136:139], off
	v_lshl_add_u64 v[10:11], v[10:11], 0, v[18:19]
	s_waitcnt vmcnt(21)
; DI unsigned cvt_pk_bf16(float lo, float hi) { unsigned r; asm volatile("v_cvt_pk_bf16_f32 %0, %1, %2" : "=v"(r) : "v"(lo), "v"(hi)); return r; }
; DI void unpack8(const u32x4 v, float* f) { f[0] = bf_lo(v.x); f[1] = bf_hi(v.x); f[2] = bf_lo(v.y); f[3] = bf_hi(v.y); f[4] = bf_lo(v.z); f[5] = bf_hi(v.z); f[6] = bf_lo(v.w); f[7] = bf_hi(v.w); }
; DI void phase_scan2(const bf16_t* la, const bf16_t* bb, const bf16_t* y, const float* hin, bf16_t* yh) {
;     ...
;     for (int t = 0; t < 32; ++t) {
;       float l[8], bv[8], yv[8]; unpack8(*(const u32x4*)(la + base + (size_t)t * DM), l); unpack8(*(const u32x4*)(bb + base + (size_t)t * DM), bv); unpack8(*(const u32x4*)(y + base + (size_t)t * DM), yv);
;       float o[8];
; #pragma unroll
;       for (int e = 0; e < 8; ++e) { h[e] = __expf(l[e]) * h[e] + bv[e]; o[e] = h[e] * yv[e]; }
;       u32x4 wv; wv.x = cvt_pk_bf16(o[0], o[1]); wv.y = cvt_pk_bf16(o[2], o[3]); wv.z = cvt_pk_bf16(o[4], o[5]); wv.w = cvt_pk_bf16(o[6], o[7]);
;       *(u32x4*)(yh + base + (size_t)t * DM) = wv;
	v_lshlrev_b32_e32 v20, 16, v64
	v_and_b32_e32 v21, 0xffff0000, v64
	v_mul_f32_e32 v22, 0x3fb8aa3b, v20
	v_mul_f32_e32 v23, 0x3fb8aa3b, v21
	v_exp_f32_e32 v22, v22
	v_exp_f32_e32 v23, v23
	v_lshlrev_b32_e32 v20, 16, v68
	v_and_b32_e32 v21, 0xffff0000, v68
	v_fma_f32 v6, v6, v22, v20
	v_fma_f32 v7, v7, v23, v21
	v_lshlrev_b32_e32 v20, 16, v72
	v_and_b32_e32 v21, 0xffff0000, v72
	v_mul_f32_e32 v20, v6, v20
	v_mul_f32_e32 v21, v7, v21
	v_cvt_pk_bf16_f32 v136, v20, v21
	v_lshlrev_b32_e32 v24, 16, v65
	v_and_b32_e32 v25, 0xffff0000, v65
	v_mul_f32_e32 v26, 0x3fb8aa3b, v24
	v_mul_f32_e32 v27, 0x3fb8aa3b, v25
	v_exp_f32_e32 v26, v26
	v_exp_f32_e32 v27, v27
	v_lshlrev_b32_e32 v24, 16, v69
	v_and_b32_e32 v25, 0xffff0000, v69
	v_fma_f32 v8, v8, v26, v24
	v_fma_f32 v9, v9, v27, v25
	v_lshlrev_b32_e32 v24, 16, v73
	v_and_b32_e32 v25, 0xffff0000, v73
	v_mul_f32_e32 v24, v8, v24
	v_mul_f32_e32 v25, v9, v25
	v_cvt_pk_bf16_f32 v137, v24, v25
	v_lshlrev_b32_e32 v20, 16, v66
	v_and_b32_e32 v21, 0xffff0000, v66
	v_mul_f32_e32 v22, 0x3fb8aa3b, v20
	v_mul_f32_e32 v23, 0x3fb8aa3b, v21
	v_exp_f32_e32 v22, v22
	v_exp_f32_e32 v23, v23
	v_lshlrev_b32_e32 v20, 16, v70
	v_and_b32_e32 v21, 0xffff0000, v70
	v_fma_f32 v2, v2, v22, v20
	v_fma_f32 v3, v3, v23, v21
	v_lshlrev_b32_e32 v20, 16, v74
	v_and_b32_e32 v21, 0xffff0000, v74
	v_mul_f32_e32 v20, v2, v20
	v_mul_f32_e32 v21, v3, v21
	v_cvt_pk_bf16_f32 v138, v20, v21
	v_lshlrev_b32_e32 v24, 16, v67
	v_and_b32_e32 v25, 0xffff0000, v67
	v_mul_f32_e32 v26, 0x3fb8aa3b, v24
	v_mul_f32_e32 v27, 0x3fb8aa3b, v25
	v_exp_f32_e32 v26, v26
	v_exp_f32_e32 v27, v27
	v_lshlrev_b32_e32 v24, 16, v71
	v_and_b32_e32 v25, 0xffff0000, v71
	v_fma_f32 v4, v4, v26, v24
	v_fma_f32 v5, v5, v27, v25
	v_lshlrev_b32_e32 v24, 16, v75
	v_and_b32_e32 v25, 0xffff0000, v75
	v_mul_f32_e32 v24, v4, v24
	v_mul_f32_e32 v25, v5, v25
	v_cvt_pk_bf16_f32 v139, v24, v25
	s_nop 0
	global_store_dwordx4 v[10:11], v[136:139], off
	v_lshl_add_u64 v[10:11], v[10:11], 0, v[18:19]
	s_waitcnt vmcnt(19)
	v_lshlrev_b32_e32 v20, 16, v76
	v_and_b32_e32 v21, 0xffff0000, v76
	v_mul_f32_e32 v22, 0x3fb8aa3b, v20
	v_mul_f32_e32 v23, 0x3fb8aa3b, v21
	v_exp_f32_e32 v22, v22
	v_exp_f32_e32 v23, v23
	v_lshlrev_b32_e32 v20, 16, v80
	v_and_b32_e32 v21, 0xffff0000, v80
	v_fma_f32 v6, v6, v22, v20
	v_fma_f32 v7, v7, v23, v21
	v_lshlrev_b32_e32 v20, 16, v84
	v_and_b32_e32 v21, 0xffff0000, v84
	v_mul_f32_e32 v20, v6, v20
	v_mul_f32_e32 v21, v7, v21
	v_cvt_pk_bf16_f32 v136, v20, v21
	v_lshlrev_b32_e32 v24, 16, v77
	v_and_b32_e32 v25, 0xffff0000, v77
	v_mul_f32_e32 v26, 0x3fb8aa3b, v24
	v_mul_f32_e32 v27, 0x3fb8aa3b, v25
	v_exp_f32_e32 v26, v26
	v_exp_f32_e32 v27, v27
	v_lshlrev_b32_e32 v24, 16, v81
	v_and_b32_e32 v25, 0xffff0000, v81
	v_fma_f32 v8, v8, v26, v24
	v_fma_f32 v9, v9, v27, v25
	v_lshlrev_b32_e32 v24, 16, v85
	v_and_b32_e32 v25, 0xffff0000, v85
	v_mul_f32_e32 v24, v8, v24
	v_mul_f32_e32 v25, v9, v25
	v_cvt_pk_bf16_f32 v137, v24, v25
	v_lshlrev_b32_e32 v20, 16, v78
	v_and_b32_e32 v21, 0xffff0000, v78
	v_mul_f32_e32 v22, 0x3fb8aa3b, v20
	v_mul_f32_e32 v23, 0x3fb8aa3b, v21
	v_exp_f32_e32 v22, v22
	v_exp_f32_e32 v23, v23
	v_lshlrev_b32_e32 v20, 16, v82
	v_and_b32_e32 v21, 0xffff0000, v82
	v_fma_f32 v2, v2, v22, v20
	v_fma_f32 v3, v3, v23, v21
	v_lshlrev_b32_e32 v20, 16, v86
	v_and_b32_e32 v21, 0xffff0000, v86
	v_mul_f32_e32 v20, v2, v20
	v_mul_f32_e32 v21, v3, v21
	v_cvt_pk_bf16_f32 v138, v20, v21
	v_lshlrev_b32_e32 v24, 16, v79
	v_and_b32_e32 v25, 0xffff0000, v79
	v_mul_f32_e32 v26, 0x3fb8aa3b, v24
	v_mul_f32_e32 v27, 0x3fb8aa3b, v25
	v_exp_f32_e32 v26, v26
	v_exp_f32_e32 v27, v27
	v_lshlrev_b32_e32 v24, 16, v83
	v_and_b32_e32 v25, 0xffff0000, v83
	v_fma_f32 v4, v4, v26, v24
	v_fma_f32 v5, v5, v27, v25
	v_lshlrev_b32_e32 v24, 16, v87
	v_and_b32_e32 v25, 0xffff0000, v87
	v_mul_f32_e32 v24, v4, v24
	v_mul_f32_e32 v25, v5, v25
	v_cvt_pk_bf16_f32 v139, v24, v25
	s_nop 0
	global_store_dwordx4 v[10:11], v[136:139], off
	v_lshl_add_u64 v[10:11], v[10:11], 0, v[18:19]
	s_waitcnt vmcnt(13)
	v_lshlrev_b32_e32 v20, 16, v88
	v_and_b32_e32 v21, 0xffff0000, v88
	v_mul_f32_e32 v22, 0x3fb8aa3b, v20
	v_mul_f32_e32 v23, 0x3fb8aa3b, v21
	v_exp_f32_e32 v22, v22
	v_exp_f32_e32 v23, v23
	v_lshlrev_b32_e32 v20, 16, v92
	v_and_b32_e32 v21, 0xffff0000, v92
	v_fma_f32 v6, v6, v22, v20
	v_fma_f32 v7, v7, v23, v21
	v_lshlrev_b32_e32 v20, 16, v96
	v_and_b32_e32 v21, 0xffff0000, v96
	v_mul_f32_e32 v20, v6, v20
	v_mul_f32_e32 v21, v7, v21
	v_cvt_pk_bf16_f32 v136, v20, v21
	v_lshlrev_b32_e32 v24, 16, v89
	v_and_b32_e32 v25, 0xffff0000, v89
	v_mul_f32_e32 v26, 0x3fb8aa3b, v24
	v_mul_f32_e32 v27, 0x3fb8aa3b, v25
	v_exp_f32_e32 v26, v26
	v_exp_f32_e32 v27, v27
	v_lshlrev_b32_e32 v24, 16, v93
	v_and_b32_e32 v25, 0xffff0000, v93
	v_fma_f32 v8, v8, v26, v24
	v_fma_f32 v9, v9, v27, v25
	v_lshlrev_b32_e32 v24, 16, v97
	v_and_b32_e32 v25, 0xffff0000, v97
	v_mul_f32_e32 v24, v8, v24
	v_mul_f32_e32 v25, v9, v25
	v_cvt_pk_bf16_f32 v137, v24, v25
	v_lshlrev_b32_e32 v20, 16, v90
	v_and_b32_e32 v21, 0xffff0000, v90
	v_mul_f32_e32 v22, 0x3fb8aa3b, v20
	v_mul_f32_e32 v23, 0x3fb8aa3b, v21
	v_exp_f32_e32 v22, v22
	v_exp_f32_e32 v23, v23
	v_lshlrev_b32_e32 v20, 16, v94
	v_and_b32_e32 v21, 0xffff0000, v94
	v_fma_f32 v2, v2, v22, v20
	v_fma_f32 v3, v3, v23, v21
	v_lshlrev_b32_e32 v20, 16, v98
	v_and_b32_e32 v21, 0xffff0000, v98
	v_mul_f32_e32 v20, v2, v20
	v_mul_f32_e32 v21, v3, v21
	v_cvt_pk_bf16_f32 v138, v20, v21
	v_lshlrev_b32_e32 v24, 16, v91
	v_and_b32_e32 v25, 0xffff0000, v91
	v_mul_f32_e32 v26, 0x3fb8aa3b, v24
	v_mul_f32_e32 v27, 0x3fb8aa3b, v25
	v_exp_f32_e32 v26, v26
	v_exp_f32_e32 v27, v27
	v_lshlrev_b32_e32 v24, 16, v95
	v_and_b32_e32 v25, 0xffff0000, v95
	v_fma_f32 v4, v4, v26, v24
	v_fma_f32 v5, v5, v27, v25
	v_lshlrev_b32_e32 v24, 16, v99
	v_and_b32_e32 v25, 0xffff0000, v99
	v_mul_f32_e32 v24, v4, v24
	v_mul_f32_e32 v25, v5, v25
	v_cvt_pk_bf16_f32 v139, v24, v25
	s_nop 0
	global_store_dwordx4 v[10:11], v[136:139], off
	v_lshl_add_u64 v[10:11], v[10:11], 0, v[18:19]
	s_waitcnt vmcnt(11)
; DI unsigned cvt_pk_bf16(float lo, float hi) { unsigned r; asm volatile("v_cvt_pk_bf16_f32 %0, %1, %2" : "=v"(r) : "v"(lo), "v"(hi)); return r; }
; DI int tid_fresh() { int t = threadIdx.x; asm volatile("" : "+v"(t)); return t; }
; DI void unpack8(const u32x4 v, float* f) { f[0] = bf_lo(v.x); f[1] = bf_hi(v.x); f[2] = bf_lo(v.y); f[3] = bf_hi(v.y); f[4] = bf_lo(v.z); f[5] = bf_hi(v.z); f[6] = bf_lo(v.w); f[7] = bf_hi(v.w); }
; DI void phase_scan2(const bf16_t* la, const bf16_t* bb, const bf16_t* y, const float* hin, bf16_t* yh) {
;   for (int it = blockIdx.x * 512 + tid_fresh(); it < NB * 128 * 256; it += gridDim.x * 512) {
;     const int chg = it & 255, c = (it >> 8) & 127, b = it >> 15;
;     const size_t base = ((size_t)b * SEQ + c * 32) * DM + chg * 8;
;     const size_t so = ((size_t)b * 128 + c) * DM + chg * 8;
;     float h[8];
;     { const f32x4 a = *(const f32x4*)(hin + so), bq = *(const f32x4*)(hin + so + 4);
; #pragma unroll
;       for (int e = 0; e < 4; ++e) { h[e] = a[e]; h[4 + e] = bq[e]; } }
; #pragma unroll 8
;     for (int t = 0; t < 32; ++t) {
;       float l[8], bv[8], yv[8]; unpack8(*(const u32x4*)(la + base + (size_t)t * DM), l); unpack8(*(const u32x4*)(bb + base + (size_t)t * DM), bv); unpack8(*(const u32x4*)(y + base + (size_t)t * DM), yv);
;       float o[8];
; #pragma unroll
;       for (int e = 0; e < 8; ++e) { h[e] = __expf(l[e]) * h[e] + bv[e]; o[e] = h[e] * yv[e]; }
;       u32x4 wv; wv.x = cvt_pk_bf16(o[0], o[1]); wv.y = cvt_pk_bf16(o[2], o[3]); wv.z = cvt_pk_bf16(o[4], o[5]); wv.w = cvt_pk_bf16(o[6], o[7]);
;       *(u32x4*)(yh + base + (size_t)t * DM) = wv;
;     }
	v_lshlrev_b32_e32 v20, 16, v100
	v_and_b32_e32 v21, 0xffff0000, v100
	v_mul_f32_e32 v22, 0x3fb8aa3b, v20
	v_mul_f32_e32 v23, 0x3fb8aa3b, v21
	v_exp_f32_e32 v22, v22
	v_exp_f32_e32 v23, v23
	v_lshlrev_b32_e32 v20, 16, v104
	v_and_b32_e32 v21, 0xffff0000, v104
	v_fma_f32 v6, v6, v22, v20
	v_fma_f32 v7, v7, v23, v21
	v_lshlrev_b32_e32 v20, 16, v108
	v_and_b32_e32 v21, 0xffff0000, v108
	v_mul_f32_e32 v20, v6, v20
	v_mul_f32_e32 v21, v7, v21
	v_cvt_pk_bf16_f32 v136, v20, v21
	v_lshlrev_b32_e32 v24, 16, v101
	v_and_b32_e32 v25, 0xffff0000, v101
	v_mul_f32_e32 v26, 0x3fb8aa3b, v24
	v_mul_f32_e32 v27, 0x3fb8aa3b, v25
	v_exp_f32_e32 v26, v26
	v_exp_f32_e32 v27, v27
	v_lshlrev_b32_e32 v24, 16, v105
	v_and_b32_e32 v25, 0xffff0000, v105
	v_fma_f32 v8, v8, v26, v24
	v_fma_f32 v9, v9, v27, v25
	v_lshlrev_b32_e32 v24, 16, v109
	v_and_b32_e32 v25, 0xffff0000, v109
	v_mul_f32_e32 v24, v8, v24
	v_mul_f32_e32 v25, v9, v25
	v_cvt_pk_bf16_f32 v137, v24, v25
	v_lshlrev_b32_e32 v20, 16, v102
	v_and_b32_e32 v21, 0xffff0000, v102
	v_mul_f32_e32 v22, 0x3fb8aa3b, v20
	v_mul_f32_e32 v23, 0x3fb8aa3b, v21
	v_exp_f32_e32 v22, v22
	v_exp_f32_e32 v23, v23
	v_lshlrev_b32_e32 v20, 16, v106
	v_and_b32_e32 v21, 0xffff0000, v106
	v_fma_f32 v2, v2, v22, v20
	v_fma_f32 v3, v3, v23, v21
	v_lshlrev_b32_e32 v20, 16, v110
	v_and_b32_e32 v21, 0xffff0000, v110
	v_mul_f32_e32 v20, v2, v20
	v_mul_f32_e32 v21, v3, v21
	v_cvt_pk_bf16_f32 v138, v20, v21
	v_lshlrev_b32_e32 v24, 16, v103
	v_and_b32_e32 v25, 0xffff0000, v103
	v_mul_f32_e32 v26, 0x3fb8aa3b, v24
	v_mul_f32_e32 v27, 0x3fb8aa3b, v25
	v_exp_f32_e32 v26, v26
	v_exp_f32_e32 v27, v27
	v_lshlrev_b32_e32 v24, 16, v107
	v_and_b32_e32 v25, 0xffff0000, v107
	v_fma_f32 v4, v4, v26, v24
	v_fma_f32 v5, v5, v27, v25
	v_lshlrev_b32_e32 v24, 16, v111
	v_and_b32_e32 v25, 0xffff0000, v111
	v_mul_f32_e32 v24, v4, v24
	v_mul_f32_e32 v25, v5, v25
	v_cvt_pk_bf16_f32 v139, v24, v25
	s_nop 0
	global_store_dwordx4 v[10:11], v[136:139], off
	v_lshl_add_u64 v[10:11], v[10:11], 0, v[18:19]
	s_waitcnt vmcnt(9)
	v_lshlrev_b32_e32 v20, 16, v112
	v_and_b32_e32 v21, 0xffff0000, v112
	v_mul_f32_e32 v22, 0x3fb8aa3b, v20
	v_mul_f32_e32 v23, 0x3fb8aa3b, v21
	v_exp_f32_e32 v22, v22
	v_exp_f32_e32 v23, v23
	v_lshlrev_b32_e32 v20, 16, v116
	v_and_b32_e32 v21, 0xffff0000, v116
	v_fma_f32 v6, v6, v22, v20
	v_fma_f32 v7, v7, v23, v21
	v_lshlrev_b32_e32 v20, 16, v120
	v_and_b32_e32 v21, 0xffff0000, v120
	v_mul_f32_e32 v20, v6, v20
	v_mul_f32_e32 v21, v7, v21
	v_cvt_pk_bf16_f32 v136, v20, v21
	v_lshlrev_b32_e32 v24, 16, v113
	v_and_b32_e32 v25, 0xffff0000, v113
	v_mul_f32_e32 v26, 0x3fb8aa3b, v24
	v_mul_f32_e32 v27, 0x3fb8aa3b, v25
	v_exp_f32_e32 v26, v26
	v_exp_f32_e32 v27, v27
	v_lshlrev_b32_e32 v24, 16, v117
	v_and_b32_e32 v25, 0xffff0000, v117
	v_fma_f32 v8, v8, v26, v24
	v_fma_f32 v9, v9, v27, v25
	v_lshlrev_b32_e32 v24, 16, v121
	v_and_b32_e32 v25, 0xffff0000, v121
	v_mul_f32_e32 v24, v8, v24
	v_mul_f32_e32 v25, v9, v25
	v_cvt_pk_bf16_f32 v137, v24, v25
	v_lshlrev_b32_e32 v20, 16, v114
	v_and_b32_e32 v21, 0xffff0000, v114
	v_mul_f32_e32 v22, 0x3fb8aa3b, v20
	v_mul_f32_e32 v23, 0x3fb8aa3b, v21
	v_exp_f32_e32 v22, v22
	v_exp_f32_e32 v23, v23
	v_lshlrev_b32_e32 v20, 16, v118
	v_and_b32_e32 v21, 0xffff0000, v118
	v_fma_f32 v2, v2, v22, v20
	v_fma_f32 v3, v3, v23, v21
	v_lshlrev_b32_e32 v20, 16, v122
	v_and_b32_e32 v21, 0xffff0000, v122
	v_mul_f32_e32 v20, v2, v20
	v_mul_f32_e32 v21, v3, v21
	v_cvt_pk_bf16_f32 v138, v20, v21
	v_lshlrev_b32_e32 v24, 16, v115
	v_and_b32_e32 v25, 0xffff0000, v115
	v_mul_f32_e32 v26, 0x3fb8aa3b, v24
	v_mul_f32_e32 v27, 0x3fb8aa3b, v25
	v_exp_f32_e32 v26, v26
	v_exp_f32_e32 v27, v27
	v_lshlrev_b32_e32 v24, 16, v119
	v_and_b32_e32 v25, 0xffff0000, v119
	v_fma_f32 v4, v4, v26, v24
	v_fma_f32 v5, v5, v27, v25
	v_lshlrev_b32_e32 v24, 16, v123
	v_and_b32_e32 v25, 0xffff0000, v123
	v_mul_f32_e32 v24, v4, v24
	v_mul_f32_e32 v25, v5, v25
	v_cvt_pk_bf16_f32 v139, v24, v25
	s_nop 0
	global_store_dwordx4 v[10:11], v[136:139], off
	v_lshl_add_u64 v[10:11], v[10:11], 0, v[18:19]
	s_waitcnt vmcnt(7)
	v_lshlrev_b32_e32 v20, 16, v124
	v_and_b32_e32 v21, 0xffff0000, v124
	v_mul_f32_e32 v22, 0x3fb8aa3b, v20
	v_mul_f32_e32 v23, 0x3fb8aa3b, v21
	v_exp_f32_e32 v22, v22
	v_exp_f32_e32 v23, v23
	v_lshlrev_b32_e32 v20, 16, v128
	v_and_b32_e32 v21, 0xffff0000, v128
	v_fma_f32 v6, v6, v22, v20
	v_fma_f32 v7, v7, v23, v21
	v_lshlrev_b32_e32 v20, 16, v132
	v_and_b32_e32 v21, 0xffff0000, v132
	v_mul_f32_e32 v20, v6, v20
	v_mul_f32_e32 v21, v7, v21
	v_cvt_pk_bf16_f32 v136, v20, v21
	v_lshlrev_b32_e32 v24, 16, v125
	v_and_b32_e32 v25, 0xffff0000, v125
	v_mul_f32_e32 v26, 0x3fb8aa3b, v24
	v_mul_f32_e32 v27, 0x3fb8aa3b, v25
	v_exp_f32_e32 v26, v26
	v_exp_f32_e32 v27, v27
	v_lshlrev_b32_e32 v24, 16, v129
	v_and_b32_e32 v25, 0xffff0000, v129
	v_fma_f32 v8, v8, v26, v24
	v_fma_f32 v9, v9, v27, v25
	v_lshlrev_b32_e32 v24, 16, v133
	v_and_b32_e32 v25, 0xffff0000, v133
	v_mul_f32_e32 v24, v8, v24
	v_mul_f32_e32 v25, v9, v25
	v_cvt_pk_bf16_f32 v137, v24, v25
	v_lshlrev_b32_e32 v20, 16, v126
	v_and_b32_e32 v21, 0xffff0000, v126
	v_mul_f32_e32 v22, 0x3fb8aa3b, v20
	v_mul_f32_e32 v23, 0x3fb8aa3b, v21
	v_exp_f32_e32 v22, v22
	v_exp_f32_e32 v23, v23
	v_lshlrev_b32_e32 v20, 16, v130
	v_and_b32_e32 v21, 0xffff0000, v130
	v_fma_f32 v2, v2, v22, v20
	v_fma_f32 v3, v3, v23, v21
	v_lshlrev_b32_e32 v20, 16, v134
	v_and_b32_e32 v21, 0xffff0000, v134
	v_mul_f32_e32 v20, v2, v20
	v_mul_f32_e32 v21, v3, v21
	v_cvt_pk_bf16_f32 v138, v20, v21
	v_lshlrev_b32_e32 v24, 16, v127
	v_and_b32_e32 v25, 0xffff0000, v127
	v_mul_f32_e32 v26, 0x3fb8aa3b, v24
	v_mul_f32_e32 v27, 0x3fb8aa3b, v25
	v_exp_f32_e32 v26, v26
	v_exp_f32_e32 v27, v27
	v_lshlrev_b32_e32 v24, 16, v131
	v_and_b32_e32 v25, 0xffff0000, v131
	v_fma_f32 v4, v4, v26, v24
	v_fma_f32 v5, v5, v27, v25
	v_lshlrev_b32_e32 v24, 16, v135
	v_and_b32_e32 v25, 0xffff0000, v135
	v_mul_f32_e32 v24, v4, v24
	v_mul_f32_e32 v25, v5, v25
	v_cvt_pk_bf16_f32 v139, v24, v25
	s_nop 0
	global_store_dwordx4 v[10:11], v[136:139], off
	v_lshl_add_u64 v[10:11], v[10:11], 0, v[18:19]
	s_load_dword s3, s[68:69], 0x0
	s_waitcnt lgkmcnt(0)
	v_lshl_add_u32 v32, s3, 9, v32
	s_mov_b32 s3, 0x1ffff
	v_cmp_lt_i32_e32 vcc, s3, v32
	s_or_b64 s[8:9], vcc, s[8:9]
	s_andn2_b64 exec, exec, s[8:9]
	s_cbranch_execnz .LBB0_34

; DI void unpack8(const u32x4 v, float* f) { f[0] = bf_lo(v.x); f[1] = bf_hi(v.x); f[2] = bf_lo(v.y); f[3] = bf_hi(v.y); f[4] = bf_lo(v.z); f[5] = bf_hi(v.z); f[6] = bf_lo(v.w); f[7] = bf_hi(v.w); }
; DI void phase_scan1(const bf16_t* la, const bf16_t* bb, float* asum, float* hend) {
;     ...
;     const size_t base = ((size_t)b * SEQ + c * 32) * DM + chg * 8;
;     float h[8], as[8];
; #pragma unroll
;     for (int e = 0; e < 8; ++e) { h[e] = 0.f; as[e] = 0.f; }
; #pragma unroll 8
;     for (int t = 0; t < 32; ++t) {
;       float l[8], bv[8]; unpack8(*(const u32x4*)(la + base + (size_t)t * DM), l); unpack8(*(const u32x4*)(bb + base + (size_t)t * DM), bv);
; #pragma unroll
;       for (int e = 0; e < 8; ++e) { h[e] = __expf(l[e]) * h[e] + bv[e]; as[e] += l[e]; }
.LBB0_52:
	v_mov_b32_e32 v26, 0x8000000
	v_mov_b32_e32 v27, 0
	v_lshl_add_u64 v[22:23], v[22:23], 0, v[26:27]
	v_mov_b32_e32 v26, 0x1000
	global_load_dwordx4 v[40:43], v[22:23], off
	global_load_dwordx4 v[44:47], v[20:21], off
	v_lshl_add_u64 v[22:23], v[22:23], 0, v[26:27]
	v_lshl_add_u64 v[20:21], v[20:21], 0, v[26:27]
	global_load_dwordx4 v[48:51], v[22:23], off
	global_load_dwordx4 v[52:55], v[20:21], off
	v_lshl_add_u64 v[22:23], v[22:23], 0, v[26:27]
	v_lshl_add_u64 v[20:21], v[20:21], 0, v[26:27]
	global_load_dwordx4 v[56:59], v[22:23], off
	global_load_dwordx4 v[60:63], v[20:21], off
	v_lshl_add_u64 v[22:23], v[22:23], 0, v[26:27]
	v_lshl_add_u64 v[20:21], v[20:21], 0, v[26:27]
	global_load_dwordx4 v[64:67], v[22:23], off
	global_load_dwordx4 v[68:71], v[20:21], off
	v_lshl_add_u64 v[22:23], v[22:23], 0, v[26:27]
	v_lshl_add_u64 v[20:21], v[20:21], 0, v[26:27]
	global_load_dwordx4 v[72:75], v[22:23], off
	global_load_dwordx4 v[76:79], v[20:21], off
	v_lshl_add_u64 v[22:23], v[22:23], 0, v[26:27]
	v_lshl_add_u64 v[20:21], v[20:21], 0, v[26:27]
	global_load_dwordx4 v[80:83], v[22:23], off
	global_load_dwordx4 v[84:87], v[20:21], off
	v_lshl_add_u64 v[22:23], v[22:23], 0, v[26:27]
	v_lshl_add_u64 v[20:21], v[20:21], 0, v[26:27]
	global_load_dwordx4 v[88:91], v[22:23], off
	global_load_dwordx4 v[92:95], v[20:21], off
	v_lshl_add_u64 v[22:23], v[22:23], 0, v[26:27]
	v_lshl_add_u64 v[20:21], v[20:21], 0, v[26:27]
	global_load_dwordx4 v[96:99], v[22:23], off
	global_load_dwordx4 v[100:103], v[20:21], off
	v_lshl_add_u64 v[22:23], v[22:23], 0, v[26:27]
	v_lshl_add_u64 v[20:21], v[20:21], 0, v[26:27]
	s_waitcnt vmcnt(14)
	v_lshlrev_b32_e32 v28, 16, v40
	v_and_b32_e32 v29, 0xffff0000, v40
	v_mul_f32_e32 v30, 0x3fb8aa3b, v28
	v_mul_f32_e32 v31, 0x3fb8aa3b, v29
	v_exp_f32_e32 v30, v30
	v_exp_f32_e32 v31, v31
	v_add_f32_e32 v14, v14, v28
	v_add_f32_e32 v15, v15, v29
	v_lshlrev_b32_e32 v28, 16, v44
	v_and_b32_e32 v29, 0xffff0000, v44
	v_fma_f32 v6, v6, v30, v28
	v_fma_f32 v7, v7, v31, v29
	v_lshlrev_b32_e32 v32, 16, v41
	v_and_b32_e32 v33, 0xffff0000, v41
	v_mul_f32_e32 v34, 0x3fb8aa3b, v32
	v_mul_f32_e32 v35, 0x3fb8aa3b, v33
	v_exp_f32_e32 v34, v34
	v_exp_f32_e32 v35, v35
	v_add_f32_e32 v16, v16, v32
	v_add_f32_e32 v17, v17, v33
	v_lshlrev_b32_e32 v32, 16, v45
	v_and_b32_e32 v33, 0xffff0000, v45
	v_fma_f32 v8, v8, v34, v32
	v_fma_f32 v9, v9, v35, v33
	v_lshlrev_b32_e32 v28, 16, v42
	v_and_b32_e32 v29, 0xffff0000, v42
	v_mul_f32_e32 v30, 0x3fb8aa3b, v28
	v_mul_f32_e32 v31, 0x3fb8aa3b, v29
	v_exp_f32_e32 v30, v30
	v_exp_f32_e32 v31, v31
	v_add_f32_e32 v10, v10, v28
	v_add_f32_e32 v11, v11, v29
	v_lshlrev_b32_e32 v28, 16, v46
	v_and_b32_e32 v29, 0xffff0000, v46
	v_fma_f32 v2, v2, v30, v28
	v_fma_f32 v3, v3, v31, v29
	v_lshlrev_b32_e32 v32, 16, v43
	v_and_b32_e32 v33, 0xffff0000, v43
	v_mul_f32_e32 v34, 0x3fb8aa3b, v32
	v_mul_f32_e32 v35, 0x3fb8aa3b, v33
	v_exp_f32_e32 v34, v34
	v_exp_f32_e32 v35, v35
	v_add_f32_e32 v12, v12, v32
	v_add_f32_e32 v13, v13, v33
	v_lshlrev_b32_e32 v32, 16, v47
	v_and_b32_e32 v33, 0xffff0000, v47
	v_fma_f32 v4, v4, v34, v32
	v_fma_f32 v5, v5, v35, v33
	s_waitcnt vmcnt(12)
	v_lshlrev_b32_e32 v28, 16, v48
	v_and_b32_e32 v29, 0xffff0000, v48
	v_mul_f32_e32 v30, 0x3fb8aa3b, v28
	v_mul_f32_e32 v31, 0x3fb8aa3b, v29
	v_exp_f32_e32 v30, v30
	v_exp_f32_e32 v31, v31
	v_add_f32_e32 v14, v14, v28
	v_add_f32_e32 v15, v15, v29
	v_lshlrev_b32_e32 v28, 16, v52
	v_and_b32_e32 v29, 0xffff0000, v52
	v_fma_f32 v6, v6, v30, v28
	v_fma_f32 v7, v7, v31, v29
	v_lshlrev_b32_e32 v32, 16, v49
	v_and_b32_e32 v33, 0xffff0000, v49
	v_mul_f32_e32 v34, 0x3fb8aa3b, v32
	v_mul_f32_e32 v35, 0x3fb8aa3b, v33
	v_exp_f32_e32 v34, v34
	v_exp_f32_e32 v35, v35
	v_add_f32_e32 v16, v16, v32
	v_add_f32_e32 v17, v17, v33
	v_lshlrev_b32_e32 v32, 16, v53
	v_and_b32_e32 v33, 0xffff0000, v53
	v_fma_f32 v8, v8, v34, v32
	v_fma_f32 v9, v9, v35, v33
	v_lshlrev_b32_e32 v28, 16, v50
	v_and_b32_e32 v29, 0xffff0000, v50
	v_mul_f32_e32 v30, 0x3fb8aa3b, v28
	v_mul_f32_e32 v31, 0x3fb8aa3b, v29
	v_exp_f32_e32 v30, v30
	v_exp_f32_e32 v31, v31
	v_add_f32_e32 v10, v10, v28
	v_add_f32_e32 v11, v11, v29
	v_lshlrev_b32_e32 v28, 16, v54
	v_and_b32_e32 v29, 0xffff0000, v54
	v_fma_f32 v2, v2, v30, v28
	v_fma_f32 v3, v3, v31, v29
	v_lshlrev_b32_e32 v32, 16, v51
	v_and_b32_e32 v33, 0xffff0000, v51
	v_mul_f32_e32 v34, 0x3fb8aa3b, v32
	v_mul_f32_e32 v35, 0x3fb8aa3b, v33
	v_exp_f32_e32 v34, v34
	v_exp_f32_e32 v35, v35
	v_add_f32_e32 v12, v12, v32
	v_add_f32_e32 v13, v13, v33
	v_lshlrev_b32_e32 v32, 16, v55
	v_and_b32_e32 v33, 0xffff0000, v55
	v_fma_f32 v4, v4, v34, v32
	v_fma_f32 v5, v5, v35, v33
	s_waitcnt vmcnt(10)
	v_lshlrev_b32_e32 v28, 16, v56
	v_and_b32_e32 v29, 0xffff0000, v56
	v_mul_f32_e32 v30, 0x3fb8aa3b, v28
	v_mul_f32_e32 v31, 0x3fb8aa3b, v29
	v_exp_f32_e32 v30, v30
	v_exp_f32_e32 v31, v31
	v_add_f32_e32 v14, v14, v28
	v_add_f32_e32 v15, v15, v29
	v_lshlrev_b32_e32 v28, 16, v60
	v_and_b32_e32 v29, 0xffff0000, v60
	v_fma_f32 v6, v6, v30, v28
	v_fma_f32 v7, v7, v31, v29
	v_lshlrev_b32_e32 v32, 16, v57
	v_and_b32_e32 v33, 0xffff0000, v57
	v_mul_f32_e32 v34, 0x3fb8aa3b, v32
	v_mul_f32_e32 v35, 0x3fb8aa3b, v33
	v_exp_f32_e32 v34, v34
	v_exp_f32_e32 v35, v35
	v_add_f32_e32 v16, v16, v32
	v_add_f32_e32 v17, v17, v33
	v_lshlrev_b32_e32 v32, 16, v61
	v_and_b32_e32 v33, 0xffff0000, v61
	v_fma_f32 v8, v8, v34, v32
	v_fma_f32 v9, v9, v35, v33
	v_lshlrev_b32_e32 v28, 16, v58
	v_and_b32_e32 v29, 0xffff0000, v58
	v_mul_f32_e32 v30, 0x3fb8aa3b, v28
	v_mul_f32_e32 v31, 0x3fb8aa3b, v29
	v_exp_f32_e32 v30, v30
	v_exp_f32_e32 v31, v31
	v_add_f32_e32 v10, v10, v28
	v_add_f32_e32 v11, v11, v29
	v_lshlrev_b32_e32 v28, 16, v62
	v_and_b32_e32 v29, 0xffff0000, v62
	v_fma_f32 v2, v2, v30, v28
	v_fma_f32 v3, v3, v31, v29
	v_lshlrev_b32_e32 v32, 16, v59
	v_and_b32_e32 v33, 0xffff0000, v59
	v_mul_f32_e32 v34, 0x3fb8aa3b, v32
	v_mul_f32_e32 v35, 0x3fb8aa3b, v33
	v_exp_f32_e32 v34, v34
	v_exp_f32_e32 v35, v35
	v_add_f32_e32 v12, v12, v32
	v_add_f32_e32 v13, v13, v33
	v_lshlrev_b32_e32 v32, 16, v63
	v_and_b32_e32 v33, 0xffff0000, v63
	v_fma_f32 v4, v4, v34, v32
	v_fma_f32 v5, v5, v35, v33
	s_waitcnt vmcnt(8)
; DI void unpack8(const u32x4 v, float* f) { f[0] = bf_lo(v.x); f[1] = bf_hi(v.x); f[2] = bf_lo(v.y); f[3] = bf_hi(v.y); f[4] = bf_lo(v.z); f[5] = bf_hi(v.z); f[6] = bf_lo(v.w); f[7] = bf_hi(v.w); }
; DI void phase_scan1(const bf16_t* la, const bf16_t* bb, float* asum, float* hend) {
;     ...
;     for (int t = 0; t < 32; ++t) {
;       float l[8], bv[8]; unpack8(*(const u32x4*)(la + base + (size_t)t * DM), l); unpack8(*(const u32x4*)(bb + base + (size_t)t * DM), bv);
; #pragma unroll
;       for (int e = 0; e < 8; ++e) { h[e] = __expf(l[e]) * h[e] + bv[e]; as[e] += l[e]; }
	v_lshlrev_b32_e32 v28, 16, v64
	v_and_b32_e32 v29, 0xffff0000, v64
	v_mul_f32_e32 v30, 0x3fb8aa3b, v28
	v_mul_f32_e32 v31, 0x3fb8aa3b, v29
	v_exp_f32_e32 v30, v30
	v_exp_f32_e32 v31, v31
	v_add_f32_e32 v14, v14, v28
	v_add_f32_e32 v15, v15, v29
	v_lshlrev_b32_e32 v28, 16, v68
	v_and_b32_e32 v29, 0xffff0000, v68
	v_fma_f32 v6, v6, v30, v28
	v_fma_f32 v7, v7, v31, v29
	v_lshlrev_b32_e32 v32, 16, v65
	v_and_b32_e32 v33, 0xffff0000, v65
	v_mul_f32_e32 v34, 0x3fb8aa3b, v32
	v_mul_f32_e32 v35, 0x3fb8aa3b, v33
	v_exp_f32_e32 v34, v34
	v_exp_f32_e32 v35, v35
	v_add_f32_e32 v16, v16, v32
	v_add_f32_e32 v17, v17, v33
	v_lshlrev_b32_e32 v32, 16, v69
	v_and_b32_e32 v33, 0xffff0000, v69
	v_fma_f32 v8, v8, v34, v32
	v_fma_f32 v9, v9, v35, v33
	v_lshlrev_b32_e32 v28, 16, v66
	v_and_b32_e32 v29, 0xffff0000, v66
	v_mul_f32_e32 v30, 0x3fb8aa3b, v28
	v_mul_f32_e32 v31, 0x3fb8aa3b, v29
	v_exp_f32_e32 v30, v30
	v_exp_f32_e32 v31, v31
	v_add_f32_e32 v10, v10, v28
	v_add_f32_e32 v11, v11, v29
	v_lshlrev_b32_e32 v28, 16, v70
	v_and_b32_e32 v29, 0xffff0000, v70
	v_fma_f32 v2, v2, v30, v28
	v_fma_f32 v3, v3, v31, v29
	v_lshlrev_b32_e32 v32, 16, v67
	v_and_b32_e32 v33, 0xffff0000, v67
	v_mul_f32_e32 v34, 0x3fb8aa3b, v32
	v_mul_f32_e32 v35, 0x3fb8aa3b, v33
	v_exp_f32_e32 v34, v34
	v_exp_f32_e32 v35, v35
	v_add_f32_e32 v12, v12, v32
	v_add_f32_e32 v13, v13, v33
	v_lshlrev_b32_e32 v32, 16, v71
	v_and_b32_e32 v33, 0xffff0000, v71
	v_fma_f32 v4, v4, v34, v32
	v_fma_f32 v5, v5, v35, v33
	global_load_dwordx4 v[40:43], v[22:23], off
	global_load_dwordx4 v[44:47], v[20:21], off
	v_lshl_add_u64 v[22:23], v[22:23], 0, v[26:27]
	v_lshl_add_u64 v[20:21], v[20:21], 0, v[26:27]
	global_load_dwordx4 v[48:51], v[22:23], off
	global_load_dwordx4 v[52:55], v[20:21], off
	v_lshl_add_u64 v[22:23], v[22:23], 0, v[26:27]
	v_lshl_add_u64 v[20:21], v[20:21], 0, v[26:27]
	global_load_dwordx4 v[56:59], v[22:23], off
	global_load_dwordx4 v[60:63], v[20:21], off
	v_lshl_add_u64 v[22:23], v[22:23], 0, v[26:27]
	v_lshl_add_u64 v[20:21], v[20:21], 0, v[26:27]
	global_load_dwordx4 v[64:67], v[22:23], off
	global_load_dwordx4 v[68:71], v[20:21], off
	v_lshl_add_u64 v[22:23], v[22:23], 0, v[26:27]
	v_lshl_add_u64 v[20:21], v[20:21], 0, v[26:27]
	s_waitcnt vmcnt(14)
	v_lshlrev_b32_e32 v28, 16, v72
	v_and_b32_e32 v29, 0xffff0000, v72
	v_mul_f32_e32 v30, 0x3fb8aa3b, v28
	v_mul_f32_e32 v31, 0x3fb8aa3b, v29
	v_exp_f32_e32 v30, v30
	v_exp_f32_e32 v31, v31
	v_add_f32_e32 v14, v14, v28
	v_add_f32_e32 v15, v15, v29
	v_lshlrev_b32_e32 v28, 16, v76
	v_and_b32_e32 v29, 0xffff0000, v76
	v_fma_f32 v6, v6, v30, v28
	v_fma_f32 v7, v7, v31, v29
	v_lshlrev_b32_e32 v32, 16, v73
	v_and_b32_e32 v33, 0xffff0000, v73
	v_mul_f32_e32 v34, 0x3fb8aa3b, v32
	v_mul_f32_e32 v35, 0x3fb8aa3b, v33
	v_exp_f32_e32 v34, v34
	v_exp_f32_e32 v35, v35
	v_add_f32_e32 v16, v16, v32
	v_add_f32_e32 v17, v17, v33
	v_lshlrev_b32_e32 v32, 16, v77
	v_and_b32_e32 v33, 0xffff0000, v77
	v_fma_f32 v8, v8, v34, v32
	v_fma_f32 v9, v9, v35, v33
	v_lshlrev_b32_e32 v28, 16, v74
	v_and_b32_e32 v29, 0xffff0000, v74
	v_mul_f32_e32 v30, 0x3fb8aa3b, v28
	v_mul_f32_e32 v31, 0x3fb8aa3b, v29
	v_exp_f32_e32 v30, v30
	v_exp_f32_e32 v31, v31
	v_add_f32_e32 v10, v10, v28
	v_add_f32_e32 v11, v11, v29
	v_lshlrev_b32_e32 v28, 16, v78
	v_and_b32_e32 v29, 0xffff0000, v78
	v_fma_f32 v2, v2, v30, v28
	v_fma_f32 v3, v3, v31, v29
	v_lshlrev_b32_e32 v32, 16, v75
	v_and_b32_e32 v33, 0xffff0000, v75
	v_mul_f32_e32 v34, 0x3fb8aa3b, v32
	v_mul_f32_e32 v35, 0x3fb8aa3b, v33
	v_exp_f32_e32 v34, v34
	v_exp_f32_e32 v35, v35
	v_add_f32_e32 v12, v12, v32
	v_add_f32_e32 v13, v13, v33
	v_lshlrev_b32_e32 v32, 16, v79
	v_and_b32_e32 v33, 0xffff0000, v79
	v_fma_f32 v4, v4, v34, v32
	v_fma_f32 v5, v5, v35, v33
	s_waitcnt vmcnt(12)
	v_lshlrev_b32_e32 v28, 16, v80
	v_and_b32_e32 v29, 0xffff0000, v80
	v_mul_f32_e32 v30, 0x3fb8aa3b, v28
	v_mul_f32_e32 v31, 0x3fb8aa3b, v29
	v_exp_f32_e32 v30, v30
	v_exp_f32_e32 v31, v31
	v_add_f32_e32 v14, v14, v28
	v_add_f32_e32 v15, v15, v29
	v_lshlrev_b32_e32 v28, 16, v84
	v_and_b32_e32 v29, 0xffff0000, v84
	v_fma_f32 v6, v6, v30, v28
	v_fma_f32 v7, v7, v31, v29
	v_lshlrev_b32_e32 v32, 16, v81
	v_and_b32_e32 v33, 0xffff0000, v81
	v_mul_f32_e32 v34, 0x3fb8aa3b, v32
	v_mul_f32_e32 v35, 0x3fb8aa3b, v33
	v_exp_f32_e32 v34, v34
	v_exp_f32_e32 v35, v35
	v_add_f32_e32 v16, v16, v32
	v_add_f32_e32 v17, v17, v33
	v_lshlrev_b32_e32 v32, 16, v85
	v_and_b32_e32 v33, 0xffff0000, v85
	v_fma_f32 v8, v8, v34, v32
	v_fma_f32 v9, v9, v35, v33
	v_lshlrev_b32_e32 v28, 16, v82
	v_and_b32_e32 v29, 0xffff0000, v82
	v_mul_f32_e32 v30, 0x3fb8aa3b, v28
	v_mul_f32_e32 v31, 0x3fb8aa3b, v29
	v_exp_f32_e32 v30, v30
	v_exp_f32_e32 v31, v31
	v_add_f32_e32 v10, v10, v28
	v_add_f32_e32 v11, v11, v29
	v_lshlrev_b32_e32 v28, 16, v86
	v_and_b32_e32 v29, 0xffff0000, v86
	v_fma_f32 v2, v2, v30, v28
	v_fma_f32 v3, v3, v31, v29
	v_lshlrev_b32_e32 v32, 16, v83
	v_and_b32_e32 v33, 0xffff0000, v83
	v_mul_f32_e32 v34, 0x3fb8aa3b, v32
	v_mul_f32_e32 v35, 0x3fb8aa3b, v33
	v_exp_f32_e32 v34, v34
	v_exp_f32_e32 v35, v35
	v_add_f32_e32 v12, v12, v32
	v_add_f32_e32 v13, v13, v33
	v_lshlrev_b32_e32 v32, 16, v87
	v_and_b32_e32 v33, 0xffff0000, v87
	v_fma_f32 v4, v4, v34, v32
	v_fma_f32 v5, v5, v35, v33
	s_waitcnt vmcnt(10)
; DI void unpack8(const u32x4 v, float* f) { f[0] = bf_lo(v.x); f[1] = bf_hi(v.x); f[2] = bf_lo(v.y); f[3] = bf_hi(v.y); f[4] = bf_lo(v.z); f[5] = bf_hi(v.z); f[6] = bf_lo(v.w); f[7] = bf_hi(v.w); }
; DI void phase_scan1(const bf16_t* la, const bf16_t* bb, float* asum, float* hend) {
;     ...
;     for (int t = 0; t < 32; ++t) {
;       float l[8], bv[8]; unpack8(*(const u32x4*)(la + base + (size_t)t * DM), l); unpack8(*(const u32x4*)(bb + base + (size_t)t * DM), bv);
; #pragma unroll
;       for (int e = 0; e < 8; ++e) { h[e] = __expf(l[e]) * h[e] + bv[e]; as[e] += l[e]; }
	v_lshlrev_b32_e32 v28, 16, v88
	v_and_b32_e32 v29, 0xffff0000, v88
	v_mul_f32_e32 v30, 0x3fb8aa3b, v28
	v_mul_f32_e32 v31, 0x3fb8aa3b, v29
	v_exp_f32_e32 v30, v30
	v_exp_f32_e32 v31, v31
	v_add_f32_e32 v14, v14, v28
	v_add_f32_e32 v15, v15, v29
	v_lshlrev_b32_e32 v28, 16, v92
	v_and_b32_e32 v29, 0xffff0000, v92
	v_fma_f32 v6, v6, v30, v28
	v_fma_f32 v7, v7, v31, v29
	v_lshlrev_b32_e32 v32, 16, v89
	v_and_b32_e32 v33, 0xffff0000, v89
	v_mul_f32_e32 v34, 0x3fb8aa3b, v32
	v_mul_f32_e32 v35, 0x3fb8aa3b, v33
	v_exp_f32_e32 v34, v34
	v_exp_f32_e32 v35, v35
	v_add_f32_e32 v16, v16, v32
	v_add_f32_e32 v17, v17, v33
	v_lshlrev_b32_e32 v32, 16, v93
	v_and_b32_e32 v33, 0xffff0000, v93
	v_fma_f32 v8, v8, v34, v32
	v_fma_f32 v9, v9, v35, v33
	v_lshlrev_b32_e32 v28, 16, v90
	v_and_b32_e32 v29, 0xffff0000, v90
	v_mul_f32_e32 v30, 0x3fb8aa3b, v28
	v_mul_f32_e32 v31, 0x3fb8aa3b, v29
	v_exp_f32_e32 v30, v30
	v_exp_f32_e32 v31, v31
	v_add_f32_e32 v10, v10, v28
	v_add_f32_e32 v11, v11, v29
	v_lshlrev_b32_e32 v28, 16, v94
	v_and_b32_e32 v29, 0xffff0000, v94
	v_fma_f32 v2, v2, v30, v28
	v_fma_f32 v3, v3, v31, v29
	v_lshlrev_b32_e32 v32, 16, v91
	v_and_b32_e32 v33, 0xffff0000, v91
	v_mul_f32_e32 v34, 0x3fb8aa3b, v32
	v_mul_f32_e32 v35, 0x3fb8aa3b, v33
	v_exp_f32_e32 v34, v34
	v_exp_f32_e32 v35, v35
	v_add_f32_e32 v12, v12, v32
	v_add_f32_e32 v13, v13, v33
	v_lshlrev_b32_e32 v32, 16, v95
	v_and_b32_e32 v33, 0xffff0000, v95
	v_fma_f32 v4, v4, v34, v32
	v_fma_f32 v5, v5, v35, v33
	s_waitcnt vmcnt(8)
	v_lshlrev_b32_e32 v28, 16, v96
	v_and_b32_e32 v29, 0xffff0000, v96
	v_mul_f32_e32 v30, 0x3fb8aa3b, v28
	v_mul_f32_e32 v31, 0x3fb8aa3b, v29
	v_exp_f32_e32 v30, v30
	v_exp_f32_e32 v31, v31
	v_add_f32_e32 v14, v14, v28
	v_add_f32_e32 v15, v15, v29
	v_lshlrev_b32_e32 v28, 16, v100
	v_and_b32_e32 v29, 0xffff0000, v100
	v_fma_f32 v6, v6, v30, v28
	v_fma_f32 v7, v7, v31, v29
	v_lshlrev_b32_e32 v32, 16, v97
	v_and_b32_e32 v33, 0xffff0000, v97
	v_mul_f32_e32 v34, 0x3fb8aa3b, v32
	v_mul_f32_e32 v35, 0x3fb8aa3b, v33
	v_exp_f32_e32 v34, v34
	v_exp_f32_e32 v35, v35
	v_add_f32_e32 v16, v16, v32
	v_add_f32_e32 v17, v17, v33
	v_lshlrev_b32_e32 v32, 16, v101
	v_and_b32_e32 v33, 0xffff0000, v101
	v_fma_f32 v8, v8, v34, v32
	v_fma_f32 v9, v9, v35, v33
	v_lshlrev_b32_e32 v28, 16, v98
	v_and_b32_e32 v29, 0xffff0000, v98
	v_mul_f32_e32 v30, 0x3fb8aa3b, v28
	v_mul_f32_e32 v31, 0x3fb8aa3b, v29
	v_exp_f32_e32 v30, v30
	v_exp_f32_e32 v31, v31
	v_add_f32_e32 v10, v10, v28
	v_add_f32_e32 v11, v11, v29
	v_lshlrev_b32_e32 v28, 16, v102
	v_and_b32_e32 v29, 0xffff0000, v102
	v_fma_f32 v2, v2, v30, v28
	v_fma_f32 v3, v3, v31, v29
	v_lshlrev_b32_e32 v32, 16, v99
	v_and_b32_e32 v33, 0xffff0000, v99
	v_mul_f32_e32 v34, 0x3fb8aa3b, v32
	v_mul_f32_e32 v35, 0x3fb8aa3b, v33
	v_exp_f32_e32 v34, v34
	v_exp_f32_e32 v35, v35
	v_add_f32_e32 v12, v12, v32
	v_add_f32_e32 v13, v13, v33
	v_lshlrev_b32_e32 v32, 16, v103
	v_and_b32_e32 v33, 0xffff0000, v103
	v_fma_f32 v4, v4, v34, v32
	v_fma_f32 v5, v5, v35, v33
	global_load_dwordx4 v[72:75], v[22:23], off
	global_load_dwordx4 v[76:79], v[20:21], off
	v_lshl_add_u64 v[22:23], v[22:23], 0, v[26:27]
	v_lshl_add_u64 v[20:21], v[20:21], 0, v[26:27]
	global_load_dwordx4 v[80:83], v[22:23], off
	global_load_dwordx4 v[84:87], v[20:21], off
	v_lshl_add_u64 v[22:23], v[22:23], 0, v[26:27]
	v_lshl_add_u64 v[20:21], v[20:21], 0, v[26:27]
	global_load_dwordx4 v[88:91], v[22:23], off
	global_load_dwordx4 v[92:95], v[20:21], off
	v_lshl_add_u64 v[22:23], v[22:23], 0, v[26:27]
	v_lshl_add_u64 v[20:21], v[20:21], 0, v[26:27]
	global_load_dwordx4 v[96:99], v[22:23], off
	global_load_dwordx4 v[100:103], v[20:21], off
	v_lshl_add_u64 v[22:23], v[22:23], 0, v[26:27]
	v_lshl_add_u64 v[20:21], v[20:21], 0, v[26:27]
	s_waitcnt vmcnt(14)
	v_lshlrev_b32_e32 v28, 16, v40
	v_and_b32_e32 v29, 0xffff0000, v40
	v_mul_f32_e32 v30, 0x3fb8aa3b, v28
	v_mul_f32_e32 v31, 0x3fb8aa3b, v29
	v_exp_f32_e32 v30, v30
	v_exp_f32_e32 v31, v31
	v_add_f32_e32 v14, v14, v28
	v_add_f32_e32 v15, v15, v29
	v_lshlrev_b32_e32 v28, 16, v44
	v_and_b32_e32 v29, 0xffff0000, v44
	v_fma_f32 v6, v6, v30, v28
	v_fma_f32 v7, v7, v31, v29
	v_lshlrev_b32_e32 v32, 16, v41
	v_and_b32_e32 v33, 0xffff0000, v41
	v_mul_f32_e32 v34, 0x3fb8aa3b, v32
	v_mul_f32_e32 v35, 0x3fb8aa3b, v33
	v_exp_f32_e32 v34, v34
	v_exp_f32_e32 v35, v35
	v_add_f32_e32 v16, v16, v32
	v_add_f32_e32 v17, v17, v33
	v_lshlrev_b32_e32 v32, 16, v45
	v_and_b32_e32 v33, 0xffff0000, v45
	v_fma_f32 v8, v8, v34, v32
	v_fma_f32 v9, v9, v35, v33
	v_lshlrev_b32_e32 v28, 16, v42
	v_and_b32_e32 v29, 0xffff0000, v42
	v_mul_f32_e32 v30, 0x3fb8aa3b, v28
	v_mul_f32_e32 v31, 0x3fb8aa3b, v29
	v_exp_f32_e32 v30, v30
	v_exp_f32_e32 v31, v31
	v_add_f32_e32 v10, v10, v28
	v_add_f32_e32 v11, v11, v29
	v_lshlrev_b32_e32 v28, 16, v46
	v_and_b32_e32 v29, 0xffff0000, v46
	v_fma_f32 v2, v2, v30, v28
	v_fma_f32 v3, v3, v31, v29
	v_lshlrev_b32_e32 v32, 16, v43
	v_and_b32_e32 v33, 0xffff0000, v43
	v_mul_f32_e32 v34, 0x3fb8aa3b, v32
	v_mul_f32_e32 v35, 0x3fb8aa3b, v33
	v_exp_f32_e32 v34, v34
	v_exp_f32_e32 v35, v35
	v_add_f32_e32 v12, v12, v32
	v_add_f32_e32 v13, v13, v33
	v_lshlrev_b32_e32 v32, 16, v47
	v_and_b32_e32 v33, 0xffff0000, v47
	v_fma_f32 v4, v4, v34, v32
	v_fma_f32 v5, v5, v35, v33
	s_waitcnt vmcnt(12)
; DI void unpack8(const u32x4 v, float* f) { f[0] = bf_lo(v.x); f[1] = bf_hi(v.x); f[2] = bf_lo(v.y); f[3] = bf_hi(v.y); f[4] = bf_lo(v.z); f[5] = bf_hi(v.z); f[6] = bf_lo(v.w); f[7] = bf_hi(v.w); }
; DI void phase_scan1(const bf16_t* la, const bf16_t* bb, float* asum, float* hend) {
;     ...
;     for (int t = 0; t < 32; ++t) {
;       float l[8], bv[8]; unpack8(*(const u32x4*)(la + base + (size_t)t * DM), l); unpack8(*(const u32x4*)(bb + base + (size_t)t * DM), bv);
; #pragma unroll
;       for (int e = 0; e < 8; ++e) { h[e] = __expf(l[e]) * h[e] + bv[e]; as[e] += l[e]; }
	v_lshlrev_b32_e32 v28, 16, v48
	v_and_b32_e32 v29, 0xffff0000, v48
	v_mul_f32_e32 v30, 0x3fb8aa3b, v28
	v_mul_f32_e32 v31, 0x3fb8aa3b, v29
	v_exp_f32_e32 v30, v30
	v_exp_f32_e32 v31, v31
	v_add_f32_e32 v14, v14, v28
	v_add_f32_e32 v15, v15, v29
	v_lshlrev_b32_e32 v28, 16, v52
	v_and_b32_e32 v29, 0xffff0000, v52
	v_fma_f32 v6, v6, v30, v28
	v_fma_f32 v7, v7, v31, v29
	v_lshlrev_b32_e32 v32, 16, v49
	v_and_b32_e32 v33, 0xffff0000, v49
	v_mul_f32_e32 v34, 0x3fb8aa3b, v32
	v_mul_f32_e32 v35, 0x3fb8aa3b, v33
	v_exp_f32_e32 v34, v34
	v_exp_f32_e32 v35, v35
	v_add_f32_e32 v16, v16, v32
	v_add_f32_e32 v17, v17, v33
	v_lshlrev_b32_e32 v32, 16, v53
	v_and_b32_e32 v33, 0xffff0000, v53
	v_fma_f32 v8, v8, v34, v32
	v_fma_f32 v9, v9, v35, v33
	v_lshlrev_b32_e32 v28, 16, v50
	v_and_b32_e32 v29, 0xffff0000, v50
	v_mul_f32_e32 v30, 0x3fb8aa3b, v28
	v_mul_f32_e32 v31, 0x3fb8aa3b, v29
	v_exp_f32_e32 v30, v30
	v_exp_f32_e32 v31, v31
	v_add_f32_e32 v10, v10, v28
	v_add_f32_e32 v11, v11, v29
	v_lshlrev_b32_e32 v28, 16, v54
	v_and_b32_e32 v29, 0xffff0000, v54
	v_fma_f32 v2, v2, v30, v28
	v_fma_f32 v3, v3, v31, v29
	v_lshlrev_b32_e32 v32, 16, v51
	v_and_b32_e32 v33, 0xffff0000, v51
	v_mul_f32_e32 v34, 0x3fb8aa3b, v32
	v_mul_f32_e32 v35, 0x3fb8aa3b, v33
	v_exp_f32_e32 v34, v34
	v_exp_f32_e32 v35, v35
	v_add_f32_e32 v12, v12, v32
	v_add_f32_e32 v13, v13, v33
	v_lshlrev_b32_e32 v32, 16, v55
	v_and_b32_e32 v33, 0xffff0000, v55
	v_fma_f32 v4, v4, v34, v32
	v_fma_f32 v5, v5, v35, v33
	s_waitcnt vmcnt(10)
	v_lshlrev_b32_e32 v28, 16, v56
	v_and_b32_e32 v29, 0xffff0000, v56
	v_mul_f32_e32 v30, 0x3fb8aa3b, v28
	v_mul_f32_e32 v31, 0x3fb8aa3b, v29
	v_exp_f32_e32 v30, v30
	v_exp_f32_e32 v31, v31
	v_add_f32_e32 v14, v14, v28
	v_add_f32_e32 v15, v15, v29
	v_lshlrev_b32_e32 v28, 16, v60
	v_and_b32_e32 v29, 0xffff0000, v60
	v_fma_f32 v6, v6, v30, v28
	v_fma_f32 v7, v7, v31, v29
	v_lshlrev_b32_e32 v32, 16, v57
	v_and_b32_e32 v33, 0xffff0000, v57
	v_mul_f32_e32 v34, 0x3fb8aa3b, v32
	v_mul_f32_e32 v35, 0x3fb8aa3b, v33
	v_exp_f32_e32 v34, v34
	v_exp_f32_e32 v35, v35
	v_add_f32_e32 v16, v16, v32
	v_add_f32_e32 v17, v17, v33
	v_lshlrev_b32_e32 v32, 16, v61
	v_and_b32_e32 v33, 0xffff0000, v61
	v_fma_f32 v8, v8, v34, v32
	v_fma_f32 v9, v9, v35, v33
	v_lshlrev_b32_e32 v28, 16, v58
	v_and_b32_e32 v29, 0xffff0000, v58
	v_mul_f32_e32 v30, 0x3fb8aa3b, v28
	v_mul_f32_e32 v31, 0x3fb8aa3b, v29
	v_exp_f32_e32 v30, v30
	v_exp_f32_e32 v31, v31
	v_add_f32_e32 v10, v10, v28
	v_add_f32_e32 v11, v11, v29
	v_lshlrev_b32_e32 v28, 16, v62
	v_and_b32_e32 v29, 0xffff0000, v62
	v_fma_f32 v2, v2, v30, v28
	v_fma_f32 v3, v3, v31, v29
	v_lshlrev_b32_e32 v32, 16, v59
	v_and_b32_e32 v33, 0xffff0000, v59
	v_mul_f32_e32 v34, 0x3fb8aa3b, v32
	v_mul_f32_e32 v35, 0x3fb8aa3b, v33
	v_exp_f32_e32 v34, v34
	v_exp_f32_e32 v35, v35
	v_add_f32_e32 v12, v12, v32
	v_add_f32_e32 v13, v13, v33
	v_lshlrev_b32_e32 v32, 16, v63
	v_and_b32_e32 v33, 0xffff0000, v63
	v_fma_f32 v4, v4, v34, v32
	v_fma_f32 v5, v5, v35, v33
	s_waitcnt vmcnt(8)
	v_lshlrev_b32_e32 v28, 16, v64
	v_and_b32_e32 v29, 0xffff0000, v64
	v_mul_f32_e32 v30, 0x3fb8aa3b, v28
	v_mul_f32_e32 v31, 0x3fb8aa3b, v29
	v_exp_f32_e32 v30, v30
	v_exp_f32_e32 v31, v31
	v_add_f32_e32 v14, v14, v28
	v_add_f32_e32 v15, v15, v29
	v_lshlrev_b32_e32 v28, 16, v68
	v_and_b32_e32 v29, 0xffff0000, v68
	v_fma_f32 v6, v6, v30, v28
	v_fma_f32 v7, v7, v31, v29
	v_lshlrev_b32_e32 v32, 16, v65
	v_and_b32_e32 v33, 0xffff0000, v65
	v_mul_f32_e32 v34, 0x3fb8aa3b, v32
	v_mul_f32_e32 v35, 0x3fb8aa3b, v33
	v_exp_f32_e32 v34, v34
	v_exp_f32_e32 v35, v35
	v_add_f32_e32 v16, v16, v32
	v_add_f32_e32 v17, v17, v33
	v_lshlrev_b32_e32 v32, 16, v69
	v_and_b32_e32 v33, 0xffff0000, v69
	v_fma_f32 v8, v8, v34, v32
	v_fma_f32 v9, v9, v35, v33
	v_lshlrev_b32_e32 v28, 16, v66
	v_and_b32_e32 v29, 0xffff0000, v66
	v_mul_f32_e32 v30, 0x3fb8aa3b, v28
	v_mul_f32_e32 v31, 0x3fb8aa3b, v29
	v_exp_f32_e32 v30, v30
	v_exp_f32_e32 v31, v31
	v_add_f32_e32 v10, v10, v28
	v_add_f32_e32 v11, v11, v29
	v_lshlrev_b32_e32 v28, 16, v70
	v_and_b32_e32 v29, 0xffff0000, v70
	v_fma_f32 v2, v2, v30, v28
	v_fma_f32 v3, v3, v31, v29
	v_lshlrev_b32_e32 v32, 16, v67
	v_and_b32_e32 v33, 0xffff0000, v67
	v_mul_f32_e32 v34, 0x3fb8aa3b, v32
	v_mul_f32_e32 v35, 0x3fb8aa3b, v33
	v_exp_f32_e32 v34, v34
	v_exp_f32_e32 v35, v35
	v_add_f32_e32 v12, v12, v32
	v_add_f32_e32 v13, v13, v33
	v_lshlrev_b32_e32 v32, 16, v71
	v_and_b32_e32 v33, 0xffff0000, v71
	v_fma_f32 v4, v4, v34, v32
	v_fma_f32 v5, v5, v35, v33
	global_load_dwordx4 v[40:43], v[22:23], off
	global_load_dwordx4 v[44:47], v[20:21], off
	v_lshl_add_u64 v[22:23], v[22:23], 0, v[26:27]
	v_lshl_add_u64 v[20:21], v[20:21], 0, v[26:27]
	global_load_dwordx4 v[48:51], v[22:23], off
	global_load_dwordx4 v[52:55], v[20:21], off
	v_lshl_add_u64 v[22:23], v[22:23], 0, v[26:27]
	v_lshl_add_u64 v[20:21], v[20:21], 0, v[26:27]
	global_load_dwordx4 v[56:59], v[22:23], off
	global_load_dwordx4 v[60:63], v[20:21], off
	v_lshl_add_u64 v[22:23], v[22:23], 0, v[26:27]
	v_lshl_add_u64 v[20:21], v[20:21], 0, v[26:27]
	global_load_dwordx4 v[64:67], v[22:23], off
	global_load_dwordx4 v[68:71], v[20:21], off
	v_lshl_add_u64 v[22:23], v[22:23], 0, v[26:27]
	v_lshl_add_u64 v[20:21], v[20:21], 0, v[26:27]
	s_waitcnt vmcnt(14)
; DI void unpack8(const u32x4 v, float* f) { f[0] = bf_lo(v.x); f[1] = bf_hi(v.x); f[2] = bf_lo(v.y); f[3] = bf_hi(v.y); f[4] = bf_lo(v.z); f[5] = bf_hi(v.z); f[6] = bf_lo(v.w); f[7] = bf_hi(v.w); }
; DI void phase_scan1(const bf16_t* la, const bf16_t* bb, float* asum, float* hend) {
;     ...
;     for (int t = 0; t < 32; ++t) {
;       float l[8], bv[8]; unpack8(*(const u32x4*)(la + base + (size_t)t * DM), l); unpack8(*(const u32x4*)(bb + base + (size_t)t * DM), bv);
; #pragma unroll
;       for (int e = 0; e < 8; ++e) { h[e] = __expf(l[e]) * h[e] + bv[e]; as[e] += l[e]; }
	v_lshlrev_b32_e32 v28, 16, v72
	v_and_b32_e32 v29, 0xffff0000, v72
	v_mul_f32_e32 v30, 0x3fb8aa3b, v28
	v_mul_f32_e32 v31, 0x3fb8aa3b, v29
	v_exp_f32_e32 v30, v30
	v_exp_f32_e32 v31, v31
	v_add_f32_e32 v14, v14, v28
	v_add_f32_e32 v15, v15, v29
	v_lshlrev_b32_e32 v28, 16, v76
	v_and_b32_e32 v29, 0xffff0000, v76
	v_fma_f32 v6, v6, v30, v28
	v_fma_f32 v7, v7, v31, v29
	v_lshlrev_b32_e32 v32, 16, v73
	v_and_b32_e32 v33, 0xffff0000, v73
	v_mul_f32_e32 v34, 0x3fb8aa3b, v32
	v_mul_f32_e32 v35, 0x3fb8aa3b, v33
	v_exp_f32_e32 v34, v34
	v_exp_f32_e32 v35, v35
	v_add_f32_e32 v16, v16, v32
	v_add_f32_e32 v17, v17, v33
	v_lshlrev_b32_e32 v32, 16, v77
	v_and_b32_e32 v33, 0xffff0000, v77
	v_fma_f32 v8, v8, v34, v32
	v_fma_f32 v9, v9, v35, v33
	v_lshlrev_b32_e32 v28, 16, v74
	v_and_b32_e32 v29, 0xffff0000, v74
	v_mul_f32_e32 v30, 0x3fb8aa3b, v28
	v_mul_f32_e32 v31, 0x3fb8aa3b, v29
	v_exp_f32_e32 v30, v30
	v_exp_f32_e32 v31, v31
	v_add_f32_e32 v10, v10, v28
	v_add_f32_e32 v11, v11, v29
	v_lshlrev_b32_e32 v28, 16, v78
	v_and_b32_e32 v29, 0xffff0000, v78
	v_fma_f32 v2, v2, v30, v28
	v_fma_f32 v3, v3, v31, v29
	v_lshlrev_b32_e32 v32, 16, v75
	v_and_b32_e32 v33, 0xffff0000, v75
	v_mul_f32_e32 v34, 0x3fb8aa3b, v32
	v_mul_f32_e32 v35, 0x3fb8aa3b, v33
	v_exp_f32_e32 v34, v34
	v_exp_f32_e32 v35, v35
	v_add_f32_e32 v12, v12, v32
	v_add_f32_e32 v13, v13, v33
	v_lshlrev_b32_e32 v32, 16, v79
	v_and_b32_e32 v33, 0xffff0000, v79
	v_fma_f32 v4, v4, v34, v32
	v_fma_f32 v5, v5, v35, v33
	s_waitcnt vmcnt(12)
	v_lshlrev_b32_e32 v28, 16, v80
	v_and_b32_e32 v29, 0xffff0000, v80
	v_mul_f32_e32 v30, 0x3fb8aa3b, v28
	v_mul_f32_e32 v31, 0x3fb8aa3b, v29
	v_exp_f32_e32 v30, v30
	v_exp_f32_e32 v31, v31
	v_add_f32_e32 v14, v14, v28
	v_add_f32_e32 v15, v15, v29
	v_lshlrev_b32_e32 v28, 16, v84
	v_and_b32_e32 v29, 0xffff0000, v84
	v_fma_f32 v6, v6, v30, v28
	v_fma_f32 v7, v7, v31, v29
	v_lshlrev_b32_e32 v32, 16, v81
	v_and_b32_e32 v33, 0xffff0000, v81
	v_mul_f32_e32 v34, 0x3fb8aa3b, v32
	v_mul_f32_e32 v35, 0x3fb8aa3b, v33
	v_exp_f32_e32 v34, v34
	v_exp_f32_e32 v35, v35
	v_add_f32_e32 v16, v16, v32
	v_add_f32_e32 v17, v17, v33
	v_lshlrev_b32_e32 v32, 16, v85
	v_and_b32_e32 v33, 0xffff0000, v85
	v_fma_f32 v8, v8, v34, v32
	v_fma_f32 v9, v9, v35, v33
	v_lshlrev_b32_e32 v28, 16, v82
	v_and_b32_e32 v29, 0xffff0000, v82
	v_mul_f32_e32 v30, 0x3fb8aa3b, v28
	v_mul_f32_e32 v31, 0x3fb8aa3b, v29
	v_exp_f32_e32 v30, v30
	v_exp_f32_e32 v31, v31
	v_add_f32_e32 v10, v10, v28
	v_add_f32_e32 v11, v11, v29
	v_lshlrev_b32_e32 v28, 16, v86
	v_and_b32_e32 v29, 0xffff0000, v86
	v_fma_f32 v2, v2, v30, v28
	v_fma_f32 v3, v3, v31, v29
	v_lshlrev_b32_e32 v32, 16, v83
	v_and_b32_e32 v33, 0xffff0000, v83
	v_mul_f32_e32 v34, 0x3fb8aa3b, v32
	v_mul_f32_e32 v35, 0x3fb8aa3b, v33
	v_exp_f32_e32 v34, v34
	v_exp_f32_e32 v35, v35
	v_add_f32_e32 v12, v12, v32
	v_add_f32_e32 v13, v13, v33
	v_lshlrev_b32_e32 v32, 16, v87
	v_and_b32_e32 v33, 0xffff0000, v87
	v_fma_f32 v4, v4, v34, v32
	v_fma_f32 v5, v5, v35, v33
	s_waitcnt vmcnt(10)
	v_lshlrev_b32_e32 v28, 16, v88
	v_and_b32_e32 v29, 0xffff0000, v88
	v_mul_f32_e32 v30, 0x3fb8aa3b, v28
	v_mul_f32_e32 v31, 0x3fb8aa3b, v29
	v_exp_f32_e32 v30, v30
	v_exp_f32_e32 v31, v31
	v_add_f32_e32 v14, v14, v28
	v_add_f32_e32 v15, v15, v29
	v_lshlrev_b32_e32 v28, 16, v92
	v_and_b32_e32 v29, 0xffff0000, v92
	v_fma_f32 v6, v6, v30, v28
	v_fma_f32 v7, v7, v31, v29
	v_lshlrev_b32_e32 v32, 16, v89
	v_and_b32_e32 v33, 0xffff0000, v89
	v_mul_f32_e32 v34, 0x3fb8aa3b, v32
	v_mul_f32_e32 v35, 0x3fb8aa3b, v33
	v_exp_f32_e32 v34, v34
	v_exp_f32_e32 v35, v35
	v_add_f32_e32 v16, v16, v32
	v_add_f32_e32 v17, v17, v33
	v_lshlrev_b32_e32 v32, 16, v93
	v_and_b32_e32 v33, 0xffff0000, v93
	v_fma_f32 v8, v8, v34, v32
	v_fma_f32 v9, v9, v35, v33
	v_lshlrev_b32_e32 v28, 16, v90
	v_and_b32_e32 v29, 0xffff0000, v90
	v_mul_f32_e32 v30, 0x3fb8aa3b, v28
	v_mul_f32_e32 v31, 0x3fb8aa3b, v29
	v_exp_f32_e32 v30, v30
	v_exp_f32_e32 v31, v31
	v_add_f32_e32 v10, v10, v28
	v_add_f32_e32 v11, v11, v29
	v_lshlrev_b32_e32 v28, 16, v94
	v_and_b32_e32 v29, 0xffff0000, v94
	v_fma_f32 v2, v2, v30, v28
	v_fma_f32 v3, v3, v31, v29
	v_lshlrev_b32_e32 v32, 16, v91
	v_and_b32_e32 v33, 0xffff0000, v91
	v_mul_f32_e32 v34, 0x3fb8aa3b, v32
	v_mul_f32_e32 v35, 0x3fb8aa3b, v33
	v_exp_f32_e32 v34, v34
	v_exp_f32_e32 v35, v35
	v_add_f32_e32 v12, v12, v32
	v_add_f32_e32 v13, v13, v33
	v_lshlrev_b32_e32 v32, 16, v95
	v_and_b32_e32 v33, 0xffff0000, v95
	v_fma_f32 v4, v4, v34, v32
	v_fma_f32 v5, v5, v35, v33
	s_waitcnt vmcnt(8)
	v_lshlrev_b32_e32 v28, 16, v96
	v_and_b32_e32 v29, 0xffff0000, v96
	v_mul_f32_e32 v30, 0x3fb8aa3b, v28
	v_mul_f32_e32 v31, 0x3fb8aa3b, v29
	v_exp_f32_e32 v30, v30
	v_exp_f32_e32 v31, v31
	v_add_f32_e32 v14, v14, v28
	v_add_f32_e32 v15, v15, v29
	v_lshlrev_b32_e32 v28, 16, v100
	v_and_b32_e32 v29, 0xffff0000, v100
	v_fma_f32 v6, v6, v30, v28
	v_fma_f32 v7, v7, v31, v29
	v_lshlrev_b32_e32 v32, 16, v97
	v_and_b32_e32 v33, 0xffff0000, v97
	v_mul_f32_e32 v34, 0x3fb8aa3b, v32
	v_mul_f32_e32 v35, 0x3fb8aa3b, v33
	v_exp_f32_e32 v34, v34
	v_exp_f32_e32 v35, v35
	v_add_f32_e32 v16, v16, v32
	v_add_f32_e32 v17, v17, v33
	v_lshlrev_b32_e32 v32, 16, v101
	v_and_b32_e32 v33, 0xffff0000, v101
	v_fma_f32 v8, v8, v34, v32
	v_fma_f32 v9, v9, v35, v33
	v_lshlrev_b32_e32 v28, 16, v98
	v_and_b32_e32 v29, 0xffff0000, v98
	v_mul_f32_e32 v30, 0x3fb8aa3b, v28
	v_mul_f32_e32 v31, 0x3fb8aa3b, v29
	v_exp_f32_e32 v30, v30
	v_exp_f32_e32 v31, v31
	v_add_f32_e32 v10, v10, v28
	v_add_f32_e32 v11, v11, v29
	v_lshlrev_b32_e32 v28, 16, v102
	v_and_b32_e32 v29, 0xffff0000, v102
	v_fma_f32 v2, v2, v30, v28
	v_fma_f32 v3, v3, v31, v29
	v_lshlrev_b32_e32 v32, 16, v99
	v_and_b32_e32 v33, 0xffff0000, v99
	v_mul_f32_e32 v34, 0x3fb8aa3b, v32
	v_mul_f32_e32 v35, 0x3fb8aa3b, v33
	v_exp_f32_e32 v34, v34
	v_exp_f32_e32 v35, v35
	v_add_f32_e32 v12, v12, v32
	v_add_f32_e32 v13, v13, v33
	v_lshlrev_b32_e32 v32, 16, v103
	v_and_b32_e32 v33, 0xffff0000, v103
	v_fma_f32 v4, v4, v34, v32
	v_fma_f32 v5, v5, v35, v33
	global_load_dwordx4 v[72:75], v[22:23], off
	global_load_dwordx4 v[76:79], v[20:21], off
	v_lshl_add_u64 v[22:23], v[22:23], 0, v[26:27]
	v_lshl_add_u64 v[20:21], v[20:21], 0, v[26:27]
	global_load_dwordx4 v[80:83], v[22:23], off
	global_load_dwordx4 v[84:87], v[20:21], off
	v_lshl_add_u64 v[22:23], v[22:23], 0, v[26:27]
	v_lshl_add_u64 v[20:21], v[20:21], 0, v[26:27]
	global_load_dwordx4 v[88:91], v[22:23], off
	global_load_dwordx4 v[92:95], v[20:21], off
	v_lshl_add_u64 v[22:23], v[22:23], 0, v[26:27]
	v_lshl_add_u64 v[20:21], v[20:21], 0, v[26:27]
	global_load_dwordx4 v[96:99], v[22:23], off
	global_load_dwordx4 v[100:103], v[20:21], off
	v_lshl_add_u64 v[22:23], v[22:23], 0, v[26:27]
	v_lshl_add_u64 v[20:21], v[20:21], 0, v[26:27]
	s_waitcnt vmcnt(14)
; DI void unpack8(const u32x4 v, float* f) { f[0] = bf_lo(v.x); f[1] = bf_hi(v.x); f[2] = bf_lo(v.y); f[3] = bf_hi(v.y); f[4] = bf_lo(v.z); f[5] = bf_hi(v.z); f[6] = bf_lo(v.w); f[7] = bf_hi(v.w); }
; DI void phase_scan1(const bf16_t* la, const bf16_t* bb, float* asum, float* hend) {
;     ...
;     for (int t = 0; t < 32; ++t) {
;       float l[8], bv[8]; unpack8(*(const u32x4*)(la + base + (size_t)t * DM), l); unpack8(*(const u32x4*)(bb + base + (size_t)t * DM), bv);
; #pragma unroll
;       for (int e = 0; e < 8; ++e) { h[e] = __expf(l[e]) * h[e] + bv[e]; as[e] += l[e]; }
	v_lshlrev_b32_e32 v28, 16, v40
	v_and_b32_e32 v29, 0xffff0000, v40
	v_mul_f32_e32 v30, 0x3fb8aa3b, v28
	v_mul_f32_e32 v31, 0x3fb8aa3b, v29
	v_exp_f32_e32 v30, v30
	v_exp_f32_e32 v31, v31
	v_add_f32_e32 v14, v14, v28
	v_add_f32_e32 v15, v15, v29
	v_lshlrev_b32_e32 v28, 16, v44
	v_and_b32_e32 v29, 0xffff0000, v44
	v_fma_f32 v6, v6, v30, v28
	v_fma_f32 v7, v7, v31, v29
	v_lshlrev_b32_e32 v32, 16, v41
	v_and_b32_e32 v33, 0xffff0000, v41
	v_mul_f32_e32 v34, 0x3fb8aa3b, v32
	v_mul_f32_e32 v35, 0x3fb8aa3b, v33
	v_exp_f32_e32 v34, v34
	v_exp_f32_e32 v35, v35
	v_add_f32_e32 v16, v16, v32
	v_add_f32_e32 v17, v17, v33
	v_lshlrev_b32_e32 v32, 16, v45
	v_and_b32_e32 v33, 0xffff0000, v45
	v_fma_f32 v8, v8, v34, v32
	v_fma_f32 v9, v9, v35, v33
	v_lshlrev_b32_e32 v28, 16, v42
	v_and_b32_e32 v29, 0xffff0000, v42
	v_mul_f32_e32 v30, 0x3fb8aa3b, v28
	v_mul_f32_e32 v31, 0x3fb8aa3b, v29
	v_exp_f32_e32 v30, v30
	v_exp_f32_e32 v31, v31
	v_add_f32_e32 v10, v10, v28
	v_add_f32_e32 v11, v11, v29
	v_lshlrev_b32_e32 v28, 16, v46
	v_and_b32_e32 v29, 0xffff0000, v46
	v_fma_f32 v2, v2, v30, v28
	v_fma_f32 v3, v3, v31, v29
	v_lshlrev_b32_e32 v32, 16, v43
	v_and_b32_e32 v33, 0xffff0000, v43
	v_mul_f32_e32 v34, 0x3fb8aa3b, v32
	v_mul_f32_e32 v35, 0x3fb8aa3b, v33
	v_exp_f32_e32 v34, v34
	v_exp_f32_e32 v35, v35
	v_add_f32_e32 v12, v12, v32
	v_add_f32_e32 v13, v13, v33
	v_lshlrev_b32_e32 v32, 16, v47
	v_and_b32_e32 v33, 0xffff0000, v47
	v_fma_f32 v4, v4, v34, v32
	v_fma_f32 v5, v5, v35, v33
	s_waitcnt vmcnt(12)
	v_lshlrev_b32_e32 v28, 16, v48
	v_and_b32_e32 v29, 0xffff0000, v48
	v_mul_f32_e32 v30, 0x3fb8aa3b, v28
	v_mul_f32_e32 v31, 0x3fb8aa3b, v29
	v_exp_f32_e32 v30, v30
	v_exp_f32_e32 v31, v31
	v_add_f32_e32 v14, v14, v28
	v_add_f32_e32 v15, v15, v29
	v_lshlrev_b32_e32 v28, 16, v52
	v_and_b32_e32 v29, 0xffff0000, v52
	v_fma_f32 v6, v6, v30, v28
	v_fma_f32 v7, v7, v31, v29
	v_lshlrev_b32_e32 v32, 16, v49
	v_and_b32_e32 v33, 0xffff0000, v49
	v_mul_f32_e32 v34, 0x3fb8aa3b, v32
	v_mul_f32_e32 v35, 0x3fb8aa3b, v33
	v_exp_f32_e32 v34, v34
	v_exp_f32_e32 v35, v35
	v_add_f32_e32 v16, v16, v32
	v_add_f32_e32 v17, v17, v33
	v_lshlrev_b32_e32 v32, 16, v53
	v_and_b32_e32 v33, 0xffff0000, v53
	v_fma_f32 v8, v8, v34, v32
	v_fma_f32 v9, v9, v35, v33
	v_lshlrev_b32_e32 v28, 16, v50
	v_and_b32_e32 v29, 0xffff0000, v50
	v_mul_f32_e32 v30, 0x3fb8aa3b, v28
	v_mul_f32_e32 v31, 0x3fb8aa3b, v29
	v_exp_f32_e32 v30, v30
	v_exp_f32_e32 v31, v31
	v_add_f32_e32 v10, v10, v28
	v_add_f32_e32 v11, v11, v29
	v_lshlrev_b32_e32 v28, 16, v54
	v_and_b32_e32 v29, 0xffff0000, v54
	v_fma_f32 v2, v2, v30, v28
	v_fma_f32 v3, v3, v31, v29
	v_lshlrev_b32_e32 v32, 16, v51
	v_and_b32_e32 v33, 0xffff0000, v51
	v_mul_f32_e32 v34, 0x3fb8aa3b, v32
	v_mul_f32_e32 v35, 0x3fb8aa3b, v33
	v_exp_f32_e32 v34, v34
	v_exp_f32_e32 v35, v35
	v_add_f32_e32 v12, v12, v32
	v_add_f32_e32 v13, v13, v33
	v_lshlrev_b32_e32 v32, 16, v55
	v_and_b32_e32 v33, 0xffff0000, v55
	v_fma_f32 v4, v4, v34, v32
	v_fma_f32 v5, v5, v35, v33
	s_waitcnt vmcnt(10)
	v_lshlrev_b32_e32 v28, 16, v56
	v_and_b32_e32 v29, 0xffff0000, v56
	v_mul_f32_e32 v30, 0x3fb8aa3b, v28
	v_mul_f32_e32 v31, 0x3fb8aa3b, v29
	v_exp_f32_e32 v30, v30
	v_exp_f32_e32 v31, v31
	v_add_f32_e32 v14, v14, v28
	v_add_f32_e32 v15, v15, v29
	v_lshlrev_b32_e32 v28, 16, v60
	v_and_b32_e32 v29, 0xffff0000, v60
	v_fma_f32 v6, v6, v30, v28
	v_fma_f32 v7, v7, v31, v29
	v_lshlrev_b32_e32 v32, 16, v57
	v_and_b32_e32 v33, 0xffff0000, v57
	v_mul_f32_e32 v34, 0x3fb8aa3b, v32
	v_mul_f32_e32 v35, 0x3fb8aa3b, v33
	v_exp_f32_e32 v34, v34
	v_exp_f32_e32 v35, v35
	v_add_f32_e32 v16, v16, v32
	v_add_f32_e32 v17, v17, v33
	v_lshlrev_b32_e32 v32, 16, v61
	v_and_b32_e32 v33, 0xffff0000, v61
	v_fma_f32 v8, v8, v34, v32
	v_fma_f32 v9, v9, v35, v33
	v_lshlrev_b32_e32 v28, 16, v58
	v_and_b32_e32 v29, 0xffff0000, v58
	v_mul_f32_e32 v30, 0x3fb8aa3b, v28
	v_mul_f32_e32 v31, 0x3fb8aa3b, v29
	v_exp_f32_e32 v30, v30
	v_exp_f32_e32 v31, v31
	v_add_f32_e32 v10, v10, v28
	v_add_f32_e32 v11, v11, v29
	v_lshlrev_b32_e32 v28, 16, v62
	v_and_b32_e32 v29, 0xffff0000, v62
	v_fma_f32 v2, v2, v30, v28
	v_fma_f32 v3, v3, v31, v29
	v_lshlrev_b32_e32 v32, 16, v59
	v_and_b32_e32 v33, 0xffff0000, v59
	v_mul_f32_e32 v34, 0x3fb8aa3b, v32
	v_mul_f32_e32 v35, 0x3fb8aa3b, v33
	v_exp_f32_e32 v34, v34
	v_exp_f32_e32 v35, v35
	v_add_f32_e32 v12, v12, v32
	v_add_f32_e32 v13, v13, v33
	v_lshlrev_b32_e32 v32, 16, v63
	v_and_b32_e32 v33, 0xffff0000, v63
	v_fma_f32 v4, v4, v34, v32
	v_fma_f32 v5, v5, v35, v33
	s_waitcnt vmcnt(8)
	v_lshlrev_b32_e32 v28, 16, v64
	v_and_b32_e32 v29, 0xffff0000, v64
	v_mul_f32_e32 v30, 0x3fb8aa3b, v28
	v_mul_f32_e32 v31, 0x3fb8aa3b, v29
	v_exp_f32_e32 v30, v30
	v_exp_f32_e32 v31, v31
	v_add_f32_e32 v14, v14, v28
	v_add_f32_e32 v15, v15, v29
	v_lshlrev_b32_e32 v28, 16, v68
	v_and_b32_e32 v29, 0xffff0000, v68
	v_fma_f32 v6, v6, v30, v28
	v_fma_f32 v7, v7, v31, v29
	v_lshlrev_b32_e32 v32, 16, v65
	v_and_b32_e32 v33, 0xffff0000, v65
	v_mul_f32_e32 v34, 0x3fb8aa3b, v32
	v_mul_f32_e32 v35, 0x3fb8aa3b, v33
	v_exp_f32_e32 v34, v34
	v_exp_f32_e32 v35, v35
	v_add_f32_e32 v16, v16, v32
	v_add_f32_e32 v17, v17, v33
	v_lshlrev_b32_e32 v32, 16, v69
	v_and_b32_e32 v33, 0xffff0000, v69
	v_fma_f32 v8, v8, v34, v32
	v_fma_f32 v9, v9, v35, v33
	v_lshlrev_b32_e32 v28, 16, v66
	v_and_b32_e32 v29, 0xffff0000, v66
	v_mul_f32_e32 v30, 0x3fb8aa3b, v28
	v_mul_f32_e32 v31, 0x3fb8aa3b, v29
	v_exp_f32_e32 v30, v30
	v_exp_f32_e32 v31, v31
	v_add_f32_e32 v10, v10, v28
	v_add_f32_e32 v11, v11, v29
	v_lshlrev_b32_e32 v28, 16, v70
	v_and_b32_e32 v29, 0xffff0000, v70
	v_fma_f32 v2, v2, v30, v28
	v_fma_f32 v3, v3, v31, v29
	v_lshlrev_b32_e32 v32, 16, v67
	v_and_b32_e32 v33, 0xffff0000, v67
	v_mul_f32_e32 v34, 0x3fb8aa3b, v32
	v_mul_f32_e32 v35, 0x3fb8aa3b, v33
	v_exp_f32_e32 v34, v34
	v_exp_f32_e32 v35, v35
	v_add_f32_e32 v12, v12, v32
	v_add_f32_e32 v13, v13, v33
	v_lshlrev_b32_e32 v32, 16, v71
	v_and_b32_e32 v33, 0xffff0000, v71
	v_fma_f32 v4, v4, v34, v32
	v_fma_f32 v5, v5, v35, v33
	global_load_dwordx4 v[40:43], v[22:23], off
	global_load_dwordx4 v[44:47], v[20:21], off
	v_lshl_add_u64 v[22:23], v[22:23], 0, v[26:27]
	v_lshl_add_u64 v[20:21], v[20:21], 0, v[26:27]
	global_load_dwordx4 v[48:51], v[22:23], off
	global_load_dwordx4 v[52:55], v[20:21], off
	v_lshl_add_u64 v[22:23], v[22:23], 0, v[26:27]
	v_lshl_add_u64 v[20:21], v[20:21], 0, v[26:27]
	global_load_dwordx4 v[56:59], v[22:23], off
	global_load_dwordx4 v[60:63], v[20:21], off
	v_lshl_add_u64 v[22:23], v[22:23], 0, v[26:27]
	v_lshl_add_u64 v[20:21], v[20:21], 0, v[26:27]
	global_load_dwordx4 v[64:67], v[22:23], off
	global_load_dwordx4 v[68:71], v[20:21], off
	v_lshl_add_u64 v[22:23], v[22:23], 0, v[26:27]
	v_lshl_add_u64 v[20:21], v[20:21], 0, v[26:27]
	s_waitcnt vmcnt(14)
; DI void unpack8(const u32x4 v, float* f) { f[0] = bf_lo(v.x); f[1] = bf_hi(v.x); f[2] = bf_lo(v.y); f[3] = bf_hi(v.y); f[4] = bf_lo(v.z); f[5] = bf_hi(v.z); f[6] = bf_lo(v.w); f[7] = bf_hi(v.w); }
; DI void phase_scan1(const bf16_t* la, const bf16_t* bb, float* asum, float* hend) {
;     ...
;     for (int t = 0; t < 32; ++t) {
;       float l[8], bv[8]; unpack8(*(const u32x4*)(la + base + (size_t)t * DM), l); unpack8(*(const u32x4*)(bb + base + (size_t)t * DM), bv);
; #pragma unroll
;       for (int e = 0; e < 8; ++e) { h[e] = __expf(l[e]) * h[e] + bv[e]; as[e] += l[e]; }
	v_lshlrev_b32_e32 v28, 16, v72
	v_and_b32_e32 v29, 0xffff0000, v72
	v_mul_f32_e32 v30, 0x3fb8aa3b, v28
	v_mul_f32_e32 v31, 0x3fb8aa3b, v29
	v_exp_f32_e32 v30, v30
	v_exp_f32_e32 v31, v31
	v_add_f32_e32 v14, v14, v28
	v_add_f32_e32 v15, v15, v29
	v_lshlrev_b32_e32 v28, 16, v76
	v_and_b32_e32 v29, 0xffff0000, v76
	v_fma_f32 v6, v6, v30, v28
	v_fma_f32 v7, v7, v31, v29
	v_lshlrev_b32_e32 v32, 16, v73
	v_and_b32_e32 v33, 0xffff0000, v73
	v_mul_f32_e32 v34, 0x3fb8aa3b, v32
	v_mul_f32_e32 v35, 0x3fb8aa3b, v33
	v_exp_f32_e32 v34, v34
	v_exp_f32_e32 v35, v35
	v_add_f32_e32 v16, v16, v32
	v_add_f32_e32 v17, v17, v33
	v_lshlrev_b32_e32 v32, 16, v77
	v_and_b32_e32 v33, 0xffff0000, v77
	v_fma_f32 v8, v8, v34, v32
	v_fma_f32 v9, v9, v35, v33
	v_lshlrev_b32_e32 v28, 16, v74
	v_and_b32_e32 v29, 0xffff0000, v74
	v_mul_f32_e32 v30, 0x3fb8aa3b, v28
	v_mul_f32_e32 v31, 0x3fb8aa3b, v29
	v_exp_f32_e32 v30, v30
	v_exp_f32_e32 v31, v31
	v_add_f32_e32 v10, v10, v28
	v_add_f32_e32 v11, v11, v29
	v_lshlrev_b32_e32 v28, 16, v78
	v_and_b32_e32 v29, 0xffff0000, v78
	v_fma_f32 v2, v2, v30, v28
	v_fma_f32 v3, v3, v31, v29
	v_lshlrev_b32_e32 v32, 16, v75
	v_and_b32_e32 v33, 0xffff0000, v75
	v_mul_f32_e32 v34, 0x3fb8aa3b, v32
	v_mul_f32_e32 v35, 0x3fb8aa3b, v33
	v_exp_f32_e32 v34, v34
	v_exp_f32_e32 v35, v35
	v_add_f32_e32 v12, v12, v32
	v_add_f32_e32 v13, v13, v33
	v_lshlrev_b32_e32 v32, 16, v79
	v_and_b32_e32 v33, 0xffff0000, v79
	v_fma_f32 v4, v4, v34, v32
	v_fma_f32 v5, v5, v35, v33
	s_waitcnt vmcnt(12)
	v_lshlrev_b32_e32 v28, 16, v80
	v_and_b32_e32 v29, 0xffff0000, v80
	v_mul_f32_e32 v30, 0x3fb8aa3b, v28
	v_mul_f32_e32 v31, 0x3fb8aa3b, v29
	v_exp_f32_e32 v30, v30
	v_exp_f32_e32 v31, v31
	v_add_f32_e32 v14, v14, v28
	v_add_f32_e32 v15, v15, v29
	v_lshlrev_b32_e32 v28, 16, v84
	v_and_b32_e32 v29, 0xffff0000, v84
	v_fma_f32 v6, v6, v30, v28
	v_fma_f32 v7, v7, v31, v29
	v_lshlrev_b32_e32 v32, 16, v81
	v_and_b32_e32 v33, 0xffff0000, v81
	v_mul_f32_e32 v34, 0x3fb8aa3b, v32
	v_mul_f32_e32 v35, 0x3fb8aa3b, v33
	v_exp_f32_e32 v34, v34
	v_exp_f32_e32 v35, v35
	v_add_f32_e32 v16, v16, v32
	v_add_f32_e32 v17, v17, v33
	v_lshlrev_b32_e32 v32, 16, v85
	v_and_b32_e32 v33, 0xffff0000, v85
	v_fma_f32 v8, v8, v34, v32
	v_fma_f32 v9, v9, v35, v33
	v_lshlrev_b32_e32 v28, 16, v82
	v_and_b32_e32 v29, 0xffff0000, v82
	v_mul_f32_e32 v30, 0x3fb8aa3b, v28
	v_mul_f32_e32 v31, 0x3fb8aa3b, v29
	v_exp_f32_e32 v30, v30
	v_exp_f32_e32 v31, v31
	v_add_f32_e32 v10, v10, v28
	v_add_f32_e32 v11, v11, v29
	v_lshlrev_b32_e32 v28, 16, v86
	v_and_b32_e32 v29, 0xffff0000, v86
	v_fma_f32 v2, v2, v30, v28
	v_fma_f32 v3, v3, v31, v29
	v_lshlrev_b32_e32 v32, 16, v83
	v_and_b32_e32 v33, 0xffff0000, v83
	v_mul_f32_e32 v34, 0x3fb8aa3b, v32
	v_mul_f32_e32 v35, 0x3fb8aa3b, v33
	v_exp_f32_e32 v34, v34
	v_exp_f32_e32 v35, v35
	v_add_f32_e32 v12, v12, v32
	v_add_f32_e32 v13, v13, v33
	v_lshlrev_b32_e32 v32, 16, v87
	v_and_b32_e32 v33, 0xffff0000, v87
	v_fma_f32 v4, v4, v34, v32
	v_fma_f32 v5, v5, v35, v33
	s_waitcnt vmcnt(10)
	v_lshlrev_b32_e32 v28, 16, v88
	v_and_b32_e32 v29, 0xffff0000, v88
	v_mul_f32_e32 v30, 0x3fb8aa3b, v28
	v_mul_f32_e32 v31, 0x3fb8aa3b, v29
	v_exp_f32_e32 v30, v30
	v_exp_f32_e32 v31, v31
	v_add_f32_e32 v14, v14, v28
	v_add_f32_e32 v15, v15, v29
	v_lshlrev_b32_e32 v28, 16, v92
	v_and_b32_e32 v29, 0xffff0000, v92
	v_fma_f32 v6, v6, v30, v28
	v_fma_f32 v7, v7, v31, v29
	v_lshlrev_b32_e32 v32, 16, v89
	v_and_b32_e32 v33, 0xffff0000, v89
	v_mul_f32_e32 v34, 0x3fb8aa3b, v32
	v_mul_f32_e32 v35, 0x3fb8aa3b, v33
	v_exp_f32_e32 v34, v34
	v_exp_f32_e32 v35, v35
	v_add_f32_e32 v16, v16, v32
	v_add_f32_e32 v17, v17, v33
	v_lshlrev_b32_e32 v32, 16, v93
	v_and_b32_e32 v33, 0xffff0000, v93
	v_fma_f32 v8, v8, v34, v32
	v_fma_f32 v9, v9, v35, v33
	v_lshlrev_b32_e32 v28, 16, v90
	v_and_b32_e32 v29, 0xffff0000, v90
	v_mul_f32_e32 v30, 0x3fb8aa3b, v28
	v_mul_f32_e32 v31, 0x3fb8aa3b, v29
	v_exp_f32_e32 v30, v30
	v_exp_f32_e32 v31, v31
	v_add_f32_e32 v10, v10, v28
	v_add_f32_e32 v11, v11, v29
	v_lshlrev_b32_e32 v28, 16, v94
	v_and_b32_e32 v29, 0xffff0000, v94
	v_fma_f32 v2, v2, v30, v28
	v_fma_f32 v3, v3, v31, v29
	v_lshlrev_b32_e32 v32, 16, v91
	v_and_b32_e32 v33, 0xffff0000, v91
	v_mul_f32_e32 v34, 0x3fb8aa3b, v32
	v_mul_f32_e32 v35, 0x3fb8aa3b, v33
	v_exp_f32_e32 v34, v34
	v_exp_f32_e32 v35, v35
	v_add_f32_e32 v12, v12, v32
	v_add_f32_e32 v13, v13, v33
	v_lshlrev_b32_e32 v32, 16, v95
	v_and_b32_e32 v33, 0xffff0000, v95
	v_fma_f32 v4, v4, v34, v32
	v_fma_f32 v5, v5, v35, v33
	s_waitcnt vmcnt(8)
	v_lshlrev_b32_e32 v28, 16, v96
	v_and_b32_e32 v29, 0xffff0000, v96
	v_mul_f32_e32 v30, 0x3fb8aa3b, v28
	v_mul_f32_e32 v31, 0x3fb8aa3b, v29
	v_exp_f32_e32 v30, v30
	v_exp_f32_e32 v31, v31
	v_add_f32_e32 v14, v14, v28
	v_add_f32_e32 v15, v15, v29
	v_lshlrev_b32_e32 v28, 16, v100
	v_and_b32_e32 v29, 0xffff0000, v100
	v_fma_f32 v6, v6, v30, v28
	v_fma_f32 v7, v7, v31, v29
	v_lshlrev_b32_e32 v32, 16, v97
	v_and_b32_e32 v33, 0xffff0000, v97
	v_mul_f32_e32 v34, 0x3fb8aa3b, v32
	v_mul_f32_e32 v35, 0x3fb8aa3b, v33
	v_exp_f32_e32 v34, v34
	v_exp_f32_e32 v35, v35
	v_add_f32_e32 v16, v16, v32
	v_add_f32_e32 v17, v17, v33
	v_lshlrev_b32_e32 v32, 16, v101
	v_and_b32_e32 v33, 0xffff0000, v101
	v_fma_f32 v8, v8, v34, v32
	v_fma_f32 v9, v9, v35, v33
	v_lshlrev_b32_e32 v28, 16, v98
	v_and_b32_e32 v29, 0xffff0000, v98
	v_mul_f32_e32 v30, 0x3fb8aa3b, v28
	v_mul_f32_e32 v31, 0x3fb8aa3b, v29
	v_exp_f32_e32 v30, v30
	v_exp_f32_e32 v31, v31
	v_add_f32_e32 v10, v10, v28
	v_add_f32_e32 v11, v11, v29
	v_lshlrev_b32_e32 v28, 16, v102
	v_and_b32_e32 v29, 0xffff0000, v102
	v_fma_f32 v2, v2, v30, v28
	v_fma_f32 v3, v3, v31, v29
	v_lshlrev_b32_e32 v32, 16, v99
	v_and_b32_e32 v33, 0xffff0000, v99
	v_mul_f32_e32 v34, 0x3fb8aa3b, v32
	v_mul_f32_e32 v35, 0x3fb8aa3b, v33
	v_exp_f32_e32 v34, v34
	v_exp_f32_e32 v35, v35
	v_add_f32_e32 v12, v12, v32
	v_add_f32_e32 v13, v13, v33
	v_lshlrev_b32_e32 v32, 16, v103
	v_and_b32_e32 v33, 0xffff0000, v103
	v_fma_f32 v4, v4, v34, v32
	v_fma_f32 v5, v5, v35, v33
	global_load_dwordx4 v[72:75], v[22:23], off
	global_load_dwordx4 v[76:79], v[20:21], off
	v_lshl_add_u64 v[22:23], v[22:23], 0, v[26:27]
	v_lshl_add_u64 v[20:21], v[20:21], 0, v[26:27]
	global_load_dwordx4 v[80:83], v[22:23], off
	global_load_dwordx4 v[84:87], v[20:21], off
	v_lshl_add_u64 v[22:23], v[22:23], 0, v[26:27]
	v_lshl_add_u64 v[20:21], v[20:21], 0, v[26:27]
	global_load_dwordx4 v[88:91], v[22:23], off
	global_load_dwordx4 v[92:95], v[20:21], off
	v_lshl_add_u64 v[22:23], v[22:23], 0, v[26:27]
	v_lshl_add_u64 v[20:21], v[20:21], 0, v[26:27]
	global_load_dwordx4 v[96:99], v[22:23], off
	global_load_dwordx4 v[100:103], v[20:21], off
	v_lshl_add_u64 v[22:23], v[22:23], 0, v[26:27]
	v_lshl_add_u64 v[20:21], v[20:21], 0, v[26:27]
	s_waitcnt vmcnt(14)
; DI void unpack8(const u32x4 v, float* f) { f[0] = bf_lo(v.x); f[1] = bf_hi(v.x); f[2] = bf_lo(v.y); f[3] = bf_hi(v.y); f[4] = bf_lo(v.z); f[5] = bf_hi(v.z); f[6] = bf_lo(v.w); f[7] = bf_hi(v.w); }
; DI void phase_scan1(const bf16_t* la, const bf16_t* bb, float* asum, float* hend) {
;     ...
;     for (int t = 0; t < 32; ++t) {
;       float l[8], bv[8]; unpack8(*(const u32x4*)(la + base + (size_t)t * DM), l); unpack8(*(const u32x4*)(bb + base + (size_t)t * DM), bv);
; #pragma unroll
;       for (int e = 0; e < 8; ++e) { h[e] = __expf(l[e]) * h[e] + bv[e]; as[e] += l[e]; }
	v_lshlrev_b32_e32 v28, 16, v40
	v_and_b32_e32 v29, 0xffff0000, v40
	v_mul_f32_e32 v30, 0x3fb8aa3b, v28
	v_mul_f32_e32 v31, 0x3fb8aa3b, v29
	v_exp_f32_e32 v30, v30
	v_exp_f32_e32 v31, v31
	v_add_f32_e32 v14, v14, v28
	v_add_f32_e32 v15, v15, v29
	v_lshlrev_b32_e32 v28, 16, v44
	v_and_b32_e32 v29, 0xffff0000, v44
	v_fma_f32 v6, v6, v30, v28
	v_fma_f32 v7, v7, v31, v29
	v_lshlrev_b32_e32 v32, 16, v41
	v_and_b32_e32 v33, 0xffff0000, v41
	v_mul_f32_e32 v34, 0x3fb8aa3b, v32
	v_mul_f32_e32 v35, 0x3fb8aa3b, v33
	v_exp_f32_e32 v34, v34
	v_exp_f32_e32 v35, v35
	v_add_f32_e32 v16, v16, v32
	v_add_f32_e32 v17, v17, v33
	v_lshlrev_b32_e32 v32, 16, v45
	v_and_b32_e32 v33, 0xffff0000, v45
	v_fma_f32 v8, v8, v34, v32
	v_fma_f32 v9, v9, v35, v33
	v_lshlrev_b32_e32 v28, 16, v42
	v_and_b32_e32 v29, 0xffff0000, v42
	v_mul_f32_e32 v30, 0x3fb8aa3b, v28
	v_mul_f32_e32 v31, 0x3fb8aa3b, v29
	v_exp_f32_e32 v30, v30
	v_exp_f32_e32 v31, v31
	v_add_f32_e32 v10, v10, v28
	v_add_f32_e32 v11, v11, v29
	v_lshlrev_b32_e32 v28, 16, v46
	v_and_b32_e32 v29, 0xffff0000, v46
	v_fma_f32 v2, v2, v30, v28
	v_fma_f32 v3, v3, v31, v29
	v_lshlrev_b32_e32 v32, 16, v43
	v_and_b32_e32 v33, 0xffff0000, v43
	v_mul_f32_e32 v34, 0x3fb8aa3b, v32
	v_mul_f32_e32 v35, 0x3fb8aa3b, v33
	v_exp_f32_e32 v34, v34
	v_exp_f32_e32 v35, v35
	v_add_f32_e32 v12, v12, v32
	v_add_f32_e32 v13, v13, v33
	v_lshlrev_b32_e32 v32, 16, v47
	v_and_b32_e32 v33, 0xffff0000, v47
	v_fma_f32 v4, v4, v34, v32
	v_fma_f32 v5, v5, v35, v33
	s_waitcnt vmcnt(12)
	v_lshlrev_b32_e32 v28, 16, v48
	v_and_b32_e32 v29, 0xffff0000, v48
	v_mul_f32_e32 v30, 0x3fb8aa3b, v28
	v_mul_f32_e32 v31, 0x3fb8aa3b, v29
	v_exp_f32_e32 v30, v30
	v_exp_f32_e32 v31, v31
	v_add_f32_e32 v14, v14, v28
	v_add_f32_e32 v15, v15, v29
	v_lshlrev_b32_e32 v28, 16, v52
	v_and_b32_e32 v29, 0xffff0000, v52
	v_fma_f32 v6, v6, v30, v28
	v_fma_f32 v7, v7, v31, v29
	v_lshlrev_b32_e32 v32, 16, v49
	v_and_b32_e32 v33, 0xffff0000, v49
	v_mul_f32_e32 v34, 0x3fb8aa3b, v32
	v_mul_f32_e32 v35, 0x3fb8aa3b, v33
	v_exp_f32_e32 v34, v34
	v_exp_f32_e32 v35, v35
	v_add_f32_e32 v16, v16, v32
	v_add_f32_e32 v17, v17, v33
	v_lshlrev_b32_e32 v32, 16, v53
	v_and_b32_e32 v33, 0xffff0000, v53
	v_fma_f32 v8, v8, v34, v32
	v_fma_f32 v9, v9, v35, v33
	v_lshlrev_b32_e32 v28, 16, v50
	v_and_b32_e32 v29, 0xffff0000, v50
	v_mul_f32_e32 v30, 0x3fb8aa3b, v28
	v_mul_f32_e32 v31, 0x3fb8aa3b, v29
	v_exp_f32_e32 v30, v30
	v_exp_f32_e32 v31, v31
	v_add_f32_e32 v10, v10, v28
	v_add_f32_e32 v11, v11, v29
	v_lshlrev_b32_e32 v28, 16, v54
	v_and_b32_e32 v29, 0xffff0000, v54
	v_fma_f32 v2, v2, v30, v28
	v_fma_f32 v3, v3, v31, v29
	v_lshlrev_b32_e32 v32, 16, v51
	v_and_b32_e32 v33, 0xffff0000, v51
	v_mul_f32_e32 v34, 0x3fb8aa3b, v32
	v_mul_f32_e32 v35, 0x3fb8aa3b, v33
	v_exp_f32_e32 v34, v34
	v_exp_f32_e32 v35, v35
	v_add_f32_e32 v12, v12, v32
	v_add_f32_e32 v13, v13, v33
	v_lshlrev_b32_e32 v32, 16, v55
	v_and_b32_e32 v33, 0xffff0000, v55
	v_fma_f32 v4, v4, v34, v32
	v_fma_f32 v5, v5, v35, v33
	s_waitcnt vmcnt(10)
	v_lshlrev_b32_e32 v28, 16, v56
	v_and_b32_e32 v29, 0xffff0000, v56
	v_mul_f32_e32 v30, 0x3fb8aa3b, v28
	v_mul_f32_e32 v31, 0x3fb8aa3b, v29
	v_exp_f32_e32 v30, v30
	v_exp_f32_e32 v31, v31
	v_add_f32_e32 v14, v14, v28
	v_add_f32_e32 v15, v15, v29
	v_lshlrev_b32_e32 v28, 16, v60
	v_and_b32_e32 v29, 0xffff0000, v60
	v_fma_f32 v6, v6, v30, v28
	v_fma_f32 v7, v7, v31, v29
	v_lshlrev_b32_e32 v32, 16, v57
	v_and_b32_e32 v33, 0xffff0000, v57
	v_mul_f32_e32 v34, 0x3fb8aa3b, v32
	v_mul_f32_e32 v35, 0x3fb8aa3b, v33
	v_exp_f32_e32 v34, v34
	v_exp_f32_e32 v35, v35
	v_add_f32_e32 v16, v16, v32
	v_add_f32_e32 v17, v17, v33
	v_lshlrev_b32_e32 v32, 16, v61
	v_and_b32_e32 v33, 0xffff0000, v61
	v_fma_f32 v8, v8, v34, v32
	v_fma_f32 v9, v9, v35, v33
	v_lshlrev_b32_e32 v28, 16, v58
	v_and_b32_e32 v29, 0xffff0000, v58
	v_mul_f32_e32 v30, 0x3fb8aa3b, v28
	v_mul_f32_e32 v31, 0x3fb8aa3b, v29
	v_exp_f32_e32 v30, v30
	v_exp_f32_e32 v31, v31
	v_add_f32_e32 v10, v10, v28
	v_add_f32_e32 v11, v11, v29
	v_lshlrev_b32_e32 v28, 16, v62
	v_and_b32_e32 v29, 0xffff0000, v62
	v_fma_f32 v2, v2, v30, v28
	v_fma_f32 v3, v3, v31, v29
	v_lshlrev_b32_e32 v32, 16, v59
	v_and_b32_e32 v33, 0xffff0000, v59
	v_mul_f32_e32 v34, 0x3fb8aa3b, v32
	v_mul_f32_e32 v35, 0x3fb8aa3b, v33
	v_exp_f32_e32 v34, v34
	v_exp_f32_e32 v35, v35
	v_add_f32_e32 v12, v12, v32
	v_add_f32_e32 v13, v13, v33
	v_lshlrev_b32_e32 v32, 16, v63
	v_and_b32_e32 v33, 0xffff0000, v63
	v_fma_f32 v4, v4, v34, v32
	v_fma_f32 v5, v5, v35, v33
	s_waitcnt vmcnt(8)
	v_lshlrev_b32_e32 v28, 16, v64
	v_and_b32_e32 v29, 0xffff0000, v64
	v_mul_f32_e32 v30, 0x3fb8aa3b, v28
	v_mul_f32_e32 v31, 0x3fb8aa3b, v29
	v_exp_f32_e32 v30, v30
	v_exp_f32_e32 v31, v31
	v_add_f32_e32 v14, v14, v28
	v_add_f32_e32 v15, v15, v29
	v_lshlrev_b32_e32 v28, 16, v68
	v_and_b32_e32 v29, 0xffff0000, v68
	v_fma_f32 v6, v6, v30, v28
	v_fma_f32 v7, v7, v31, v29
	v_lshlrev_b32_e32 v32, 16, v65
	v_and_b32_e32 v33, 0xffff0000, v65
	v_mul_f32_e32 v34, 0x3fb8aa3b, v32
	v_mul_f32_e32 v35, 0x3fb8aa3b, v33
	v_exp_f32_e32 v34, v34
	v_exp_f32_e32 v35, v35
	v_add_f32_e32 v16, v16, v32
	v_add_f32_e32 v17, v17, v33
	v_lshlrev_b32_e32 v32, 16, v69
	v_and_b32_e32 v33, 0xffff0000, v69
	v_fma_f32 v8, v8, v34, v32
	v_fma_f32 v9, v9, v35, v33
	v_lshlrev_b32_e32 v28, 16, v66
	v_and_b32_e32 v29, 0xffff0000, v66
	v_mul_f32_e32 v30, 0x3fb8aa3b, v28
	v_mul_f32_e32 v31, 0x3fb8aa3b, v29
	v_exp_f32_e32 v30, v30
	v_exp_f32_e32 v31, v31
	v_add_f32_e32 v10, v10, v28
	v_add_f32_e32 v11, v11, v29
	v_lshlrev_b32_e32 v28, 16, v70
	v_and_b32_e32 v29, 0xffff0000, v70
	v_fma_f32 v2, v2, v30, v28
	v_fma_f32 v3, v3, v31, v29
	v_lshlrev_b32_e32 v32, 16, v67
	v_and_b32_e32 v33, 0xffff0000, v67
	v_mul_f32_e32 v34, 0x3fb8aa3b, v32
	v_mul_f32_e32 v35, 0x3fb8aa3b, v33
	v_exp_f32_e32 v34, v34
	v_exp_f32_e32 v35, v35
	v_add_f32_e32 v12, v12, v32
	v_add_f32_e32 v13, v13, v33
	v_lshlrev_b32_e32 v32, 16, v71
	v_and_b32_e32 v33, 0xffff0000, v71
	v_fma_f32 v4, v4, v34, v32
	v_fma_f32 v5, v5, v35, v33
	s_waitcnt vmcnt(6)
; DI void unpack8(const u32x4 v, float* f) { f[0] = bf_lo(v.x); f[1] = bf_hi(v.x); f[2] = bf_lo(v.y); f[3] = bf_hi(v.y); f[4] = bf_lo(v.z); f[5] = bf_hi(v.z); f[6] = bf_lo(v.w); f[7] = bf_hi(v.w); }
; DI void phase_scan1(const bf16_t* la, const bf16_t* bb, float* asum, float* hend) {
;     ...
;     for (int t = 0; t < 32; ++t) {
;       float l[8], bv[8]; unpack8(*(const u32x4*)(la + base + (size_t)t * DM), l); unpack8(*(const u32x4*)(bb + base + (size_t)t * DM), bv);
; #pragma unroll
;       for (int e = 0; e < 8; ++e) { h[e] = __expf(l[e]) * h[e] + bv[e]; as[e] += l[e]; }
;     }
;     const size_t so = ((size_t)b * 128 + c) * DM + chg * 8;
;     *(f32x4*)(asum + so) = (f32x4){as[0], as[1], as[2], as[3]}; *(f32x4*)(asum + so + 4) = (f32x4){as[4], as[5], as[6], as[7]};
;     *(f32x4*)(hend + so) = (f32x4){h[0], h[1], h[2], h[3]}; *(f32x4*)(hend + so + 4) = (f32x4){h[4], h[5], h[6], h[7]};
	v_lshlrev_b32_e32 v28, 16, v72
	v_and_b32_e32 v29, 0xffff0000, v72
	v_mul_f32_e32 v30, 0x3fb8aa3b, v28
	v_mul_f32_e32 v31, 0x3fb8aa3b, v29
	v_exp_f32_e32 v30, v30
	v_exp_f32_e32 v31, v31
	v_add_f32_e32 v14, v14, v28
	v_add_f32_e32 v15, v15, v29
	v_lshlrev_b32_e32 v28, 16, v76
	v_and_b32_e32 v29, 0xffff0000, v76
	v_fma_f32 v6, v6, v30, v28
	v_fma_f32 v7, v7, v31, v29
	v_lshlrev_b32_e32 v32, 16, v73
	v_and_b32_e32 v33, 0xffff0000, v73
	v_mul_f32_e32 v34, 0x3fb8aa3b, v32
	v_mul_f32_e32 v35, 0x3fb8aa3b, v33
	v_exp_f32_e32 v34, v34
	v_exp_f32_e32 v35, v35
	v_add_f32_e32 v16, v16, v32
	v_add_f32_e32 v17, v17, v33
	v_lshlrev_b32_e32 v32, 16, v77
	v_and_b32_e32 v33, 0xffff0000, v77
	v_fma_f32 v8, v8, v34, v32
	v_fma_f32 v9, v9, v35, v33
	v_lshlrev_b32_e32 v28, 16, v74
	v_and_b32_e32 v29, 0xffff0000, v74
	v_mul_f32_e32 v30, 0x3fb8aa3b, v28
	v_mul_f32_e32 v31, 0x3fb8aa3b, v29
	v_exp_f32_e32 v30, v30
	v_exp_f32_e32 v31, v31
	v_add_f32_e32 v10, v10, v28
	v_add_f32_e32 v11, v11, v29
	v_lshlrev_b32_e32 v28, 16, v78
	v_and_b32_e32 v29, 0xffff0000, v78
	v_fma_f32 v2, v2, v30, v28
	v_fma_f32 v3, v3, v31, v29
	v_lshlrev_b32_e32 v32, 16, v75
	v_and_b32_e32 v33, 0xffff0000, v75
	v_mul_f32_e32 v34, 0x3fb8aa3b, v32
	v_mul_f32_e32 v35, 0x3fb8aa3b, v33
	v_exp_f32_e32 v34, v34
	v_exp_f32_e32 v35, v35
	v_add_f32_e32 v12, v12, v32
	v_add_f32_e32 v13, v13, v33
	v_lshlrev_b32_e32 v32, 16, v79
	v_and_b32_e32 v33, 0xffff0000, v79
	v_fma_f32 v4, v4, v34, v32
	v_fma_f32 v5, v5, v35, v33
	s_waitcnt vmcnt(4)
	v_lshlrev_b32_e32 v28, 16, v80
	v_and_b32_e32 v29, 0xffff0000, v80
	v_mul_f32_e32 v30, 0x3fb8aa3b, v28
	v_mul_f32_e32 v31, 0x3fb8aa3b, v29
	v_exp_f32_e32 v30, v30
	v_exp_f32_e32 v31, v31
	v_add_f32_e32 v14, v14, v28
	v_add_f32_e32 v15, v15, v29
	v_lshlrev_b32_e32 v28, 16, v84
	v_and_b32_e32 v29, 0xffff0000, v84
	v_fma_f32 v6, v6, v30, v28
	v_fma_f32 v7, v7, v31, v29
	v_lshlrev_b32_e32 v32, 16, v81
	v_and_b32_e32 v33, 0xffff0000, v81
	v_mul_f32_e32 v34, 0x3fb8aa3b, v32
	v_mul_f32_e32 v35, 0x3fb8aa3b, v33
	v_exp_f32_e32 v34, v34
	v_exp_f32_e32 v35, v35
	v_add_f32_e32 v16, v16, v32
	v_add_f32_e32 v17, v17, v33
	v_lshlrev_b32_e32 v32, 16, v85
	v_and_b32_e32 v33, 0xffff0000, v85
	v_fma_f32 v8, v8, v34, v32
	v_fma_f32 v9, v9, v35, v33
	v_lshlrev_b32_e32 v28, 16, v82
	v_and_b32_e32 v29, 0xffff0000, v82
	v_mul_f32_e32 v30, 0x3fb8aa3b, v28
	v_mul_f32_e32 v31, 0x3fb8aa3b, v29
	v_exp_f32_e32 v30, v30
	v_exp_f32_e32 v31, v31
	v_add_f32_e32 v10, v10, v28
	v_add_f32_e32 v11, v11, v29
	v_lshlrev_b32_e32 v28, 16, v86
	v_and_b32_e32 v29, 0xffff0000, v86
	v_fma_f32 v2, v2, v30, v28
	v_fma_f32 v3, v3, v31, v29
	v_lshlrev_b32_e32 v32, 16, v83
	v_and_b32_e32 v33, 0xffff0000, v83
	v_mul_f32_e32 v34, 0x3fb8aa3b, v32
	v_mul_f32_e32 v35, 0x3fb8aa3b, v33
	v_exp_f32_e32 v34, v34
	v_exp_f32_e32 v35, v35
	v_add_f32_e32 v12, v12, v32
	v_add_f32_e32 v13, v13, v33
	v_lshlrev_b32_e32 v32, 16, v87
	v_and_b32_e32 v33, 0xffff0000, v87
	v_fma_f32 v4, v4, v34, v32
	v_fma_f32 v5, v5, v35, v33
	s_waitcnt vmcnt(2)
	v_lshlrev_b32_e32 v28, 16, v88
	v_and_b32_e32 v29, 0xffff0000, v88
	v_mul_f32_e32 v30, 0x3fb8aa3b, v28
	v_mul_f32_e32 v31, 0x3fb8aa3b, v29
	v_exp_f32_e32 v30, v30
	v_exp_f32_e32 v31, v31
	v_add_f32_e32 v14, v14, v28
	v_add_f32_e32 v15, v15, v29
	v_lshlrev_b32_e32 v28, 16, v92
	v_and_b32_e32 v29, 0xffff0000, v92
	v_fma_f32 v6, v6, v30, v28
	v_fma_f32 v7, v7, v31, v29
	v_lshlrev_b32_e32 v32, 16, v89
	v_and_b32_e32 v33, 0xffff0000, v89
	v_mul_f32_e32 v34, 0x3fb8aa3b, v32
	v_mul_f32_e32 v35, 0x3fb8aa3b, v33
	v_exp_f32_e32 v34, v34
	v_exp_f32_e32 v35, v35
	v_add_f32_e32 v16, v16, v32
	v_add_f32_e32 v17, v17, v33
	v_lshlrev_b32_e32 v32, 16, v93
	v_and_b32_e32 v33, 0xffff0000, v93
	v_fma_f32 v8, v8, v34, v32
	v_fma_f32 v9, v9, v35, v33
	v_lshlrev_b32_e32 v28, 16, v90
	v_and_b32_e32 v29, 0xffff0000, v90
	v_mul_f32_e32 v30, 0x3fb8aa3b, v28
	v_mul_f32_e32 v31, 0x3fb8aa3b, v29
	v_exp_f32_e32 v30, v30
	v_exp_f32_e32 v31, v31
	v_add_f32_e32 v10, v10, v28
	v_add_f32_e32 v11, v11, v29
	v_lshlrev_b32_e32 v28, 16, v94
	v_and_b32_e32 v29, 0xffff0000, v94
	v_fma_f32 v2, v2, v30, v28
	v_fma_f32 v3, v3, v31, v29
	v_lshlrev_b32_e32 v32, 16, v91
	v_and_b32_e32 v33, 0xffff0000, v91
	v_mul_f32_e32 v34, 0x3fb8aa3b, v32
	v_mul_f32_e32 v35, 0x3fb8aa3b, v33
	v_exp_f32_e32 v34, v34
	v_exp_f32_e32 v35, v35
	v_add_f32_e32 v12, v12, v32
	v_add_f32_e32 v13, v13, v33
	v_lshlrev_b32_e32 v32, 16, v95
	v_and_b32_e32 v33, 0xffff0000, v95
	v_fma_f32 v4, v4, v34, v32
	v_fma_f32 v5, v5, v35, v33
	s_waitcnt vmcnt(0)
	v_lshlrev_b32_e32 v28, 16, v96
	v_and_b32_e32 v29, 0xffff0000, v96
	v_mul_f32_e32 v30, 0x3fb8aa3b, v28
	v_mul_f32_e32 v31, 0x3fb8aa3b, v29
	v_exp_f32_e32 v30, v30
	v_exp_f32_e32 v31, v31
	v_add_f32_e32 v14, v14, v28
	v_add_f32_e32 v15, v15, v29
	v_lshlrev_b32_e32 v28, 16, v100
	v_and_b32_e32 v29, 0xffff0000, v100
	v_fma_f32 v6, v6, v30, v28
	v_fma_f32 v7, v7, v31, v29
	v_lshlrev_b32_e32 v32, 16, v97
	v_and_b32_e32 v33, 0xffff0000, v97
	v_mul_f32_e32 v34, 0x3fb8aa3b, v32
	v_mul_f32_e32 v35, 0x3fb8aa3b, v33
	v_exp_f32_e32 v34, v34
	v_exp_f32_e32 v35, v35
	v_add_f32_e32 v16, v16, v32
	v_add_f32_e32 v17, v17, v33
	v_lshlrev_b32_e32 v32, 16, v101
	v_and_b32_e32 v33, 0xffff0000, v101
	v_fma_f32 v8, v8, v34, v32
	v_fma_f32 v9, v9, v35, v33
	v_lshlrev_b32_e32 v28, 16, v98
	v_and_b32_e32 v29, 0xffff0000, v98
	v_mul_f32_e32 v30, 0x3fb8aa3b, v28
	v_mul_f32_e32 v31, 0x3fb8aa3b, v29
	v_exp_f32_e32 v30, v30
	v_exp_f32_e32 v31, v31
	v_add_f32_e32 v10, v10, v28
	v_add_f32_e32 v11, v11, v29
	v_lshlrev_b32_e32 v28, 16, v102
	v_and_b32_e32 v29, 0xffff0000, v102
	v_fma_f32 v2, v2, v30, v28
	v_fma_f32 v3, v3, v31, v29
	v_lshlrev_b32_e32 v32, 16, v99
	v_and_b32_e32 v33, 0xffff0000, v99
	v_mul_f32_e32 v34, 0x3fb8aa3b, v32
	v_mul_f32_e32 v35, 0x3fb8aa3b, v33
	v_exp_f32_e32 v34, v34
	v_exp_f32_e32 v35, v35
	v_add_f32_e32 v12, v12, v32
	v_add_f32_e32 v13, v13, v33
	v_lshlrev_b32_e32 v32, 16, v103
	v_and_b32_e32 v33, 0xffff0000, v103
	v_fma_f32 v4, v4, v34, v32
	v_fma_f32 v5, v5, v35, v33
	v_and_b32_e32 v20, 0x7f, v39
	v_lshlrev_b32_e32 v21, 3, v0
	v_and_b32_e32 v21, 0x7f8, v21
	v_lshlrev_b64 v[18:19], 18, v[18:19]
	v_lshlrev_b32_e32 v20, 11, v20
	v_or3_b32 v18, v18, v20, v21
	v_lshlrev_b64 v[18:19], 2, v[18:19]
	v_add_u32_e32 v0, s3, v0
	s_mov_b32 s12, 0x1ffff
	v_lshl_add_u64 v[20:21], s[6:7], 0, v[18:19]
	v_cmp_lt_i32_e32 vcc, s12, v0
	global_store_dwordx4 v[20:21], v[14:17], off
	global_store_dwordx4 v[20:21], v[10:13], off offset:16
	s_or_b64 s[10:11], vcc, s[10:11]
	v_add_u32_e32 v38, s14, v38
	v_lshl_add_u64 v[10:11], s[4:5], 0, v[18:19]
	global_store_dwordx4 v[10:11], v[6:9], off
	global_store_dwordx4 v[10:11], v[2:5], off offset:16
	s_andn2_b64 exec, exec, s[10:11]
	s_cbranch_execnz .LBB0_51
